# early s_barrier before last 3 MFMAs of each MFMA segment
# baseline (speedup 1.0000x reference)
; #define PG8_STAGE(bufoff, gbase, voff) do { _Pragma("unroll") for (int _i = 0; _i < 2; ++_i) \
;         __builtin_amdgcn_global_load_lds((const unsigned*)((const char*)(gbase) + (voff)[_i]), (LAS unsigned*)(lds + (bufoff) + ldsw + _i * 8192), 16, 0, 0); } while (0)
; #define PG8_LDA(dst, b, h) do { _Pragma("unroll") for (int m = 0; m < 4; ++m) _Pragma("unroll") for (int k = 0; k < 2; ++k) dst[m][k] = *(const LAS bf16x8*)(lds + PG8_SA(b, h) + aoff + m * 2048 + k * 1024); } while (0)
; #define PG8_LDB(dst, b, h) do { _Pragma("unroll") for (int n = 0; n < 2; ++n) _Pragma("unroll") for (int k = 0; k < 2; ++k) dst[n][k] = *(const LAS bf16x8*)(lds + PG8_SB(b, h) + boff + n * 2048 + k * 1024); } while (0)
; #define PG8_MMA(ai, bj, At, Bt) do { __builtin_amdgcn_s_setprio(1); _Pragma("unroll") for (int m = 0; m < 4; ++m) _Pragma("unroll") for (int n = 0; n < 2; ++n) _Pragma("unroll") for (int k = 0; k < 2; ++k) \
;         acc[ai][bj][m][n] = __builtin_amdgcn_mfma_f32_16x16x32_bf16(Bt[n][k], At[m][k], acc[ai][bj][m][n], 0, 0, 0); __builtin_amdgcn_s_setprio(0); } while (0)
; #define PG8_WAIT_V(n) asm volatile("s_waitcnt vmcnt(" #n ")" ::: "memory")
; #define PG8_WAIT_L(n) asm volatile("s_waitcnt lgkmcnt(" #n ")" ::: "memory")
; #define PG8_BAR __builtin_amdgcn_s_barrier()
; #define PG8_SCHED __builtin_amdgcn_sched_barrier(0)
; template <class Epi>
; __device__ __forceinline__ void gemm_phase(LAS unsigned char* lds, const Gemm g, const TileOrder& S, const Epi& E) {
;     ...
;             const bool last = (t == nt - 2);
;             const char* a1 = cA + (size_t)(t + 1) * kstepA;
;             const char* a2 = last ? nA : cA + (size_t)(t + 2) * kstepA; const char* b2 = last ? nB : cB + (size_t)(t + 2) * kstep;
;             const char* a3 = a2 + kstepA; const char* b3 = b2 + kstep;
;             PG8_LDB(B0, 0, 0); PG8_LDB(B1, 0, 1); PG8_SCHED; PG8_LDA(At, 0, 0); PG8_STAGE(PG8_SA(1, 1), a1 + hstepA, voffA);
;             PG8_WAIT_V(8); PG8_WAIT_L(0); PG8_BAR; PG8_MMA(0, 0, At, B0); PG8_MMA(0, 1, At, B1); PG8_BAR; PG8_SCHED;
;             PG8_LDA(At, 0, 1); PG8_STAGE(PG8_SB(0, 0), b2, voffB); PG8_STAGE(PG8_SB(0, 1), b2 + hstepB, voffB); PG8_STAGE(PG8_SA(0, 0), a2, voffA);
;             PG8_WAIT_V(8); PG8_WAIT_L(0); PG8_BAR; PG8_MMA(1, 0, At, B0); PG8_MMA(1, 1, At, B1); PG8_BAR; PG8_SCHED;
.LBB0_51:
	s_add_u32 s2, s28, 0xfff80080
	s_addc_u32 s3, s29, -1
	s_add_i32 s6, 0, 0x10000
	s_cmp_eq_u32 s72, 28
	s_cselect_b32 s31, s49, s3
	s_cselect_b32 s30, s68, s2
	v_add_u32_e32 v0, s6, v186
	s_cselect_b32 s3, s47, s71
	s_cselect_b32 s2, s69, s70
	s_add_i32 s12, 0, 0x14000
	s_waitcnt lgkmcnt(0)
	ds_read_b128 v[130:133], v0
	ds_read_b128 v[134:137], v0 offset:1024
	ds_read_b128 v[138:141], v0 offset:2048
	ds_read_b128 v[142:145], v0 offset:3072
	v_add_u32_e32 v0, s12, v186
	ds_read_b128 v[154:157], v0
	ds_read_b128 v[158:161], v0 offset:1024
	ds_read_b128 v[162:165], v0 offset:2048
	ds_read_b128 v[166:169], v0 offset:3072
	v_lshl_add_u64 v[182:183], s[28:29], 0, v[150:151]
	s_add_i32 m0, s56, 0xc000
	ds_read_b128 v[170:173], v187
	ds_read_b128 v[174:177], v187 offset:1024
	ds_read_b128 v[178:181], v187 offset:2048
	ds_read_b128 v[188:191], v187 offset:3072
	ds_read_b128 v[192:195], v187 offset:4096
	ds_read_b128 v[196:199], v187 offset:5120
	ds_read_b128 v[200:203], v187 offset:6144
	ds_read_b128 v[204:207], v187 offset:7168
	global_load_lds_dwordx4 v[182:183], off
	v_lshl_add_u64 v[182:183], s[28:29], 0, v[152:153]
	s_add_i32 m0, s56, 0xe000
	s_nop 0
	global_load_lds_dwordx4 v[182:183], off
	s_waitcnt vmcnt(8)
	s_waitcnt lgkmcnt(0)
	s_barrier
	s_setprio 1
	s_waitcnt lgkmcnt(0)
	v_mfma_f32_16x16x32_bf16 v[126:129], v[130:133], v[170:173], v[126:129]
	v_mfma_f32_16x16x32_bf16 v[118:121], v[138:141], v[170:173], v[118:121]
	v_mfma_f32_16x16x32_bf16 v[110:113], v[130:133], v[178:181], v[110:113]
	v_mfma_f32_16x16x32_bf16 v[102:105], v[138:141], v[178:181], v[102:105]
	v_mfma_f32_16x16x32_bf16 v[94:97], v[130:133], v[192:195], v[94:97]
	v_mfma_f32_16x16x32_bf16 v[86:89], v[138:141], v[192:195], v[86:89]
	v_mfma_f32_16x16x32_bf16 v[78:81], v[130:133], v[200:203], v[78:81]
	v_mfma_f32_16x16x32_bf16 v[70:73], v[138:141], v[200:203], v[70:73]
	v_mfma_f32_16x16x32_bf16 v[126:129], v[134:137], v[174:177], v[126:129]
	v_mfma_f32_16x16x32_bf16 v[118:121], v[142:145], v[174:177], v[118:121]
	v_mfma_f32_16x16x32_bf16 v[110:113], v[134:137], v[188:191], v[110:113]
	v_mfma_f32_16x16x32_bf16 v[102:105], v[142:145], v[188:191], v[102:105]
	v_mfma_f32_16x16x32_bf16 v[94:97], v[134:137], v[196:199], v[94:97]
	v_mfma_f32_16x16x32_bf16 v[86:89], v[142:145], v[196:199], v[86:89]
	v_mfma_f32_16x16x32_bf16 v[78:81], v[134:137], v[204:207], v[78:81]
	v_mfma_f32_16x16x32_bf16 v[70:73], v[142:145], v[204:207], v[70:73]
	s_setprio 0
	s_setprio 1
	v_mfma_f32_16x16x32_bf16 v[122:125], v[154:157], v[170:173], v[122:125]
	v_mfma_f32_16x16x32_bf16 v[114:117], v[162:165], v[170:173], v[114:117]
	v_mfma_f32_16x16x32_bf16 v[106:109], v[154:157], v[178:181], v[106:109]
	v_mfma_f32_16x16x32_bf16 v[98:101], v[162:165], v[178:181], v[98:101]
	v_mfma_f32_16x16x32_bf16 v[90:93], v[154:157], v[192:195], v[90:93]
	v_mfma_f32_16x16x32_bf16 v[82:85], v[162:165], v[192:195], v[82:85]
	v_mfma_f32_16x16x32_bf16 v[74:77], v[154:157], v[200:203], v[74:77]
	v_mfma_f32_16x16x32_bf16 v[66:69], v[162:165], v[200:203], v[66:69]
	v_mfma_f32_16x16x32_bf16 v[122:125], v[158:161], v[174:177], v[122:125]
	v_mfma_f32_16x16x32_bf16 v[114:117], v[166:169], v[174:177], v[114:117]
	v_mfma_f32_16x16x32_bf16 v[106:109], v[158:161], v[188:191], v[106:109]
	v_mfma_f32_16x16x32_bf16 v[98:101], v[166:169], v[188:191], v[98:101]
	v_mfma_f32_16x16x32_bf16 v[90:93], v[158:161], v[196:199], v[90:93]
	s_setprio 2
	s_barrier
	v_mfma_f32_16x16x32_bf16 v[82:85], v[166:169], v[196:199], v[82:85]
	v_mfma_f32_16x16x32_bf16 v[74:77], v[158:161], v[204:207], v[74:77]
	v_mfma_f32_16x16x32_bf16 v[66:69], v[166:169], v[204:207], v[66:69]
	s_setprio 0
	s_add_i32 s6, s6, s55
	v_lshl_add_u64 v[182:183], s[2:3], 0, v[148:149]
	s_mov_b32 m0, s6
	ds_read_b128 v[170:173], v187 offset:16384
	ds_read_b128 v[174:177], v187 offset:17408
	ds_read_b128 v[178:181], v187 offset:18432
	ds_read_b128 v[188:191], v187 offset:19456
	ds_read_b128 v[192:195], v187 offset:20480
	ds_read_b128 v[196:199], v187 offset:21504
	ds_read_b128 v[200:203], v187 offset:22528
	ds_read_b128 v[204:207], v187 offset:23552
	global_load_lds_dwordx4 v[182:183], off
	s_add_i32 m0, s6, 0x2000
	s_add_u32 s14, s2, 0x80000
	v_lshl_add_u64 v[208:209], s[2:3], 0, v[146:147]
	s_addc_u32 s15, s3, 0
	s_add_i32 s6, s12, s55
	global_load_lds_dwordx4 v[208:209], off
	v_lshl_add_u64 v[210:211], s[14:15], 0, v[148:149]
	s_mov_b32 m0, s6
	v_lshl_add_u64 v[212:213], s[30:31], 0, v[146:147]
	global_load_lds_dwordx4 v[210:211], off
	v_lshl_add_u64 v[210:211], s[14:15], 0, v[146:147]
	s_add_i32 m0, s6, 0x2000
	s_nop 0
	global_load_lds_dwordx4 v[210:211], off
	v_lshl_add_u64 v[210:211], s[30:31], 0, v[148:149]
	s_mov_b32 m0, s56
	s_nop 0
	global_load_lds_dwordx4 v[210:211], off
	s_mov_b32 m0, s57
	s_nop 0
	global_load_lds_dwordx4 v[212:213], off
	s_waitcnt vmcnt(8)
	s_waitcnt lgkmcnt(0)
	s_barrier
; #define PG8_STAGE(bufoff, gbase, voff) do { _Pragma("unroll") for (int _i = 0; _i < 2; ++_i) \
;         __builtin_amdgcn_global_load_lds((const unsigned*)((const char*)(gbase) + (voff)[_i]), (LAS unsigned*)(lds + (bufoff) + ldsw + _i * 8192), 16, 0, 0); } while (0)
; #define PG8_LDA(dst, b, h) do { _Pragma("unroll") for (int m = 0; m < 4; ++m) _Pragma("unroll") for (int k = 0; k < 2; ++k) dst[m][k] = *(const LAS bf16x8*)(lds + PG8_SA(b, h) + aoff + m * 2048 + k * 1024); } while (0)
; #define PG8_LDB(dst, b, h) do { _Pragma("unroll") for (int n = 0; n < 2; ++n) _Pragma("unroll") for (int k = 0; k < 2; ++k) dst[n][k] = *(const LAS bf16x8*)(lds + PG8_SB(b, h) + boff + n * 2048 + k * 1024); } while (0)
; #define PG8_MMA(ai, bj, At, Bt) do { __builtin_amdgcn_s_setprio(1); _Pragma("unroll") for (int m = 0; m < 4; ++m) _Pragma("unroll") for (int n = 0; n < 2; ++n) _Pragma("unroll") for (int k = 0; k < 2; ++k) \
;         acc[ai][bj][m][n] = __builtin_amdgcn_mfma_f32_16x16x32_bf16(Bt[n][k], At[m][k], acc[ai][bj][m][n], 0, 0, 0); __builtin_amdgcn_s_setprio(0); } while (0)
; #define PG8_WAIT_V(n) asm volatile("s_waitcnt vmcnt(" #n ")" ::: "memory")
; #define PG8_WAIT_L(n) asm volatile("s_waitcnt lgkmcnt(" #n ")" ::: "memory")
; #define PG8_BAR __builtin_amdgcn_s_barrier()
; #define PG8_SCHED __builtin_amdgcn_sched_barrier(0)
; template <class Epi>
; __device__ __forceinline__ void gemm_phase(LAS unsigned char* lds, const Gemm g, const TileOrder& S, const Epi& E) {
;     ...
;             PG8_WAIT_V(8); PG8_WAIT_L(0); PG8_BAR; PG8_MMA(1, 0, At, B0); PG8_MMA(1, 1, At, B1); PG8_BAR; PG8_SCHED;
;             PG8_LDB(B0, 1, 0); PG8_LDB(B1, 1, 1); PG8_SCHED; PG8_LDA(At, 1, 0); PG8_STAGE(PG8_SA(0, 1), a2 + hstepA, voffA);
;             PG8_WAIT_V(8); PG8_WAIT_L(0); PG8_BAR; PG8_MMA(0, 0, At, B0); PG8_MMA(0, 1, At, B1); PG8_BAR; PG8_SCHED;
	s_setprio 1
	s_waitcnt lgkmcnt(0)
	v_mfma_f32_16x16x32_bf16 v[62:65], v[130:133], v[170:173], v[62:65]
	v_mfma_f32_16x16x32_bf16 v[54:57], v[138:141], v[170:173], v[54:57]
	v_mfma_f32_16x16x32_bf16 v[46:49], v[130:133], v[178:181], v[46:49]
	v_mfma_f32_16x16x32_bf16 v[38:41], v[138:141], v[178:181], v[38:41]
	v_mfma_f32_16x16x32_bf16 v[30:33], v[130:133], v[192:195], v[30:33]
	v_mfma_f32_16x16x32_bf16 v[22:25], v[138:141], v[192:195], v[22:25]
	v_mfma_f32_16x16x32_bf16 v[14:17], v[130:133], v[200:203], v[14:17]
	v_mfma_f32_16x16x32_bf16 v[6:9], v[138:141], v[200:203], v[6:9]
	v_mfma_f32_16x16x32_bf16 v[62:65], v[134:137], v[174:177], v[62:65]
	v_mfma_f32_16x16x32_bf16 v[54:57], v[142:145], v[174:177], v[54:57]
	v_mfma_f32_16x16x32_bf16 v[46:49], v[134:137], v[188:191], v[46:49]
	v_mfma_f32_16x16x32_bf16 v[38:41], v[142:145], v[188:191], v[38:41]
	v_mfma_f32_16x16x32_bf16 v[30:33], v[134:137], v[196:199], v[30:33]
	v_mfma_f32_16x16x32_bf16 v[22:25], v[142:145], v[196:199], v[22:25]
	v_mfma_f32_16x16x32_bf16 v[14:17], v[134:137], v[204:207], v[14:17]
	v_mfma_f32_16x16x32_bf16 v[6:9], v[142:145], v[204:207], v[6:9]
	s_setprio 0
	s_setprio 1
	v_mfma_f32_16x16x32_bf16 v[58:61], v[154:157], v[170:173], v[58:61]
	v_mfma_f32_16x16x32_bf16 v[50:53], v[162:165], v[170:173], v[50:53]
	v_mfma_f32_16x16x32_bf16 v[42:45], v[154:157], v[178:181], v[42:45]
	v_mfma_f32_16x16x32_bf16 v[34:37], v[162:165], v[178:181], v[34:37]
	v_mfma_f32_16x16x32_bf16 v[26:29], v[154:157], v[192:195], v[26:29]
	v_mfma_f32_16x16x32_bf16 v[18:21], v[162:165], v[192:195], v[18:21]
	v_mfma_f32_16x16x32_bf16 v[10:13], v[154:157], v[200:203], v[10:13]
	v_mfma_f32_16x16x32_bf16 v[2:5], v[162:165], v[200:203], v[2:5]
	v_mfma_f32_16x16x32_bf16 v[58:61], v[158:161], v[174:177], v[58:61]
	v_mfma_f32_16x16x32_bf16 v[50:53], v[166:169], v[174:177], v[50:53]
	v_mfma_f32_16x16x32_bf16 v[42:45], v[158:161], v[188:191], v[42:45]
	v_mfma_f32_16x16x32_bf16 v[34:37], v[166:169], v[188:191], v[34:37]
	v_mfma_f32_16x16x32_bf16 v[26:29], v[158:161], v[196:199], v[26:29]
	s_setprio 2
	s_barrier
	v_mfma_f32_16x16x32_bf16 v[18:21], v[166:169], v[196:199], v[18:21]
	v_mfma_f32_16x16x32_bf16 v[10:13], v[158:161], v[204:207], v[10:13]
	v_mfma_f32_16x16x32_bf16 v[2:5], v[166:169], v[204:207], v[2:5]
	s_setprio 0
	s_add_i32 s6, 0, 0x18000
	v_add_u32_e32 v0, s6, v186
	s_add_i32 s12, 0, 0x1c000
	ds_read_b128 v[130:133], v0
	ds_read_b128 v[134:137], v0 offset:1024
	ds_read_b128 v[138:141], v0 offset:2048
	ds_read_b128 v[142:145], v0 offset:3072
	v_add_u32_e32 v0, s12, v186
	ds_read_b128 v[154:157], v0
	ds_read_b128 v[158:161], v0 offset:1024
	ds_read_b128 v[162:165], v0 offset:2048
	ds_read_b128 v[166:169], v0 offset:3072
	s_add_u32 s14, s30, 0x80000
	s_addc_u32 s15, s31, 0
	s_mov_b32 m0, s58
	v_lshl_add_u64 v[214:215], s[14:15], 0, v[148:149]
	ds_read_b128 v[170:173], v187 offset:32768
	ds_read_b128 v[174:177], v187 offset:33792
	ds_read_b128 v[178:181], v187 offset:34816
	ds_read_b128 v[188:191], v187 offset:35840
	ds_read_b128 v[192:195], v187 offset:36864
	ds_read_b128 v[196:199], v187 offset:37888
	ds_read_b128 v[200:203], v187 offset:38912
	ds_read_b128 v[204:207], v187 offset:39936
	global_load_lds_dwordx4 v[214:215], off
	v_lshl_add_u64 v[214:215], s[14:15], 0, v[146:147]
	s_mov_b32 m0, s59
	s_nop 0
	global_load_lds_dwordx4 v[214:215], off
	s_waitcnt vmcnt(8)
	s_waitcnt lgkmcnt(0)
	s_barrier
	s_setprio 1
	s_waitcnt lgkmcnt(0)
	v_mfma_f32_16x16x32_bf16 v[126:129], v[130:133], v[170:173], v[126:129]
	v_mfma_f32_16x16x32_bf16 v[118:121], v[138:141], v[170:173], v[118:121]
	v_mfma_f32_16x16x32_bf16 v[110:113], v[130:133], v[178:181], v[110:113]
	v_mfma_f32_16x16x32_bf16 v[102:105], v[138:141], v[178:181], v[102:105]
	v_mfma_f32_16x16x32_bf16 v[94:97], v[130:133], v[192:195], v[94:97]
	v_mfma_f32_16x16x32_bf16 v[86:89], v[138:141], v[192:195], v[86:89]
	v_mfma_f32_16x16x32_bf16 v[78:81], v[130:133], v[200:203], v[78:81]
	v_mfma_f32_16x16x32_bf16 v[70:73], v[138:141], v[200:203], v[70:73]
	v_mfma_f32_16x16x32_bf16 v[126:129], v[134:137], v[174:177], v[126:129]
	v_mfma_f32_16x16x32_bf16 v[118:121], v[142:145], v[174:177], v[118:121]
	v_mfma_f32_16x16x32_bf16 v[110:113], v[134:137], v[188:191], v[110:113]
	v_mfma_f32_16x16x32_bf16 v[102:105], v[142:145], v[188:191], v[102:105]
	v_mfma_f32_16x16x32_bf16 v[94:97], v[134:137], v[196:199], v[94:97]
	v_mfma_f32_16x16x32_bf16 v[86:89], v[142:145], v[196:199], v[86:89]
	v_mfma_f32_16x16x32_bf16 v[78:81], v[134:137], v[204:207], v[78:81]
	v_mfma_f32_16x16x32_bf16 v[70:73], v[142:145], v[204:207], v[70:73]
	s_setprio 0
	s_setprio 1
	v_mfma_f32_16x16x32_bf16 v[122:125], v[154:157], v[170:173], v[122:125]
	v_mfma_f32_16x16x32_bf16 v[114:117], v[162:165], v[170:173], v[114:117]
	v_mfma_f32_16x16x32_bf16 v[106:109], v[154:157], v[178:181], v[106:109]
	v_mfma_f32_16x16x32_bf16 v[98:101], v[162:165], v[178:181], v[98:101]
	v_mfma_f32_16x16x32_bf16 v[90:93], v[154:157], v[192:195], v[90:93]
	v_mfma_f32_16x16x32_bf16 v[82:85], v[162:165], v[192:195], v[82:85]
	v_mfma_f32_16x16x32_bf16 v[74:77], v[154:157], v[200:203], v[74:77]
	v_mfma_f32_16x16x32_bf16 v[66:69], v[162:165], v[200:203], v[66:69]
	v_mfma_f32_16x16x32_bf16 v[122:125], v[158:161], v[174:177], v[122:125]
	v_mfma_f32_16x16x32_bf16 v[114:117], v[166:169], v[174:177], v[114:117]
	v_mfma_f32_16x16x32_bf16 v[106:109], v[158:161], v[188:191], v[106:109]
	v_mfma_f32_16x16x32_bf16 v[98:101], v[166:169], v[188:191], v[98:101]
	v_mfma_f32_16x16x32_bf16 v[90:93], v[158:161], v[196:199], v[90:93]
	s_setprio 2
	s_barrier
; #define PG8_STAGE(bufoff, gbase, voff) do { _Pragma("unroll") for (int _i = 0; _i < 2; ++_i) \
;         __builtin_amdgcn_global_load_lds((const unsigned*)((const char*)(gbase) + (voff)[_i]), (LAS unsigned*)(lds + (bufoff) + ldsw + _i * 8192), 16, 0, 0); } while (0)
; #define PG8_LDA(dst, b, h) do { _Pragma("unroll") for (int m = 0; m < 4; ++m) _Pragma("unroll") for (int k = 0; k < 2; ++k) dst[m][k] = *(const LAS bf16x8*)(lds + PG8_SA(b, h) + aoff + m * 2048 + k * 1024); } while (0)
; #define PG8_MMA(ai, bj, At, Bt) do { __builtin_amdgcn_s_setprio(1); _Pragma("unroll") for (int m = 0; m < 4; ++m) _Pragma("unroll") for (int n = 0; n < 2; ++n) _Pragma("unroll") for (int k = 0; k < 2; ++k) \
;         acc[ai][bj][m][n] = __builtin_amdgcn_mfma_f32_16x16x32_bf16(Bt[n][k], At[m][k], acc[ai][bj][m][n], 0, 0, 0); __builtin_amdgcn_s_setprio(0); } while (0)
; #define PG8_WAIT_V(n) asm volatile("s_waitcnt vmcnt(" #n ")" ::: "memory")
; #define PG8_WAIT_L(n) asm volatile("s_waitcnt lgkmcnt(" #n ")" ::: "memory")
; #define PG8_BAR __builtin_amdgcn_s_barrier()
; #define PG8_SCHED __builtin_amdgcn_sched_barrier(0)
; template <class Epi>
; __device__ __forceinline__ void gemm_phase(LAS unsigned char* lds, const Gemm g, const TileOrder& S, const Epi& E) {
;     ...
;             PG8_WAIT_V(8); PG8_WAIT_L(0); PG8_BAR; PG8_MMA(0, 0, At, B0); PG8_MMA(0, 1, At, B1); PG8_BAR; PG8_SCHED;
;             PG8_LDA(At, 1, 1); PG8_STAGE(PG8_SB(1, 0), b3, voffB); PG8_STAGE(PG8_SB(1, 1), b3 + hstepB, voffB); PG8_STAGE(PG8_SA(1, 0), a3, voffA);
;             PG8_WAIT_V(8); PG8_WAIT_L(0); PG8_BAR; PG8_MMA(1, 0, At, B0); PG8_MMA(1, 1, At, B1); PG8_BAR; PG8_SCHED;
;         }
;         if (wr == 0) PG8_BAR;
	v_mfma_f32_16x16x32_bf16 v[82:85], v[166:169], v[196:199], v[82:85]
	v_mfma_f32_16x16x32_bf16 v[74:77], v[158:161], v[204:207], v[74:77]
	v_mfma_f32_16x16x32_bf16 v[66:69], v[166:169], v[204:207], v[66:69]
	s_setprio 0
	s_add_i32 s6, s6, s55
	v_lshl_add_u64 v[182:183], v[182:183], 0, s[34:35]
	s_mov_b32 m0, s6
	ds_read_b128 v[170:173], v187 offset:49152
	ds_read_b128 v[174:177], v187 offset:50176
	ds_read_b128 v[178:181], v187 offset:51200
	ds_read_b128 v[188:191], v187 offset:52224
	ds_read_b128 v[192:195], v187 offset:53248
	ds_read_b128 v[196:199], v187 offset:54272
	ds_read_b128 v[200:203], v187 offset:55296
	ds_read_b128 v[204:207], v187 offset:56320
	global_load_lds_dwordx4 v[182:183], off
	s_add_i32 m0, s6, 0x2000
	s_add_u32 s2, s2, 0x80080
	v_lshl_add_u64 v[182:183], v[208:209], 0, s[34:35]
	s_addc_u32 s3, s3, 0
	s_add_i32 s6, s12, s55
	global_load_lds_dwordx4 v[182:183], off
	v_lshl_add_u64 v[182:183], s[2:3], 0, v[148:149]
	s_mov_b32 m0, s6
	s_nop 0
	global_load_lds_dwordx4 v[182:183], off
	v_lshl_add_u64 v[182:183], s[2:3], 0, v[146:147]
	s_add_i32 m0, s6, 0x2000
	s_nop 0
	global_load_lds_dwordx4 v[182:183], off
	v_lshl_add_u64 v[182:183], v[210:211], 0, s[34:35]
	s_mov_b32 m0, s61
	s_nop 0
	global_load_lds_dwordx4 v[182:183], off
	v_lshl_add_u64 v[182:183], v[212:213], 0, s[34:35]
	s_mov_b32 m0, s62
	s_nop 0
	global_load_lds_dwordx4 v[182:183], off
	s_waitcnt vmcnt(8)
	s_waitcnt lgkmcnt(0)
	s_barrier
	s_setprio 1
	s_waitcnt lgkmcnt(0)
	v_mfma_f32_16x16x32_bf16 v[62:65], v[130:133], v[170:173], v[62:65]
	v_mfma_f32_16x16x32_bf16 v[54:57], v[138:141], v[170:173], v[54:57]
	v_mfma_f32_16x16x32_bf16 v[46:49], v[130:133], v[178:181], v[46:49]
	v_mfma_f32_16x16x32_bf16 v[38:41], v[138:141], v[178:181], v[38:41]
	v_mfma_f32_16x16x32_bf16 v[30:33], v[130:133], v[192:195], v[30:33]
	v_mfma_f32_16x16x32_bf16 v[22:25], v[138:141], v[192:195], v[22:25]
	v_mfma_f32_16x16x32_bf16 v[14:17], v[130:133], v[200:203], v[14:17]
	v_mfma_f32_16x16x32_bf16 v[6:9], v[138:141], v[200:203], v[6:9]
	v_mfma_f32_16x16x32_bf16 v[62:65], v[134:137], v[174:177], v[62:65]
	v_mfma_f32_16x16x32_bf16 v[54:57], v[142:145], v[174:177], v[54:57]
	v_mfma_f32_16x16x32_bf16 v[46:49], v[134:137], v[188:191], v[46:49]
	v_mfma_f32_16x16x32_bf16 v[38:41], v[142:145], v[188:191], v[38:41]
	v_mfma_f32_16x16x32_bf16 v[30:33], v[134:137], v[196:199], v[30:33]
	v_mfma_f32_16x16x32_bf16 v[22:25], v[142:145], v[196:199], v[22:25]
	v_mfma_f32_16x16x32_bf16 v[14:17], v[134:137], v[204:207], v[14:17]
	v_mfma_f32_16x16x32_bf16 v[6:9], v[142:145], v[204:207], v[6:9]
	s_setprio 0
	s_setprio 1
	v_mfma_f32_16x16x32_bf16 v[58:61], v[154:157], v[170:173], v[58:61]
	v_mfma_f32_16x16x32_bf16 v[50:53], v[162:165], v[170:173], v[50:53]
	v_mfma_f32_16x16x32_bf16 v[42:45], v[154:157], v[178:181], v[42:45]
	v_mfma_f32_16x16x32_bf16 v[34:37], v[162:165], v[178:181], v[34:37]
	v_mfma_f32_16x16x32_bf16 v[26:29], v[154:157], v[192:195], v[26:29]
	v_mfma_f32_16x16x32_bf16 v[18:21], v[162:165], v[192:195], v[18:21]
	v_mfma_f32_16x16x32_bf16 v[10:13], v[154:157], v[200:203], v[10:13]
	v_mfma_f32_16x16x32_bf16 v[2:5], v[162:165], v[200:203], v[2:5]
	v_mfma_f32_16x16x32_bf16 v[58:61], v[158:161], v[174:177], v[58:61]
	v_mfma_f32_16x16x32_bf16 v[50:53], v[166:169], v[174:177], v[50:53]
	v_mfma_f32_16x16x32_bf16 v[42:45], v[158:161], v[188:191], v[42:45]
	v_mfma_f32_16x16x32_bf16 v[34:37], v[166:169], v[188:191], v[34:37]
	v_mfma_f32_16x16x32_bf16 v[26:29], v[158:161], v[196:199], v[26:29]
	s_setprio 2
	s_barrier
	v_mfma_f32_16x16x32_bf16 v[18:21], v[166:169], v[196:199], v[18:21]
	v_mfma_f32_16x16x32_bf16 v[10:13], v[158:161], v[204:207], v[10:13]
	v_mfma_f32_16x16x32_bf16 v[2:5], v[166:169], v[204:207], v[2:5]
	s_setprio 0
	s_add_i32 s72, s72, 2
	s_add_u32 s28, s28, 0x100
	s_addc_u32 s29, s29, 0
	s_add_u32 s70, s70, 0x100
	s_addc_u32 s71, s71, 0
	s_cmp_gt_u32 s72, 29
	s_cbranch_scc0 .LBB0_51
	s_and_b64 vcc, exec, s[44:45]
	s_cbranch_vccz .LBB0_54
	s_barrier

; #define PG8_STAGE(bufoff, gbase, voff) do { _Pragma("unroll") for (int _i = 0; _i < 2; ++_i) \
;         __builtin_amdgcn_global_load_lds((const unsigned*)((const char*)(gbase) + (voff)[_i]), (LAS unsigned*)(lds + (bufoff) + ldsw + _i * 8192), 16, 0, 0); } while (0)
; #define PG8_LDA(dst, b, h) do { _Pragma("unroll") for (int m = 0; m < 4; ++m) _Pragma("unroll") for (int k = 0; k < 2; ++k) dst[m][k] = *(const LAS bf16x8*)(lds + PG8_SA(b, h) + aoff + m * 2048 + k * 1024); } while (0)
; #define PG8_LDB(dst, b, h) do { _Pragma("unroll") for (int n = 0; n < 2; ++n) _Pragma("unroll") for (int k = 0; k < 2; ++k) dst[n][k] = *(const LAS bf16x8*)(lds + PG8_SB(b, h) + boff + n * 2048 + k * 1024); } while (0)
; #define PG8_MMA(ai, bj, At, Bt) do { __builtin_amdgcn_s_setprio(1); _Pragma("unroll") for (int m = 0; m < 4; ++m) _Pragma("unroll") for (int n = 0; n < 2; ++n) _Pragma("unroll") for (int k = 0; k < 2; ++k) \
;         acc[ai][bj][m][n] = __builtin_amdgcn_mfma_f32_16x16x32_bf16(Bt[n][k], At[m][k], acc[ai][bj][m][n], 0, 0, 0); __builtin_amdgcn_s_setprio(0); } while (0)
; #define PG8_WAIT_V(n) asm volatile("s_waitcnt vmcnt(" #n ")" ::: "memory")
; #define PG8_WAIT_L(n) asm volatile("s_waitcnt lgkmcnt(" #n ")" ::: "memory")
; #define PG8_BAR __builtin_amdgcn_s_barrier()
; #define PG8_SCHED __builtin_amdgcn_sched_barrier(0)
; template <class Epi>
; __device__ __forceinline__ void gemm_phase(LAS unsigned char* lds, const Gemm g, const TileOrder& S, const Epi& E) {
;     ...
;             const bool last = (t == nt - 2);
;             const char* a1 = cA + (size_t)(t + 1) * kstepA;
;             const char* a2 = last ? nA : cA + (size_t)(t + 2) * kstepA; const char* b2 = last ? nB : cB + (size_t)(t + 2) * kstep;
;             const char* a3 = a2 + kstepA; const char* b3 = b2 + kstep;
;             PG8_LDB(B0, 0, 0); PG8_LDB(B1, 0, 1); PG8_SCHED; PG8_LDA(At, 0, 0); PG8_STAGE(PG8_SA(1, 1), a1 + hstepA, voffA);
;             PG8_WAIT_V(8); PG8_WAIT_L(0); PG8_BAR; PG8_MMA(0, 0, At, B0); PG8_MMA(0, 1, At, B1); PG8_BAR; PG8_SCHED;
;             PG8_LDA(At, 0, 1); PG8_STAGE(PG8_SB(0, 0), b2, voffB); PG8_STAGE(PG8_SB(0, 1), b2 + hstepB, voffB); PG8_STAGE(PG8_SA(0, 0), a2, voffA);
;             PG8_WAIT_V(8); PG8_WAIT_L(0); PG8_BAR; PG8_MMA(1, 0, At, B0); PG8_MMA(1, 1, At, B1); PG8_BAR; PG8_SCHED;
.LBB0_255:
	s_add_u32 s2, s28, 0x4000
	s_addc_u32 s3, s29, 0
	s_cmp_eq_u32 s68, 28
	s_cselect_b32 s48, s64, s2
	s_cselect_b32 s49, s43, s3
	s_cselect_b32 s30, s65, s66
	s_cselect_b32 s31, s39, s67
	s_add_u32 s2, s48, 0x8000
	s_addc_u32 s3, s49, 0
	s_add_i32 s6, 0, 0x10000
	s_add_i32 s14, 0, 0x14000
	v_add_u32_e32 v134, s6, v238
	v_add_u32_e32 v158, s14, v238
	ds_read_b128 v[118:121], v134
	ds_read_b128 v[126:129], v134 offset:1024
	ds_read_b128 v[130:133], v134 offset:2048
	ds_read_b128 v[134:137], v134 offset:3072
	ds_read_b128 v[138:141], v158
	ds_read_b128 v[142:145], v158 offset:1024
	ds_read_b128 v[154:157], v158 offset:2048
	ds_read_b128 v[158:161], v158 offset:3072
	v_lshl_add_u64 v[204:205], s[28:29], 0, v[196:197]
	s_add_i32 m0, s52, 0xc000
	ds_read_b128 v[162:165], v239
	ds_read_b128 v[166:169], v239 offset:1024
	ds_read_b128 v[170:173], v239 offset:2048
	ds_read_b128 v[174:177], v239 offset:3072
	ds_read_b128 v[178:181], v239 offset:4096
	ds_read_b128 v[182:185], v239 offset:5120
	ds_read_b128 v[186:189], v239 offset:6144
	ds_read_b128 v[200:203], v239 offset:7168
	global_load_lds_dwordx4 v[204:205], off
	v_lshl_add_u64 v[204:205], s[28:29], 0, v[198:199]
	s_add_i32 m0, s52, 0xe000
	s_nop 0
	global_load_lds_dwordx4 v[204:205], off
	s_waitcnt vmcnt(8)
	s_waitcnt lgkmcnt(0)
	s_barrier
	s_setprio 1
	s_waitcnt lgkmcnt(0)
	v_mfma_f32_16x16x32_bf16 v[150:153], v[118:121], v[162:165], v[150:153]
	v_mfma_f32_16x16x32_bf16 v[146:149], v[130:133], v[162:165], v[146:149]
	v_mfma_f32_16x16x32_bf16 v[110:113], v[118:121], v[170:173], v[110:113]
	v_mfma_f32_16x16x32_bf16 v[106:109], v[130:133], v[170:173], v[106:109]
	v_mfma_f32_16x16x32_bf16 v[94:97], v[118:121], v[178:181], v[94:97]
	v_mfma_f32_16x16x32_bf16 v[90:93], v[130:133], v[178:181], v[90:93]
	v_mfma_f32_16x16x32_bf16 v[78:81], v[118:121], v[186:189], v[78:81]
	v_mfma_f32_16x16x32_bf16 v[74:77], v[130:133], v[186:189], v[74:77]
	v_mfma_f32_16x16x32_bf16 v[150:153], v[126:129], v[166:169], v[150:153]
	v_mfma_f32_16x16x32_bf16 v[146:149], v[134:137], v[166:169], v[146:149]
	v_mfma_f32_16x16x32_bf16 v[110:113], v[126:129], v[174:177], v[110:113]
	v_mfma_f32_16x16x32_bf16 v[106:109], v[134:137], v[174:177], v[106:109]
	v_mfma_f32_16x16x32_bf16 v[94:97], v[126:129], v[182:185], v[94:97]
	v_mfma_f32_16x16x32_bf16 v[90:93], v[134:137], v[182:185], v[90:93]
	v_mfma_f32_16x16x32_bf16 v[78:81], v[126:129], v[200:203], v[78:81]
	v_mfma_f32_16x16x32_bf16 v[74:77], v[134:137], v[200:203], v[74:77]
	s_setprio 0
	s_setprio 1
	v_mfma_f32_16x16x32_bf16 v[122:125], v[138:141], v[162:165], v[122:125]
	v_mfma_f32_16x16x32_bf16 v[114:117], v[154:157], v[162:165], v[114:117]
	v_mfma_f32_16x16x32_bf16 v[102:105], v[138:141], v[170:173], v[102:105]
	v_mfma_f32_16x16x32_bf16 v[98:101], v[154:157], v[170:173], v[98:101]
	v_mfma_f32_16x16x32_bf16 v[86:89], v[138:141], v[178:181], v[86:89]
	v_mfma_f32_16x16x32_bf16 v[82:85], v[154:157], v[178:181], v[82:85]
	v_mfma_f32_16x16x32_bf16 v[70:73], v[138:141], v[186:189], v[70:73]
	v_mfma_f32_16x16x32_bf16 v[66:69], v[154:157], v[186:189], v[66:69]
	v_mfma_f32_16x16x32_bf16 v[122:125], v[142:145], v[166:169], v[122:125]
	v_mfma_f32_16x16x32_bf16 v[114:117], v[158:161], v[166:169], v[114:117]
	v_mfma_f32_16x16x32_bf16 v[102:105], v[142:145], v[174:177], v[102:105]
	v_mfma_f32_16x16x32_bf16 v[98:101], v[158:161], v[174:177], v[98:101]
	v_mfma_f32_16x16x32_bf16 v[86:89], v[142:145], v[182:185], v[86:89]
	s_setprio 2
	s_barrier
	v_mfma_f32_16x16x32_bf16 v[82:85], v[158:161], v[182:185], v[82:85]
	v_mfma_f32_16x16x32_bf16 v[70:73], v[142:145], v[200:203], v[70:73]
	v_mfma_f32_16x16x32_bf16 v[66:69], v[158:161], v[200:203], v[66:69]
	s_setprio 0
	s_add_i32 s6, s6, s51
	v_lshl_add_u64 v[204:205], s[30:31], 0, v[0:1]
	s_mov_b32 m0, s6
	ds_read_b128 v[162:165], v239 offset:16384
	ds_read_b128 v[166:169], v239 offset:17408
	ds_read_b128 v[170:173], v239 offset:18432
	ds_read_b128 v[174:177], v239 offset:19456
	ds_read_b128 v[178:181], v239 offset:20480
	ds_read_b128 v[182:185], v239 offset:21504
	ds_read_b128 v[186:189], v239 offset:22528
	ds_read_b128 v[200:203], v239 offset:23552
	global_load_lds_dwordx4 v[204:205], off
	s_add_i32 m0, s6, 0x2000
	s_add_u32 s12, s30, 0x80000
	v_lshl_add_u64 v[206:207], s[30:31], 0, v[190:191]
	s_addc_u32 s13, s31, 0
	s_add_i32 s6, s14, s51
	global_load_lds_dwordx4 v[206:207], off
	v_lshl_add_u64 v[208:209], s[12:13], 0, v[0:1]
	s_mov_b32 m0, s6
	s_nop 0
	global_load_lds_dwordx4 v[208:209], off
	v_lshl_add_u64 v[208:209], s[12:13], 0, v[190:191]
	s_add_i32 m0, s6, 0x2000
	s_nop 0
	global_load_lds_dwordx4 v[208:209], off
	v_lshl_add_u64 v[208:209], s[48:49], 0, v[194:195]
	s_mov_b32 m0, s52
	s_nop 0
	global_load_lds_dwordx4 v[208:209], off
	v_lshl_add_u64 v[208:209], s[48:49], 0, v[192:193]
	s_mov_b32 m0, s53
	s_nop 0
	global_load_lds_dwordx4 v[208:209], off
	s_waitcnt vmcnt(8)
	s_waitcnt lgkmcnt(0)
	s_barrier
; #define PG8_STAGE(bufoff, gbase, voff) do { _Pragma("unroll") for (int _i = 0; _i < 2; ++_i) \
;         __builtin_amdgcn_global_load_lds((const unsigned*)((const char*)(gbase) + (voff)[_i]), (LAS unsigned*)(lds + (bufoff) + ldsw + _i * 8192), 16, 0, 0); } while (0)
; #define PG8_LDA(dst, b, h) do { _Pragma("unroll") for (int m = 0; m < 4; ++m) _Pragma("unroll") for (int k = 0; k < 2; ++k) dst[m][k] = *(const LAS bf16x8*)(lds + PG8_SA(b, h) + aoff + m * 2048 + k * 1024); } while (0)
; #define PG8_LDB(dst, b, h) do { _Pragma("unroll") for (int n = 0; n < 2; ++n) _Pragma("unroll") for (int k = 0; k < 2; ++k) dst[n][k] = *(const LAS bf16x8*)(lds + PG8_SB(b, h) + boff + n * 2048 + k * 1024); } while (0)
; #define PG8_MMA(ai, bj, At, Bt) do { __builtin_amdgcn_s_setprio(1); _Pragma("unroll") for (int m = 0; m < 4; ++m) _Pragma("unroll") for (int n = 0; n < 2; ++n) _Pragma("unroll") for (int k = 0; k < 2; ++k) \
;         acc[ai][bj][m][n] = __builtin_amdgcn_mfma_f32_16x16x32_bf16(Bt[n][k], At[m][k], acc[ai][bj][m][n], 0, 0, 0); __builtin_amdgcn_s_setprio(0); } while (0)
; #define PG8_WAIT_V(n) asm volatile("s_waitcnt vmcnt(" #n ")" ::: "memory")
; #define PG8_WAIT_L(n) asm volatile("s_waitcnt lgkmcnt(" #n ")" ::: "memory")
; #define PG8_BAR __builtin_amdgcn_s_barrier()
; #define PG8_SCHED __builtin_amdgcn_sched_barrier(0)
; template <class Epi>
; __device__ __forceinline__ void gemm_phase(LAS unsigned char* lds, const Gemm g, const TileOrder& S, const Epi& E) {
;     ...
;             PG8_WAIT_V(8); PG8_WAIT_L(0); PG8_BAR; PG8_MMA(1, 0, At, B0); PG8_MMA(1, 1, At, B1); PG8_BAR; PG8_SCHED;
;             PG8_LDB(B0, 1, 0); PG8_LDB(B1, 1, 1); PG8_SCHED; PG8_LDA(At, 1, 0); PG8_STAGE(PG8_SA(0, 1), a2 + hstepA, voffA);
;             PG8_WAIT_V(8); PG8_WAIT_L(0); PG8_BAR; PG8_MMA(0, 0, At, B0); PG8_MMA(0, 1, At, B1); PG8_BAR; PG8_SCHED;
	s_setprio 1
	s_waitcnt lgkmcnt(0)
	v_mfma_f32_16x16x32_bf16 v[62:65], v[118:121], v[162:165], v[62:65]
	v_mfma_f32_16x16x32_bf16 v[58:61], v[130:133], v[162:165], v[58:61]
	v_mfma_f32_16x16x32_bf16 v[46:49], v[118:121], v[170:173], v[46:49]
	v_mfma_f32_16x16x32_bf16 v[42:45], v[130:133], v[170:173], v[42:45]
	v_mfma_f32_16x16x32_bf16 v[30:33], v[118:121], v[178:181], v[30:33]
	v_mfma_f32_16x16x32_bf16 v[26:29], v[130:133], v[178:181], v[26:29]
	v_mfma_f32_16x16x32_bf16 v[14:17], v[118:121], v[186:189], v[14:17]
	v_mfma_f32_16x16x32_bf16 v[10:13], v[130:133], v[186:189], v[10:13]
	v_mfma_f32_16x16x32_bf16 v[62:65], v[126:129], v[166:169], v[62:65]
	v_mfma_f32_16x16x32_bf16 v[58:61], v[134:137], v[166:169], v[58:61]
	v_mfma_f32_16x16x32_bf16 v[46:49], v[126:129], v[174:177], v[46:49]
	v_mfma_f32_16x16x32_bf16 v[42:45], v[134:137], v[174:177], v[42:45]
	v_mfma_f32_16x16x32_bf16 v[30:33], v[126:129], v[182:185], v[30:33]
	v_mfma_f32_16x16x32_bf16 v[26:29], v[134:137], v[182:185], v[26:29]
	v_mfma_f32_16x16x32_bf16 v[14:17], v[126:129], v[200:203], v[14:17]
	v_mfma_f32_16x16x32_bf16 v[10:13], v[134:137], v[200:203], v[10:13]
	s_setprio 0
	s_setprio 1
	v_mfma_f32_16x16x32_bf16 v[54:57], v[138:141], v[162:165], v[54:57]
	v_mfma_f32_16x16x32_bf16 v[50:53], v[154:157], v[162:165], v[50:53]
	v_mfma_f32_16x16x32_bf16 v[38:41], v[138:141], v[170:173], v[38:41]
	v_mfma_f32_16x16x32_bf16 v[34:37], v[154:157], v[170:173], v[34:37]
	v_mfma_f32_16x16x32_bf16 v[22:25], v[138:141], v[178:181], v[22:25]
	v_mfma_f32_16x16x32_bf16 v[18:21], v[154:157], v[178:181], v[18:21]
	v_mfma_f32_16x16x32_bf16 v[6:9], v[138:141], v[186:189], v[6:9]
	v_mfma_f32_16x16x32_bf16 v[2:5], v[154:157], v[186:189], v[2:5]
	v_mfma_f32_16x16x32_bf16 v[54:57], v[142:145], v[166:169], v[54:57]
	v_mfma_f32_16x16x32_bf16 v[50:53], v[158:161], v[166:169], v[50:53]
	v_mfma_f32_16x16x32_bf16 v[38:41], v[142:145], v[174:177], v[38:41]
	v_mfma_f32_16x16x32_bf16 v[34:37], v[158:161], v[174:177], v[34:37]
	v_mfma_f32_16x16x32_bf16 v[22:25], v[142:145], v[182:185], v[22:25]
	s_setprio 2
	s_barrier
	v_mfma_f32_16x16x32_bf16 v[18:21], v[158:161], v[182:185], v[18:21]
	v_mfma_f32_16x16x32_bf16 v[6:9], v[142:145], v[200:203], v[6:9]
	v_mfma_f32_16x16x32_bf16 v[2:5], v[158:161], v[200:203], v[2:5]
	s_setprio 0
	s_add_i32 s6, 0, 0x18000
	s_add_i32 s14, 0, 0x1c000
	v_add_u32_e32 v134, s6, v238
	v_add_u32_e32 v158, s14, v238
	ds_read_b128 v[118:121], v134
	ds_read_b128 v[126:129], v134 offset:1024
	ds_read_b128 v[130:133], v134 offset:2048
	ds_read_b128 v[134:137], v134 offset:3072
	ds_read_b128 v[138:141], v158
	ds_read_b128 v[142:145], v158 offset:1024
	ds_read_b128 v[154:157], v158 offset:2048
	ds_read_b128 v[158:161], v158 offset:3072
	s_add_u32 s12, s48, 0x4000
	s_addc_u32 s13, s49, 0
	s_mov_b32 m0, s54
	v_lshl_add_u64 v[208:209], s[12:13], 0, v[194:195]
	ds_read_b128 v[162:165], v239 offset:32768
	ds_read_b128 v[166:169], v239 offset:33792
	ds_read_b128 v[170:173], v239 offset:34816
	ds_read_b128 v[174:177], v239 offset:35840
	ds_read_b128 v[178:181], v239 offset:36864
	ds_read_b128 v[182:185], v239 offset:37888
	ds_read_b128 v[186:189], v239 offset:38912
	ds_read_b128 v[200:203], v239 offset:39936
	global_load_lds_dwordx4 v[208:209], off
	v_lshl_add_u64 v[208:209], s[12:13], 0, v[192:193]
	s_mov_b32 m0, s55
	s_nop 0
	global_load_lds_dwordx4 v[208:209], off
	s_waitcnt vmcnt(8)
	s_waitcnt lgkmcnt(0)
	s_barrier
	s_setprio 1
	s_waitcnt lgkmcnt(0)
	v_mfma_f32_16x16x32_bf16 v[150:153], v[118:121], v[162:165], v[150:153]
	v_mfma_f32_16x16x32_bf16 v[146:149], v[130:133], v[162:165], v[146:149]
	v_mfma_f32_16x16x32_bf16 v[110:113], v[118:121], v[170:173], v[110:113]
	v_mfma_f32_16x16x32_bf16 v[106:109], v[130:133], v[170:173], v[106:109]
	v_mfma_f32_16x16x32_bf16 v[94:97], v[118:121], v[178:181], v[94:97]
	v_mfma_f32_16x16x32_bf16 v[90:93], v[130:133], v[178:181], v[90:93]
	v_mfma_f32_16x16x32_bf16 v[78:81], v[118:121], v[186:189], v[78:81]
	v_mfma_f32_16x16x32_bf16 v[74:77], v[130:133], v[186:189], v[74:77]
	v_mfma_f32_16x16x32_bf16 v[150:153], v[126:129], v[166:169], v[150:153]
	v_mfma_f32_16x16x32_bf16 v[146:149], v[134:137], v[166:169], v[146:149]
	v_mfma_f32_16x16x32_bf16 v[110:113], v[126:129], v[174:177], v[110:113]
	v_mfma_f32_16x16x32_bf16 v[106:109], v[134:137], v[174:177], v[106:109]
	v_mfma_f32_16x16x32_bf16 v[94:97], v[126:129], v[182:185], v[94:97]
	v_mfma_f32_16x16x32_bf16 v[90:93], v[134:137], v[182:185], v[90:93]
	v_mfma_f32_16x16x32_bf16 v[78:81], v[126:129], v[200:203], v[78:81]
	v_mfma_f32_16x16x32_bf16 v[74:77], v[134:137], v[200:203], v[74:77]
	s_setprio 0
	s_setprio 1
	v_mfma_f32_16x16x32_bf16 v[122:125], v[138:141], v[162:165], v[122:125]
	v_mfma_f32_16x16x32_bf16 v[114:117], v[154:157], v[162:165], v[114:117]
	v_mfma_f32_16x16x32_bf16 v[102:105], v[138:141], v[170:173], v[102:105]
	v_mfma_f32_16x16x32_bf16 v[98:101], v[154:157], v[170:173], v[98:101]
	v_mfma_f32_16x16x32_bf16 v[86:89], v[138:141], v[178:181], v[86:89]
	v_mfma_f32_16x16x32_bf16 v[82:85], v[154:157], v[178:181], v[82:85]
	v_mfma_f32_16x16x32_bf16 v[70:73], v[138:141], v[186:189], v[70:73]
	v_mfma_f32_16x16x32_bf16 v[66:69], v[154:157], v[186:189], v[66:69]
	v_mfma_f32_16x16x32_bf16 v[122:125], v[142:145], v[166:169], v[122:125]
	v_mfma_f32_16x16x32_bf16 v[114:117], v[158:161], v[166:169], v[114:117]
	v_mfma_f32_16x16x32_bf16 v[102:105], v[142:145], v[174:177], v[102:105]
	v_mfma_f32_16x16x32_bf16 v[98:101], v[158:161], v[174:177], v[98:101]
	v_mfma_f32_16x16x32_bf16 v[86:89], v[142:145], v[182:185], v[86:89]
	s_setprio 2
	s_barrier
; #define PG8_STAGE(bufoff, gbase, voff) do { _Pragma("unroll") for (int _i = 0; _i < 2; ++_i) \
;         __builtin_amdgcn_global_load_lds((const unsigned*)((const char*)(gbase) + (voff)[_i]), (LAS unsigned*)(lds + (bufoff) + ldsw + _i * 8192), 16, 0, 0); } while (0)
; #define PG8_LDA(dst, b, h) do { _Pragma("unroll") for (int m = 0; m < 4; ++m) _Pragma("unroll") for (int k = 0; k < 2; ++k) dst[m][k] = *(const LAS bf16x8*)(lds + PG8_SA(b, h) + aoff + m * 2048 + k * 1024); } while (0)
; #define PG8_MMA(ai, bj, At, Bt) do { __builtin_amdgcn_s_setprio(1); _Pragma("unroll") for (int m = 0; m < 4; ++m) _Pragma("unroll") for (int n = 0; n < 2; ++n) _Pragma("unroll") for (int k = 0; k < 2; ++k) \
;         acc[ai][bj][m][n] = __builtin_amdgcn_mfma_f32_16x16x32_bf16(Bt[n][k], At[m][k], acc[ai][bj][m][n], 0, 0, 0); __builtin_amdgcn_s_setprio(0); } while (0)
; #define PG8_WAIT_V(n) asm volatile("s_waitcnt vmcnt(" #n ")" ::: "memory")
; #define PG8_WAIT_L(n) asm volatile("s_waitcnt lgkmcnt(" #n ")" ::: "memory")
; #define PG8_BAR __builtin_amdgcn_s_barrier()
; #define PG8_SCHED __builtin_amdgcn_sched_barrier(0)
; template <class Epi>
; __device__ __forceinline__ void gemm_phase(LAS unsigned char* lds, const Gemm g, const TileOrder& S, const Epi& E) {
;     ...
;             PG8_WAIT_V(8); PG8_WAIT_L(0); PG8_BAR; PG8_MMA(0, 0, At, B0); PG8_MMA(0, 1, At, B1); PG8_BAR; PG8_SCHED;
;             PG8_LDA(At, 1, 1); PG8_STAGE(PG8_SB(1, 0), b3, voffB); PG8_STAGE(PG8_SB(1, 1), b3 + hstepB, voffB); PG8_STAGE(PG8_SA(1, 0), a3, voffA);
;             PG8_WAIT_V(8); PG8_WAIT_L(0); PG8_BAR; PG8_MMA(1, 0, At, B0); PG8_MMA(1, 1, At, B1); PG8_BAR; PG8_SCHED;
;         }
;         if (wr == 0) PG8_BAR;
	v_mfma_f32_16x16x32_bf16 v[82:85], v[158:161], v[182:185], v[82:85]
	v_mfma_f32_16x16x32_bf16 v[70:73], v[142:145], v[200:203], v[70:73]
	v_mfma_f32_16x16x32_bf16 v[66:69], v[158:161], v[200:203], v[66:69]
	s_setprio 0
	s_add_i32 s6, s6, s51
	v_lshl_add_u64 v[204:205], v[204:205], 0, s[34:35]
	s_mov_b32 m0, s6
	ds_read_b128 v[162:165], v239 offset:49152
	ds_read_b128 v[166:169], v239 offset:50176
	ds_read_b128 v[170:173], v239 offset:51200
	ds_read_b128 v[174:177], v239 offset:52224
	ds_read_b128 v[178:181], v239 offset:53248
	ds_read_b128 v[182:185], v239 offset:54272
	ds_read_b128 v[186:189], v239 offset:55296
	ds_read_b128 v[200:203], v239 offset:56320
	global_load_lds_dwordx4 v[204:205], off
	s_add_i32 m0, s6, 0x2000
	s_add_u32 s12, s30, 0x80080
	v_lshl_add_u64 v[204:205], v[206:207], 0, s[34:35]
	s_addc_u32 s13, s31, 0
	s_add_i32 s6, s14, s51
	global_load_lds_dwordx4 v[204:205], off
	v_lshl_add_u64 v[204:205], s[12:13], 0, v[0:1]
	s_mov_b32 m0, s6
	s_nop 0
	global_load_lds_dwordx4 v[204:205], off
	v_lshl_add_u64 v[204:205], s[12:13], 0, v[190:191]
	s_add_i32 m0, s6, 0x2000
	s_nop 0
	global_load_lds_dwordx4 v[204:205], off
	v_lshl_add_u64 v[204:205], s[2:3], 0, v[194:195]
	s_mov_b32 m0, s60
	s_nop 0
	global_load_lds_dwordx4 v[204:205], off
	v_lshl_add_u64 v[204:205], s[2:3], 0, v[192:193]
	s_mov_b32 m0, s61
	s_nop 0
	global_load_lds_dwordx4 v[204:205], off
	s_waitcnt vmcnt(8)
	s_waitcnt lgkmcnt(0)
	s_barrier
	s_setprio 1
	s_waitcnt lgkmcnt(0)
	v_mfma_f32_16x16x32_bf16 v[62:65], v[118:121], v[162:165], v[62:65]
	v_mfma_f32_16x16x32_bf16 v[58:61], v[130:133], v[162:165], v[58:61]
	v_mfma_f32_16x16x32_bf16 v[46:49], v[118:121], v[170:173], v[46:49]
	v_mfma_f32_16x16x32_bf16 v[42:45], v[130:133], v[170:173], v[42:45]
	v_mfma_f32_16x16x32_bf16 v[30:33], v[118:121], v[178:181], v[30:33]
	v_mfma_f32_16x16x32_bf16 v[26:29], v[130:133], v[178:181], v[26:29]
	v_mfma_f32_16x16x32_bf16 v[14:17], v[118:121], v[186:189], v[14:17]
	v_mfma_f32_16x16x32_bf16 v[10:13], v[130:133], v[186:189], v[10:13]
	v_mfma_f32_16x16x32_bf16 v[62:65], v[126:129], v[166:169], v[62:65]
	v_mfma_f32_16x16x32_bf16 v[58:61], v[134:137], v[166:169], v[58:61]
	v_mfma_f32_16x16x32_bf16 v[46:49], v[126:129], v[174:177], v[46:49]
	v_mfma_f32_16x16x32_bf16 v[42:45], v[134:137], v[174:177], v[42:45]
	v_mfma_f32_16x16x32_bf16 v[30:33], v[126:129], v[182:185], v[30:33]
	v_mfma_f32_16x16x32_bf16 v[26:29], v[134:137], v[182:185], v[26:29]
	v_mfma_f32_16x16x32_bf16 v[14:17], v[126:129], v[200:203], v[14:17]
	v_mfma_f32_16x16x32_bf16 v[10:13], v[134:137], v[200:203], v[10:13]
	s_setprio 0
	s_setprio 1
	v_mfma_f32_16x16x32_bf16 v[54:57], v[138:141], v[162:165], v[54:57]
	v_mfma_f32_16x16x32_bf16 v[50:53], v[154:157], v[162:165], v[50:53]
	v_mfma_f32_16x16x32_bf16 v[38:41], v[138:141], v[170:173], v[38:41]
	v_mfma_f32_16x16x32_bf16 v[34:37], v[154:157], v[170:173], v[34:37]
	v_mfma_f32_16x16x32_bf16 v[22:25], v[138:141], v[178:181], v[22:25]
	v_mfma_f32_16x16x32_bf16 v[18:21], v[154:157], v[178:181], v[18:21]
	v_mfma_f32_16x16x32_bf16 v[6:9], v[138:141], v[186:189], v[6:9]
	v_mfma_f32_16x16x32_bf16 v[2:5], v[154:157], v[186:189], v[2:5]
	v_mfma_f32_16x16x32_bf16 v[54:57], v[142:145], v[166:169], v[54:57]
	v_mfma_f32_16x16x32_bf16 v[50:53], v[158:161], v[166:169], v[50:53]
	v_mfma_f32_16x16x32_bf16 v[38:41], v[142:145], v[174:177], v[38:41]
	v_mfma_f32_16x16x32_bf16 v[34:37], v[158:161], v[174:177], v[34:37]
	v_mfma_f32_16x16x32_bf16 v[22:25], v[142:145], v[182:185], v[22:25]
	s_setprio 2
	s_barrier
	v_mfma_f32_16x16x32_bf16 v[18:21], v[158:161], v[182:185], v[18:21]
	v_mfma_f32_16x16x32_bf16 v[6:9], v[142:145], v[200:203], v[6:9]
	v_mfma_f32_16x16x32_bf16 v[2:5], v[158:161], v[200:203], v[2:5]
	s_setprio 0
	s_add_i32 s68, s68, 2
	s_add_u32 s66, s66, 0x100
	s_addc_u32 s67, s67, 0
	s_add_u32 s28, s28, 0x10000
	s_addc_u32 s29, s29, 0
	s_cmp_gt_u32 s68, 29
	s_cbranch_scc0 .LBB0_255
	s_and_b64 vcc, exec, s[36:37]
	s_cbranch_vccz .LBB0_258
	s_barrier

; #define PG8_STAGE(bufoff, gbase, voff) do { _Pragma("unroll") for (int _i = 0; _i < 2; ++_i) \
;         __builtin_amdgcn_global_load_lds((const unsigned*)((const char*)(gbase) + (voff)[_i]), (LAS unsigned*)(lds + (bufoff) + ldsw + _i * 8192), 16, 0, 0); } while (0)
; #define PG8_LDA(dst, b, h) do { _Pragma("unroll") for (int m = 0; m < 4; ++m) _Pragma("unroll") for (int k = 0; k < 2; ++k) dst[m][k] = *(const LAS bf16x8*)(lds + PG8_SA(b, h) + aoff + m * 2048 + k * 1024); } while (0)
; #define PG8_LDB(dst, b, h) do { _Pragma("unroll") for (int n = 0; n < 2; ++n) _Pragma("unroll") for (int k = 0; k < 2; ++k) dst[n][k] = *(const LAS bf16x8*)(lds + PG8_SB(b, h) + boff + n * 2048 + k * 1024); } while (0)
; #define PG8_MMA(ai, bj, At, Bt) do { __builtin_amdgcn_s_setprio(1); _Pragma("unroll") for (int m = 0; m < 4; ++m) _Pragma("unroll") for (int n = 0; n < 2; ++n) _Pragma("unroll") for (int k = 0; k < 2; ++k) \
;         acc[ai][bj][m][n] = __builtin_amdgcn_mfma_f32_16x16x32_bf16(Bt[n][k], At[m][k], acc[ai][bj][m][n], 0, 0, 0); __builtin_amdgcn_s_setprio(0); } while (0)
; #define PG8_WAIT_V(n) asm volatile("s_waitcnt vmcnt(" #n ")" ::: "memory")
; #define PG8_WAIT_L(n) asm volatile("s_waitcnt lgkmcnt(" #n ")" ::: "memory")
; #define PG8_BAR __builtin_amdgcn_s_barrier()
; #define PG8_SCHED __builtin_amdgcn_sched_barrier(0)
; template <class Epi>
; __device__ __forceinline__ void gemm_phase(LAS unsigned char* lds, const Gemm g, const TileOrder& S, const Epi& E) {
;     ...
;             const bool last = (t == nt - 2);
;             const char* a1 = cA + (size_t)(t + 1) * kstepA;
;             const char* a2 = last ? nA : cA + (size_t)(t + 2) * kstepA; const char* b2 = last ? nB : cB + (size_t)(t + 2) * kstep;
;             const char* a3 = a2 + kstepA; const char* b3 = b2 + kstep;
;             PG8_LDB(B0, 0, 0); PG8_LDB(B1, 0, 1); PG8_SCHED; PG8_LDA(At, 0, 0); PG8_STAGE(PG8_SA(1, 1), a1 + hstepA, voffA);
;             PG8_WAIT_V(8); PG8_WAIT_L(0); PG8_BAR; PG8_MMA(0, 0, At, B0); PG8_MMA(0, 1, At, B1); PG8_BAR; PG8_SCHED;
;             PG8_LDA(At, 0, 1); PG8_STAGE(PG8_SB(0, 0), b2, voffB); PG8_STAGE(PG8_SB(0, 1), b2 + hstepB, voffB); PG8_STAGE(PG8_SA(0, 0), a2, voffA);
;             PG8_WAIT_V(8); PG8_WAIT_L(0); PG8_BAR; PG8_MMA(1, 0, At, B0); PG8_MMA(1, 1, At, B1); PG8_BAR; PG8_SCHED;
.LBB0_457:
	s_add_u32 s2, s44, 0x100
	s_addc_u32 s3, s45, 0
	s_add_i32 s6, 0, 0x10000
	s_cmp_eq_u32 s60, 4
	s_cselect_b32 s47, s39, s3
	s_cselect_b32 s46, s38, s2
	s_cselect_b32 s5, s29, s59
	s_cselect_b32 s4, s57, s58
	s_add_i32 s12, 0, 0x14000
	v_add_u32_e32 v156, s6, v142
	v_add_u32_e32 v172, s12, v142
	ds_read_b128 v[144:147], v156
	ds_read_b128 v[148:151], v156 offset:1024
	ds_read_b128 v[152:155], v156 offset:2048
	ds_read_b128 v[156:159], v156 offset:3072
	ds_read_b128 v[160:163], v172
	ds_read_b128 v[164:167], v172 offset:1024
	ds_read_b128 v[168:171], v172 offset:2048
	ds_read_b128 v[172:175], v172 offset:3072
	v_lshl_add_u64 v[208:209], s[44:45], 0, v[136:137]
	s_add_i32 m0, s26, 0xc000
	ds_read_b128 v[176:179], v143
	ds_read_b128 v[180:183], v143 offset:1024
	ds_read_b128 v[184:187], v143 offset:2048
	ds_read_b128 v[188:191], v143 offset:3072
	ds_read_b128 v[192:195], v143 offset:4096
	ds_read_b128 v[196:199], v143 offset:5120
	ds_read_b128 v[200:203], v143 offset:6144
	ds_read_b128 v[204:207], v143 offset:7168
	global_load_lds_dwordx4 v[208:209], off
	v_lshl_add_u64 v[208:209], s[44:45], 0, v[138:139]
	s_add_i32 m0, s26, 0xe000
	s_nop 0
	global_load_lds_dwordx4 v[208:209], off
	s_waitcnt vmcnt(8)
	s_waitcnt lgkmcnt(0)
	s_barrier
	s_setprio 1
	s_waitcnt lgkmcnt(0)
	v_mfma_f32_16x16x32_bf16 v[126:129], v[144:147], v[176:179], v[126:129]
	v_mfma_f32_16x16x32_bf16 v[122:125], v[152:155], v[176:179], v[122:125]
	v_mfma_f32_16x16x32_bf16 v[118:121], v[144:147], v[184:187], v[118:121]
	v_mfma_f32_16x16x32_bf16 v[114:117], v[152:155], v[184:187], v[114:117]
	v_mfma_f32_16x16x32_bf16 v[106:109], v[144:147], v[192:195], v[106:109]
	v_mfma_f32_16x16x32_bf16 v[98:101], v[152:155], v[192:195], v[98:101]
	v_mfma_f32_16x16x32_bf16 v[90:93], v[144:147], v[200:203], v[90:93]
	v_mfma_f32_16x16x32_bf16 v[82:85], v[152:155], v[200:203], v[82:85]
	v_mfma_f32_16x16x32_bf16 v[126:129], v[148:151], v[180:183], v[126:129]
	v_mfma_f32_16x16x32_bf16 v[122:125], v[156:159], v[180:183], v[122:125]
	v_mfma_f32_16x16x32_bf16 v[118:121], v[148:151], v[188:191], v[118:121]
	v_mfma_f32_16x16x32_bf16 v[114:117], v[156:159], v[188:191], v[114:117]
	v_mfma_f32_16x16x32_bf16 v[106:109], v[148:151], v[196:199], v[106:109]
	v_mfma_f32_16x16x32_bf16 v[98:101], v[156:159], v[196:199], v[98:101]
	v_mfma_f32_16x16x32_bf16 v[90:93], v[148:151], v[204:207], v[90:93]
	v_mfma_f32_16x16x32_bf16 v[82:85], v[156:159], v[204:207], v[82:85]
	s_setprio 0
	s_setprio 1
	v_mfma_f32_16x16x32_bf16 v[110:113], v[160:163], v[176:179], v[110:113]
	v_mfma_f32_16x16x32_bf16 v[102:105], v[168:171], v[176:179], v[102:105]
	v_mfma_f32_16x16x32_bf16 v[94:97], v[160:163], v[184:187], v[94:97]
	v_mfma_f32_16x16x32_bf16 v[86:89], v[168:171], v[184:187], v[86:89]
	v_mfma_f32_16x16x32_bf16 v[78:81], v[160:163], v[192:195], v[78:81]
	v_mfma_f32_16x16x32_bf16 v[74:77], v[168:171], v[192:195], v[74:77]
	v_mfma_f32_16x16x32_bf16 v[70:73], v[160:163], v[200:203], v[70:73]
	v_mfma_f32_16x16x32_bf16 v[66:69], v[168:171], v[200:203], v[66:69]
	v_mfma_f32_16x16x32_bf16 v[110:113], v[164:167], v[180:183], v[110:113]
	v_mfma_f32_16x16x32_bf16 v[102:105], v[172:175], v[180:183], v[102:105]
	v_mfma_f32_16x16x32_bf16 v[94:97], v[164:167], v[188:191], v[94:97]
	v_mfma_f32_16x16x32_bf16 v[86:89], v[172:175], v[188:191], v[86:89]
	v_mfma_f32_16x16x32_bf16 v[78:81], v[164:167], v[196:199], v[78:81]
	s_setprio 2
	s_barrier
	v_mfma_f32_16x16x32_bf16 v[74:77], v[172:175], v[196:199], v[74:77]
	v_mfma_f32_16x16x32_bf16 v[70:73], v[164:167], v[204:207], v[70:73]
	v_mfma_f32_16x16x32_bf16 v[66:69], v[172:175], v[204:207], v[66:69]
	s_setprio 0
	s_add_i32 s6, s6, s25
	v_lshl_add_u64 v[208:209], s[4:5], 0, v[0:1]
	s_mov_b32 m0, s6
	ds_read_b128 v[176:179], v143 offset:16384
	ds_read_b128 v[180:183], v143 offset:17408
	ds_read_b128 v[184:187], v143 offset:18432
	ds_read_b128 v[188:191], v143 offset:19456
	ds_read_b128 v[192:195], v143 offset:20480
	ds_read_b128 v[196:199], v143 offset:21504
	ds_read_b128 v[200:203], v143 offset:22528
	ds_read_b128 v[204:207], v143 offset:23552
	global_load_lds_dwordx4 v[208:209], off
	s_add_i32 m0, s6, 0x2000
	s_add_u32 s14, s4, 0x20000
	v_lshl_add_u64 v[210:211], s[4:5], 0, v[130:131]
	s_addc_u32 s15, s5, 0
	s_add_i32 s6, s12, s25
	global_load_lds_dwordx4 v[210:211], off
	v_lshl_add_u64 v[212:213], s[14:15], 0, v[0:1]
	s_mov_b32 m0, s6
	v_lshl_add_u64 v[214:215], s[46:47], 0, v[132:133]
	global_load_lds_dwordx4 v[212:213], off
	v_lshl_add_u64 v[212:213], s[14:15], 0, v[130:131]
	s_add_i32 m0, s6, 0x2000
	s_nop 0
	global_load_lds_dwordx4 v[212:213], off
	v_lshl_add_u64 v[212:213], s[46:47], 0, v[134:135]
	s_mov_b32 m0, s26
	s_nop 0
	global_load_lds_dwordx4 v[212:213], off
	s_mov_b32 m0, s48
	s_nop 0
	global_load_lds_dwordx4 v[214:215], off
	s_waitcnt vmcnt(8)
	s_waitcnt lgkmcnt(0)
	s_barrier
; #define PG8_STAGE(bufoff, gbase, voff) do { _Pragma("unroll") for (int _i = 0; _i < 2; ++_i) \
;         __builtin_amdgcn_global_load_lds((const unsigned*)((const char*)(gbase) + (voff)[_i]), (LAS unsigned*)(lds + (bufoff) + ldsw + _i * 8192), 16, 0, 0); } while (0)
; #define PG8_LDA(dst, b, h) do { _Pragma("unroll") for (int m = 0; m < 4; ++m) _Pragma("unroll") for (int k = 0; k < 2; ++k) dst[m][k] = *(const LAS bf16x8*)(lds + PG8_SA(b, h) + aoff + m * 2048 + k * 1024); } while (0)
; #define PG8_LDB(dst, b, h) do { _Pragma("unroll") for (int n = 0; n < 2; ++n) _Pragma("unroll") for (int k = 0; k < 2; ++k) dst[n][k] = *(const LAS bf16x8*)(lds + PG8_SB(b, h) + boff + n * 2048 + k * 1024); } while (0)
; #define PG8_MMA(ai, bj, At, Bt) do { __builtin_amdgcn_s_setprio(1); _Pragma("unroll") for (int m = 0; m < 4; ++m) _Pragma("unroll") for (int n = 0; n < 2; ++n) _Pragma("unroll") for (int k = 0; k < 2; ++k) \
;         acc[ai][bj][m][n] = __builtin_amdgcn_mfma_f32_16x16x32_bf16(Bt[n][k], At[m][k], acc[ai][bj][m][n], 0, 0, 0); __builtin_amdgcn_s_setprio(0); } while (0)
; #define PG8_WAIT_V(n) asm volatile("s_waitcnt vmcnt(" #n ")" ::: "memory")
; #define PG8_WAIT_L(n) asm volatile("s_waitcnt lgkmcnt(" #n ")" ::: "memory")
; #define PG8_BAR __builtin_amdgcn_s_barrier()
; #define PG8_SCHED __builtin_amdgcn_sched_barrier(0)
; template <class Epi>
; __device__ __forceinline__ void gemm_phase(LAS unsigned char* lds, const Gemm g, const TileOrder& S, const Epi& E) {
;     ...
;             PG8_WAIT_V(8); PG8_WAIT_L(0); PG8_BAR; PG8_MMA(1, 0, At, B0); PG8_MMA(1, 1, At, B1); PG8_BAR; PG8_SCHED;
;             PG8_LDB(B0, 1, 0); PG8_LDB(B1, 1, 1); PG8_SCHED; PG8_LDA(At, 1, 0); PG8_STAGE(PG8_SA(0, 1), a2 + hstepA, voffA);
;             PG8_WAIT_V(8); PG8_WAIT_L(0); PG8_BAR; PG8_MMA(0, 0, At, B0); PG8_MMA(0, 1, At, B1); PG8_BAR; PG8_SCHED;
	s_setprio 1
	s_waitcnt lgkmcnt(0)
	v_mfma_f32_16x16x32_bf16 v[62:65], v[144:147], v[176:179], v[62:65]
	v_mfma_f32_16x16x32_bf16 v[58:61], v[152:155], v[176:179], v[58:61]
	v_mfma_f32_16x16x32_bf16 v[54:57], v[144:147], v[184:187], v[54:57]
	v_mfma_f32_16x16x32_bf16 v[50:53], v[152:155], v[184:187], v[50:53]
	v_mfma_f32_16x16x32_bf16 v[38:41], v[144:147], v[192:195], v[38:41]
	v_mfma_f32_16x16x32_bf16 v[34:37], v[152:155], v[192:195], v[34:37]
	v_mfma_f32_16x16x32_bf16 v[22:25], v[144:147], v[200:203], v[22:25]
	v_mfma_f32_16x16x32_bf16 v[18:21], v[152:155], v[200:203], v[18:21]
	v_mfma_f32_16x16x32_bf16 v[62:65], v[148:151], v[180:183], v[62:65]
	v_mfma_f32_16x16x32_bf16 v[58:61], v[156:159], v[180:183], v[58:61]
	v_mfma_f32_16x16x32_bf16 v[54:57], v[148:151], v[188:191], v[54:57]
	v_mfma_f32_16x16x32_bf16 v[50:53], v[156:159], v[188:191], v[50:53]
	v_mfma_f32_16x16x32_bf16 v[38:41], v[148:151], v[196:199], v[38:41]
	v_mfma_f32_16x16x32_bf16 v[34:37], v[156:159], v[196:199], v[34:37]
	v_mfma_f32_16x16x32_bf16 v[22:25], v[148:151], v[204:207], v[22:25]
	v_mfma_f32_16x16x32_bf16 v[18:21], v[156:159], v[204:207], v[18:21]
	s_setprio 0
	s_setprio 1
	v_mfma_f32_16x16x32_bf16 v[46:49], v[160:163], v[176:179], v[46:49]
	v_mfma_f32_16x16x32_bf16 v[42:45], v[168:171], v[176:179], v[42:45]
	v_mfma_f32_16x16x32_bf16 v[30:33], v[160:163], v[184:187], v[30:33]
	v_mfma_f32_16x16x32_bf16 v[26:29], v[168:171], v[184:187], v[26:29]
	v_mfma_f32_16x16x32_bf16 v[14:17], v[160:163], v[192:195], v[14:17]
	v_mfma_f32_16x16x32_bf16 v[10:13], v[168:171], v[192:195], v[10:13]
	v_mfma_f32_16x16x32_bf16 v[6:9], v[160:163], v[200:203], v[6:9]
	v_mfma_f32_16x16x32_bf16 v[2:5], v[168:171], v[200:203], v[2:5]
	v_mfma_f32_16x16x32_bf16 v[46:49], v[164:167], v[180:183], v[46:49]
	v_mfma_f32_16x16x32_bf16 v[42:45], v[172:175], v[180:183], v[42:45]
	v_mfma_f32_16x16x32_bf16 v[30:33], v[164:167], v[188:191], v[30:33]
	v_mfma_f32_16x16x32_bf16 v[26:29], v[172:175], v[188:191], v[26:29]
	v_mfma_f32_16x16x32_bf16 v[14:17], v[164:167], v[196:199], v[14:17]
	s_setprio 2
	s_barrier
	v_mfma_f32_16x16x32_bf16 v[10:13], v[172:175], v[196:199], v[10:13]
	v_mfma_f32_16x16x32_bf16 v[6:9], v[164:167], v[204:207], v[6:9]
	v_mfma_f32_16x16x32_bf16 v[2:5], v[172:175], v[204:207], v[2:5]
	s_setprio 0
	s_add_i32 s6, 0, 0x18000
	s_add_i32 s12, 0, 0x1c000
	v_add_u32_e32 v156, s6, v142
	v_add_u32_e32 v172, s12, v142
	ds_read_b128 v[144:147], v156
	ds_read_b128 v[148:151], v156 offset:1024
	ds_read_b128 v[152:155], v156 offset:2048
	ds_read_b128 v[156:159], v156 offset:3072
	ds_read_b128 v[160:163], v172
	ds_read_b128 v[164:167], v172 offset:1024
	ds_read_b128 v[168:171], v172 offset:2048
	ds_read_b128 v[172:175], v172 offset:3072
	s_add_u32 s14, s46, 0x30000
	s_addc_u32 s15, s47, 0
	s_mov_b32 m0, s49
	v_lshl_add_u64 v[216:217], s[14:15], 0, v[134:135]
	ds_read_b128 v[176:179], v143 offset:32768
	ds_read_b128 v[180:183], v143 offset:33792
	ds_read_b128 v[184:187], v143 offset:34816
	ds_read_b128 v[188:191], v143 offset:35840
	ds_read_b128 v[192:195], v143 offset:36864
	ds_read_b128 v[196:199], v143 offset:37888
	ds_read_b128 v[200:203], v143 offset:38912
	ds_read_b128 v[204:207], v143 offset:39936
	global_load_lds_dwordx4 v[216:217], off
	v_lshl_add_u64 v[216:217], s[14:15], 0, v[132:133]
	s_mov_b32 m0, s50
	s_nop 0
	global_load_lds_dwordx4 v[216:217], off
	s_waitcnt vmcnt(8)
	s_waitcnt lgkmcnt(0)
	s_barrier
	s_setprio 1
	s_waitcnt lgkmcnt(0)
	v_mfma_f32_16x16x32_bf16 v[126:129], v[144:147], v[176:179], v[126:129]
	v_mfma_f32_16x16x32_bf16 v[122:125], v[152:155], v[176:179], v[122:125]
	v_mfma_f32_16x16x32_bf16 v[118:121], v[144:147], v[184:187], v[118:121]
	v_mfma_f32_16x16x32_bf16 v[114:117], v[152:155], v[184:187], v[114:117]
	v_mfma_f32_16x16x32_bf16 v[106:109], v[144:147], v[192:195], v[106:109]
	v_mfma_f32_16x16x32_bf16 v[98:101], v[152:155], v[192:195], v[98:101]
	v_mfma_f32_16x16x32_bf16 v[90:93], v[144:147], v[200:203], v[90:93]
	v_mfma_f32_16x16x32_bf16 v[82:85], v[152:155], v[200:203], v[82:85]
	v_mfma_f32_16x16x32_bf16 v[126:129], v[148:151], v[180:183], v[126:129]
	v_mfma_f32_16x16x32_bf16 v[122:125], v[156:159], v[180:183], v[122:125]
	v_mfma_f32_16x16x32_bf16 v[118:121], v[148:151], v[188:191], v[118:121]
	v_mfma_f32_16x16x32_bf16 v[114:117], v[156:159], v[188:191], v[114:117]
	v_mfma_f32_16x16x32_bf16 v[106:109], v[148:151], v[196:199], v[106:109]
	v_mfma_f32_16x16x32_bf16 v[98:101], v[156:159], v[196:199], v[98:101]
	v_mfma_f32_16x16x32_bf16 v[90:93], v[148:151], v[204:207], v[90:93]
	v_mfma_f32_16x16x32_bf16 v[82:85], v[156:159], v[204:207], v[82:85]
	s_setprio 0
	s_setprio 1
	v_mfma_f32_16x16x32_bf16 v[110:113], v[160:163], v[176:179], v[110:113]
	v_mfma_f32_16x16x32_bf16 v[102:105], v[168:171], v[176:179], v[102:105]
	v_mfma_f32_16x16x32_bf16 v[94:97], v[160:163], v[184:187], v[94:97]
	v_mfma_f32_16x16x32_bf16 v[86:89], v[168:171], v[184:187], v[86:89]
	v_mfma_f32_16x16x32_bf16 v[78:81], v[160:163], v[192:195], v[78:81]
	v_mfma_f32_16x16x32_bf16 v[74:77], v[168:171], v[192:195], v[74:77]
	v_mfma_f32_16x16x32_bf16 v[70:73], v[160:163], v[200:203], v[70:73]
	v_mfma_f32_16x16x32_bf16 v[66:69], v[168:171], v[200:203], v[66:69]
	v_mfma_f32_16x16x32_bf16 v[110:113], v[164:167], v[180:183], v[110:113]
	v_mfma_f32_16x16x32_bf16 v[102:105], v[172:175], v[180:183], v[102:105]
	v_mfma_f32_16x16x32_bf16 v[94:97], v[164:167], v[188:191], v[94:97]
	v_mfma_f32_16x16x32_bf16 v[86:89], v[172:175], v[188:191], v[86:89]
	v_mfma_f32_16x16x32_bf16 v[78:81], v[164:167], v[196:199], v[78:81]
	s_setprio 2
	s_barrier
; #define PG8_STAGE(bufoff, gbase, voff) do { _Pragma("unroll") for (int _i = 0; _i < 2; ++_i) \
;         __builtin_amdgcn_global_load_lds((const unsigned*)((const char*)(gbase) + (voff)[_i]), (LAS unsigned*)(lds + (bufoff) + ldsw + _i * 8192), 16, 0, 0); } while (0)
; #define PG8_LDA(dst, b, h) do { _Pragma("unroll") for (int m = 0; m < 4; ++m) _Pragma("unroll") for (int k = 0; k < 2; ++k) dst[m][k] = *(const LAS bf16x8*)(lds + PG8_SA(b, h) + aoff + m * 2048 + k * 1024); } while (0)
; #define PG8_MMA(ai, bj, At, Bt) do { __builtin_amdgcn_s_setprio(1); _Pragma("unroll") for (int m = 0; m < 4; ++m) _Pragma("unroll") for (int n = 0; n < 2; ++n) _Pragma("unroll") for (int k = 0; k < 2; ++k) \
;         acc[ai][bj][m][n] = __builtin_amdgcn_mfma_f32_16x16x32_bf16(Bt[n][k], At[m][k], acc[ai][bj][m][n], 0, 0, 0); __builtin_amdgcn_s_setprio(0); } while (0)
; #define PG8_WAIT_V(n) asm volatile("s_waitcnt vmcnt(" #n ")" ::: "memory")
; #define PG8_WAIT_L(n) asm volatile("s_waitcnt lgkmcnt(" #n ")" ::: "memory")
; #define PG8_BAR __builtin_amdgcn_s_barrier()
; #define PG8_SCHED __builtin_amdgcn_sched_barrier(0)
; template <class Epi>
; __device__ __forceinline__ void gemm_phase(LAS unsigned char* lds, const Gemm g, const TileOrder& S, const Epi& E) {
;     ...
;             PG8_WAIT_V(8); PG8_WAIT_L(0); PG8_BAR; PG8_MMA(0, 0, At, B0); PG8_MMA(0, 1, At, B1); PG8_BAR; PG8_SCHED;
;             PG8_LDA(At, 1, 1); PG8_STAGE(PG8_SB(1, 0), b3, voffB); PG8_STAGE(PG8_SB(1, 1), b3 + hstepB, voffB); PG8_STAGE(PG8_SA(1, 0), a3, voffA);
;             PG8_WAIT_V(8); PG8_WAIT_L(0); PG8_BAR; PG8_MMA(1, 0, At, B0); PG8_MMA(1, 1, At, B1); PG8_BAR; PG8_SCHED;
;         }
;         if (wr == 0) PG8_BAR;
	v_mfma_f32_16x16x32_bf16 v[74:77], v[172:175], v[196:199], v[74:77]
	v_mfma_f32_16x16x32_bf16 v[70:73], v[164:167], v[204:207], v[70:73]
	v_mfma_f32_16x16x32_bf16 v[66:69], v[172:175], v[204:207], v[66:69]
	s_setprio 0
	s_add_i32 s6, s6, s25
	v_lshl_add_u64 v[208:209], v[208:209], 0, s[34:35]
	s_mov_b32 m0, s6
	ds_read_b128 v[176:179], v143 offset:49152
	ds_read_b128 v[180:183], v143 offset:50176
	ds_read_b128 v[184:187], v143 offset:51200
	ds_read_b128 v[188:191], v143 offset:52224
	ds_read_b128 v[192:195], v143 offset:53248
	ds_read_b128 v[196:199], v143 offset:54272
	ds_read_b128 v[200:203], v143 offset:55296
	ds_read_b128 v[204:207], v143 offset:56320
	global_load_lds_dwordx4 v[208:209], off
	s_add_i32 m0, s6, 0x2000
	s_add_u32 s4, s4, 0x20080
	v_lshl_add_u64 v[208:209], v[210:211], 0, s[34:35]
	s_addc_u32 s5, s5, 0
	s_add_i32 s6, s12, s25
	global_load_lds_dwordx4 v[208:209], off
	v_lshl_add_u64 v[208:209], s[4:5], 0, v[0:1]
	s_mov_b32 m0, s6
	s_nop 0
	global_load_lds_dwordx4 v[208:209], off
	v_lshl_add_u64 v[208:209], s[4:5], 0, v[130:131]
	s_add_i32 m0, s6, 0x2000
	s_nop 0
	global_load_lds_dwordx4 v[208:209], off
	v_lshl_add_u64 v[208:209], v[212:213], 0, s[34:35]
	s_mov_b32 m0, s51
	s_nop 0
	global_load_lds_dwordx4 v[208:209], off
	v_lshl_add_u64 v[208:209], v[214:215], 0, s[34:35]
	s_mov_b32 m0, s52
	s_nop 0
	global_load_lds_dwordx4 v[208:209], off
	s_waitcnt vmcnt(8)
	s_waitcnt lgkmcnt(0)
	s_barrier
	s_setprio 1
	s_waitcnt lgkmcnt(0)
	v_mfma_f32_16x16x32_bf16 v[62:65], v[144:147], v[176:179], v[62:65]
	v_mfma_f32_16x16x32_bf16 v[58:61], v[152:155], v[176:179], v[58:61]
	v_mfma_f32_16x16x32_bf16 v[54:57], v[144:147], v[184:187], v[54:57]
	v_mfma_f32_16x16x32_bf16 v[50:53], v[152:155], v[184:187], v[50:53]
	v_mfma_f32_16x16x32_bf16 v[38:41], v[144:147], v[192:195], v[38:41]
	v_mfma_f32_16x16x32_bf16 v[34:37], v[152:155], v[192:195], v[34:37]
	v_mfma_f32_16x16x32_bf16 v[22:25], v[144:147], v[200:203], v[22:25]
	v_mfma_f32_16x16x32_bf16 v[18:21], v[152:155], v[200:203], v[18:21]
	v_mfma_f32_16x16x32_bf16 v[62:65], v[148:151], v[180:183], v[62:65]
	v_mfma_f32_16x16x32_bf16 v[58:61], v[156:159], v[180:183], v[58:61]
	v_mfma_f32_16x16x32_bf16 v[54:57], v[148:151], v[188:191], v[54:57]
	v_mfma_f32_16x16x32_bf16 v[50:53], v[156:159], v[188:191], v[50:53]
	v_mfma_f32_16x16x32_bf16 v[38:41], v[148:151], v[196:199], v[38:41]
	v_mfma_f32_16x16x32_bf16 v[34:37], v[156:159], v[196:199], v[34:37]
	v_mfma_f32_16x16x32_bf16 v[22:25], v[148:151], v[204:207], v[22:25]
	v_mfma_f32_16x16x32_bf16 v[18:21], v[156:159], v[204:207], v[18:21]
	s_setprio 0
	s_setprio 1
	v_mfma_f32_16x16x32_bf16 v[46:49], v[160:163], v[176:179], v[46:49]
	v_mfma_f32_16x16x32_bf16 v[42:45], v[168:171], v[176:179], v[42:45]
	v_mfma_f32_16x16x32_bf16 v[30:33], v[160:163], v[184:187], v[30:33]
	v_mfma_f32_16x16x32_bf16 v[26:29], v[168:171], v[184:187], v[26:29]
	v_mfma_f32_16x16x32_bf16 v[14:17], v[160:163], v[192:195], v[14:17]
	v_mfma_f32_16x16x32_bf16 v[10:13], v[168:171], v[192:195], v[10:13]
	v_mfma_f32_16x16x32_bf16 v[6:9], v[160:163], v[200:203], v[6:9]
	v_mfma_f32_16x16x32_bf16 v[2:5], v[168:171], v[200:203], v[2:5]
	v_mfma_f32_16x16x32_bf16 v[46:49], v[164:167], v[180:183], v[46:49]
	v_mfma_f32_16x16x32_bf16 v[42:45], v[172:175], v[180:183], v[42:45]
	v_mfma_f32_16x16x32_bf16 v[30:33], v[164:167], v[188:191], v[30:33]
	v_mfma_f32_16x16x32_bf16 v[26:29], v[172:175], v[188:191], v[26:29]
	v_mfma_f32_16x16x32_bf16 v[14:17], v[164:167], v[196:199], v[14:17]
	s_setprio 2
	s_barrier
	v_mfma_f32_16x16x32_bf16 v[10:13], v[172:175], v[196:199], v[10:13]
	v_mfma_f32_16x16x32_bf16 v[6:9], v[164:167], v[204:207], v[6:9]
	v_mfma_f32_16x16x32_bf16 v[2:5], v[172:175], v[204:207], v[2:5]
	s_setprio 0
	s_add_i32 s60, s60, 2
	s_add_u32 s58, s58, 0x100
	s_addc_u32 s59, s59, 0
	s_cmp_gt_u32 s60, 5
	s_mov_b64 s[44:45], s[2:3]
	s_cbranch_scc0 .LBB0_457
	s_and_b64 vcc, exec, s[36:37]
	s_cbranch_vccz .LBB0_460
	s_barrier

; #define PG8_STAGE(bufoff, gbase, voff) do { _Pragma("unroll") for (int _i = 0; _i < 2; ++_i) \
;         __builtin_amdgcn_global_load_lds((const unsigned*)((const char*)(gbase) + (voff)[_i]), (LAS unsigned*)(lds + (bufoff) + ldsw + _i * 8192), 16, 0, 0); } while (0)
; #define PG8_LDA(dst, b, h) do { _Pragma("unroll") for (int m = 0; m < 4; ++m) _Pragma("unroll") for (int k = 0; k < 2; ++k) dst[m][k] = *(const LAS bf16x8*)(lds + PG8_SA(b, h) + aoff + m * 2048 + k * 1024); } while (0)
; #define PG8_LDB(dst, b, h) do { _Pragma("unroll") for (int n = 0; n < 2; ++n) _Pragma("unroll") for (int k = 0; k < 2; ++k) dst[n][k] = *(const LAS bf16x8*)(lds + PG8_SB(b, h) + boff + n * 2048 + k * 1024); } while (0)
; #define PG8_MMA(ai, bj, At, Bt) do { __builtin_amdgcn_s_setprio(1); _Pragma("unroll") for (int m = 0; m < 4; ++m) _Pragma("unroll") for (int n = 0; n < 2; ++n) _Pragma("unroll") for (int k = 0; k < 2; ++k) \
;         acc[ai][bj][m][n] = __builtin_amdgcn_mfma_f32_16x16x32_bf16(Bt[n][k], At[m][k], acc[ai][bj][m][n], 0, 0, 0); __builtin_amdgcn_s_setprio(0); } while (0)
; #define PG8_WAIT_V(n) asm volatile("s_waitcnt vmcnt(" #n ")" ::: "memory")
; #define PG8_WAIT_L(n) asm volatile("s_waitcnt lgkmcnt(" #n ")" ::: "memory")
; #define PG8_BAR __builtin_amdgcn_s_barrier()
; #define PG8_SCHED __builtin_amdgcn_sched_barrier(0)
; template <class Epi>
; __device__ __forceinline__ void gemm_phase(LAS unsigned char* lds, const Gemm g, const TileOrder& S, const Epi& E) {
;     ...
;             const bool last = (t == nt - 2);
;             const char* a1 = cA + (size_t)(t + 1) * kstepA;
;             const char* a2 = last ? nA : cA + (size_t)(t + 2) * kstepA; const char* b2 = last ? nB : cB + (size_t)(t + 2) * kstep;
;             const char* a3 = a2 + kstepA; const char* b3 = b2 + kstep;
;             PG8_LDB(B0, 0, 0); PG8_LDB(B1, 0, 1); PG8_SCHED; PG8_LDA(At, 0, 0); PG8_STAGE(PG8_SA(1, 1), a1 + hstepA, voffA);
;             PG8_WAIT_V(8); PG8_WAIT_L(0); PG8_BAR; PG8_MMA(0, 0, At, B0); PG8_MMA(0, 1, At, B1); PG8_BAR; PG8_SCHED;
;             PG8_LDA(At, 0, 1); PG8_STAGE(PG8_SB(0, 0), b2, voffB); PG8_STAGE(PG8_SB(0, 1), b2 + hstepB, voffB); PG8_STAGE(PG8_SA(0, 0), a2, voffA);
;             PG8_WAIT_V(8); PG8_WAIT_L(0); PG8_BAR; PG8_MMA(1, 0, At, B0); PG8_MMA(1, 1, At, B1); PG8_BAR; PG8_SCHED;
.LBB0_596:
	s_add_u32 s2, s28, 0x100
	s_addc_u32 s3, s29, 0
	s_add_i32 s6, 0, 0x10000
	s_cmp_eq_u32 s62, 8
	s_cselect_b32 s47, s1, s3
	s_cselect_b32 s46, s0, s2
	s_cselect_b32 s31, s45, s61
	s_cselect_b32 s30, s44, s60
	s_add_i32 s12, 0, 0x14000
	v_add_u32_e32 v58, s6, v224
	v_add_u32_e32 v102, s12, v224
	ds_read_b128 v[42:45], v58
	ds_read_b128 v[46:49], v58 offset:1024
	ds_read_b128 v[50:53], v58 offset:2048
	ds_read_b128 v[58:61], v58 offset:3072
	ds_read_b128 v[74:77], v102
	ds_read_b128 v[82:85], v102 offset:1024
	ds_read_b128 v[94:97], v102 offset:2048
	ds_read_b128 v[102:105], v102 offset:3072
	v_lshl_add_u64 v[194:195], s[28:29], 0, v[214:215]
	s_add_i32 m0, s26, 0xc000
	ds_read_b128 v[114:117], v225
	ds_read_b128 v[126:129], v225 offset:1024
	ds_read_b128 v[138:141], v225 offset:2048
	ds_read_b128 v[150:153], v225 offset:3072
	ds_read_b128 v[162:165], v225 offset:4096
	ds_read_b128 v[174:177], v225 offset:5120
	ds_read_b128 v[186:189], v225 offset:6144
	ds_read_b128 v[190:193], v225 offset:7168
	global_load_lds_dwordx4 v[194:195], off
	v_lshl_add_u64 v[194:195], s[28:29], 0, v[216:217]
	s_add_i32 m0, s26, 0xe000
	s_nop 0
	global_load_lds_dwordx4 v[194:195], off
	s_waitcnt vmcnt(8)
	s_waitcnt lgkmcnt(0)
	s_barrier
	s_setprio 1
	s_waitcnt lgkmcnt(0)
	v_mfma_f32_16x16x32_bf16 v[182:185], v[42:45], v[114:117], v[182:185]
	v_mfma_f32_16x16x32_bf16 v[178:181], v[50:53], v[114:117], v[178:181]
	v_mfma_f32_16x16x32_bf16 v[158:161], v[42:45], v[138:141], v[158:161]
	v_mfma_f32_16x16x32_bf16 v[154:157], v[50:53], v[138:141], v[154:157]
	v_mfma_f32_16x16x32_bf16 v[134:137], v[42:45], v[162:165], v[134:137]
	v_mfma_f32_16x16x32_bf16 v[130:133], v[50:53], v[162:165], v[130:133]
	v_mfma_f32_16x16x32_bf16 v[110:113], v[42:45], v[186:189], v[110:113]
	v_mfma_f32_16x16x32_bf16 v[106:109], v[50:53], v[186:189], v[106:109]
	v_mfma_f32_16x16x32_bf16 v[182:185], v[46:49], v[126:129], v[182:185]
	v_mfma_f32_16x16x32_bf16 v[178:181], v[58:61], v[126:129], v[178:181]
	v_mfma_f32_16x16x32_bf16 v[158:161], v[46:49], v[150:153], v[158:161]
	v_mfma_f32_16x16x32_bf16 v[154:157], v[58:61], v[150:153], v[154:157]
	v_mfma_f32_16x16x32_bf16 v[134:137], v[46:49], v[174:177], v[134:137]
	v_mfma_f32_16x16x32_bf16 v[130:133], v[58:61], v[174:177], v[130:133]
	v_mfma_f32_16x16x32_bf16 v[110:113], v[46:49], v[190:193], v[110:113]
	v_mfma_f32_16x16x32_bf16 v[106:109], v[58:61], v[190:193], v[106:109]
	s_setprio 0
	s_setprio 1
	v_mfma_f32_16x16x32_bf16 v[170:173], v[74:77], v[114:117], v[170:173]
	v_mfma_f32_16x16x32_bf16 v[114:117], v[94:97], v[114:117], v[166:169]
	v_mfma_f32_16x16x32_bf16 v[122:125], v[74:77], v[162:165], v[122:125]
	v_mfma_f32_16x16x32_bf16 v[118:121], v[94:97], v[162:165], v[118:121]
	v_mfma_f32_16x16x32_bf16 v[98:101], v[74:77], v[186:189], v[98:101]
	v_mfma_f32_16x16x32_bf16 v[90:93], v[94:97], v[186:189], v[90:93]
	v_mfma_f32_16x16x32_bf16 v[170:173], v[82:85], v[126:129], v[170:173]
	v_mfma_f32_16x16x32_bf16 v[114:117], v[102:105], v[126:129], v[114:117]
	v_mfma_f32_16x16x32_bf16 v[126:129], v[74:77], v[138:141], v[146:149]
	v_mfma_f32_16x16x32_bf16 v[138:141], v[94:97], v[138:141], v[142:145]
	v_mfma_f32_16x16x32_bf16 v[122:125], v[82:85], v[174:177], v[122:125]
	v_mfma_f32_16x16x32_bf16 v[118:121], v[102:105], v[174:177], v[118:121]
	v_mfma_f32_16x16x32_bf16 v[98:101], v[82:85], v[190:193], v[98:101]
	s_setprio 2
	s_barrier
	v_mfma_f32_16x16x32_bf16 v[90:93], v[102:105], v[190:193], v[90:93]
	v_mfma_f32_16x16x32_bf16 v[126:129], v[82:85], v[150:153], v[126:129]
	v_mfma_f32_16x16x32_bf16 v[138:141], v[102:105], v[150:153], v[138:141]
	s_setprio 0
	s_add_i32 s6, s6, s25
	v_lshl_add_u64 v[198:199], s[30:31], 0, v[0:1]
	s_mov_b32 m0, s6
	ds_read_b128 v[142:145], v225 offset:16384
	ds_read_b128 v[146:149], v225 offset:17408
	ds_read_b128 v[150:153], v225 offset:18432
	ds_read_b128 v[162:165], v225 offset:19456
	ds_read_b128 v[166:169], v225 offset:20480
	ds_read_b128 v[174:177], v225 offset:21504
	ds_read_b128 v[186:189], v225 offset:22528
	ds_read_b128 v[190:193], v225 offset:23552
	global_load_lds_dwordx4 v[198:199], off
	s_add_i32 m0, s6, 0x2000
	s_add_u32 s14, s30, 0x30000
	v_lshl_add_u64 v[200:201], s[30:31], 0, v[208:209]
	s_addc_u32 s15, s31, 0
	s_add_i32 s6, s12, s25
	global_load_lds_dwordx4 v[200:201], off
	v_lshl_add_u64 v[194:195], s[14:15], 0, v[0:1]
	s_mov_b32 m0, s6
	v_lshl_add_u64 v[202:203], s[46:47], 0, v[212:213]
	global_load_lds_dwordx4 v[194:195], off
	v_lshl_add_u64 v[194:195], s[14:15], 0, v[208:209]
	s_add_i32 m0, s6, 0x2000
	v_lshl_add_u64 v[204:205], s[46:47], 0, v[210:211]
	global_load_lds_dwordx4 v[194:195], off
	s_mov_b32 m0, s26
	s_nop 0
	global_load_lds_dwordx4 v[202:203], off
	s_mov_b32 m0, s48
	s_nop 0
	global_load_lds_dwordx4 v[204:205], off
	s_waitcnt vmcnt(8)
	s_waitcnt lgkmcnt(0)
	s_barrier
; #define PG8_STAGE(bufoff, gbase, voff) do { _Pragma("unroll") for (int _i = 0; _i < 2; ++_i) \
;         __builtin_amdgcn_global_load_lds((const unsigned*)((const char*)(gbase) + (voff)[_i]), (LAS unsigned*)(lds + (bufoff) + ldsw + _i * 8192), 16, 0, 0); } while (0)
; #define PG8_LDA(dst, b, h) do { _Pragma("unroll") for (int m = 0; m < 4; ++m) _Pragma("unroll") for (int k = 0; k < 2; ++k) dst[m][k] = *(const LAS bf16x8*)(lds + PG8_SA(b, h) + aoff + m * 2048 + k * 1024); } while (0)
; #define PG8_LDB(dst, b, h) do { _Pragma("unroll") for (int n = 0; n < 2; ++n) _Pragma("unroll") for (int k = 0; k < 2; ++k) dst[n][k] = *(const LAS bf16x8*)(lds + PG8_SB(b, h) + boff + n * 2048 + k * 1024); } while (0)
; #define PG8_MMA(ai, bj, At, Bt) do { __builtin_amdgcn_s_setprio(1); _Pragma("unroll") for (int m = 0; m < 4; ++m) _Pragma("unroll") for (int n = 0; n < 2; ++n) _Pragma("unroll") for (int k = 0; k < 2; ++k) \
;         acc[ai][bj][m][n] = __builtin_amdgcn_mfma_f32_16x16x32_bf16(Bt[n][k], At[m][k], acc[ai][bj][m][n], 0, 0, 0); __builtin_amdgcn_s_setprio(0); } while (0)
; #define PG8_WAIT_V(n) asm volatile("s_waitcnt vmcnt(" #n ")" ::: "memory")
; #define PG8_WAIT_L(n) asm volatile("s_waitcnt lgkmcnt(" #n ")" ::: "memory")
; #define PG8_BAR __builtin_amdgcn_s_barrier()
; #define PG8_SCHED __builtin_amdgcn_sched_barrier(0)
; template <class Epi>
; __device__ __forceinline__ void gemm_phase(LAS unsigned char* lds, const Gemm g, const TileOrder& S, const Epi& E) {
;     ...
;             PG8_WAIT_V(8); PG8_WAIT_L(0); PG8_BAR; PG8_MMA(1, 0, At, B0); PG8_MMA(1, 1, At, B1); PG8_BAR; PG8_SCHED;
;             PG8_LDB(B0, 1, 0); PG8_LDB(B1, 1, 1); PG8_SCHED; PG8_LDA(At, 1, 0); PG8_STAGE(PG8_SA(0, 1), a2 + hstepA, voffA);
;             PG8_WAIT_V(8); PG8_WAIT_L(0); PG8_BAR; PG8_MMA(0, 0, At, B0); PG8_MMA(0, 1, At, B1); PG8_BAR; PG8_SCHED;
	s_setprio 1
	s_waitcnt lgkmcnt(0)
	v_mfma_f32_16x16x32_bf16 v[86:89], v[42:45], v[142:145], v[86:89]
	v_mfma_f32_16x16x32_bf16 v[78:81], v[50:53], v[142:145], v[78:81]
	v_mfma_f32_16x16x32_bf16 v[62:65], v[42:45], v[150:153], v[62:65]
	v_mfma_f32_16x16x32_bf16 v[54:57], v[50:53], v[150:153], v[54:57]
	v_mfma_f32_16x16x32_bf16 v[30:33], v[42:45], v[166:169], v[30:33]
	v_mfma_f32_16x16x32_bf16 v[26:29], v[50:53], v[166:169], v[26:29]
	v_mfma_f32_16x16x32_bf16 v[14:17], v[42:45], v[186:189], v[14:17]
	v_mfma_f32_16x16x32_bf16 v[10:13], v[50:53], v[186:189], v[10:13]
	v_mfma_f32_16x16x32_bf16 v[86:89], v[46:49], v[146:149], v[86:89]
	v_mfma_f32_16x16x32_bf16 v[78:81], v[58:61], v[146:149], v[78:81]
	v_mfma_f32_16x16x32_bf16 v[62:65], v[46:49], v[162:165], v[62:65]
	v_mfma_f32_16x16x32_bf16 v[54:57], v[58:61], v[162:165], v[54:57]
	v_mfma_f32_16x16x32_bf16 v[30:33], v[46:49], v[174:177], v[30:33]
	v_mfma_f32_16x16x32_bf16 v[26:29], v[58:61], v[174:177], v[26:29]
	v_mfma_f32_16x16x32_bf16 v[14:17], v[46:49], v[190:193], v[14:17]
	v_mfma_f32_16x16x32_bf16 v[10:13], v[58:61], v[190:193], v[10:13]
	s_setprio 0
	s_setprio 1
	v_mfma_f32_16x16x32_bf16 v[38:41], v[74:77], v[150:153], v[38:41]
	v_mfma_f32_16x16x32_bf16 v[34:37], v[94:97], v[150:153], v[34:37]
	v_mfma_f32_16x16x32_bf16 v[22:25], v[74:77], v[166:169], v[22:25]
	v_mfma_f32_16x16x32_bf16 v[18:21], v[94:97], v[166:169], v[18:21]
	v_mfma_f32_16x16x32_bf16 v[6:9], v[74:77], v[186:189], v[6:9]
	v_mfma_f32_16x16x32_bf16 v[2:5], v[94:97], v[186:189], v[2:5]
	v_mfma_f32_16x16x32_bf16 v[42:45], v[74:77], v[142:145], v[70:73]
	v_mfma_f32_16x16x32_bf16 v[46:49], v[94:97], v[142:145], v[66:69]
	v_mfma_f32_16x16x32_bf16 v[38:41], v[82:85], v[162:165], v[38:41]
	v_mfma_f32_16x16x32_bf16 v[34:37], v[102:105], v[162:165], v[34:37]
	v_mfma_f32_16x16x32_bf16 v[22:25], v[82:85], v[174:177], v[22:25]
	v_mfma_f32_16x16x32_bf16 v[18:21], v[102:105], v[174:177], v[18:21]
	v_mfma_f32_16x16x32_bf16 v[6:9], v[82:85], v[190:193], v[6:9]
	s_setprio 2
	s_barrier
	v_mfma_f32_16x16x32_bf16 v[2:5], v[102:105], v[190:193], v[2:5]
	v_mfma_f32_16x16x32_bf16 v[42:45], v[82:85], v[146:149], v[42:45]
	v_mfma_f32_16x16x32_bf16 v[46:49], v[102:105], v[146:149], v[46:49]
	s_setprio 0
	s_add_i32 s6, 0, 0x18000
	s_add_i32 s12, 0, 0x1c000
	v_add_u32_e32 v70, s6, v224
	v_add_u32_e32 v102, s12, v224
	ds_read_b128 v[50:53], v70
	ds_read_b128 v[58:61], v70 offset:1024
	ds_read_b128 v[66:69], v70 offset:2048
	ds_read_b128 v[70:73], v70 offset:3072
	ds_read_b128 v[74:77], v102
	ds_read_b128 v[82:85], v102 offset:1024
	ds_read_b128 v[94:97], v102 offset:2048
	ds_read_b128 v[102:105], v102 offset:3072
	s_add_u32 s14, s46, 0x30000
	s_addc_u32 s15, s47, 0
	s_mov_b32 m0, s49
	v_lshl_add_u64 v[166:167], s[14:15], 0, v[212:213]
	ds_read_b128 v[142:145], v225 offset:32768
	ds_read_b128 v[146:149], v225 offset:33792
	ds_read_b128 v[150:153], v225 offset:34816
	ds_read_b128 v[162:165], v225 offset:35840
	ds_read_b128 v[174:177], v225 offset:36864
	ds_read_b128 v[186:189], v225 offset:37888
	ds_read_b128 v[190:193], v225 offset:38912
	ds_read_b128 v[194:197], v225 offset:39936
	global_load_lds_dwordx4 v[166:167], off
	v_lshl_add_u64 v[166:167], s[14:15], 0, v[210:211]
	s_mov_b32 m0, s50
	s_nop 0
	global_load_lds_dwordx4 v[166:167], off
	s_waitcnt vmcnt(8)
	s_waitcnt lgkmcnt(0)
	s_barrier
	s_setprio 1
	s_waitcnt lgkmcnt(0)
	v_mfma_f32_16x16x32_bf16 v[166:169], v[50:53], v[142:145], v[182:185]
	v_mfma_f32_16x16x32_bf16 v[182:185], v[58:61], v[146:149], v[166:169]
	v_mfma_f32_16x16x32_bf16 v[166:169], v[66:69], v[142:145], v[178:181]
	v_mfma_f32_16x16x32_bf16 v[158:161], v[50:53], v[150:153], v[158:161]
	v_mfma_f32_16x16x32_bf16 v[154:157], v[66:69], v[150:153], v[154:157]
	v_mfma_f32_16x16x32_bf16 v[134:137], v[50:53], v[174:177], v[134:137]
	v_mfma_f32_16x16x32_bf16 v[130:133], v[66:69], v[174:177], v[130:133]
	v_mfma_f32_16x16x32_bf16 v[110:113], v[50:53], v[190:193], v[110:113]
	v_mfma_f32_16x16x32_bf16 v[106:109], v[66:69], v[190:193], v[106:109]
	v_mfma_f32_16x16x32_bf16 v[178:181], v[70:73], v[146:149], v[166:169]
	v_mfma_f32_16x16x32_bf16 v[158:161], v[58:61], v[162:165], v[158:161]
	v_mfma_f32_16x16x32_bf16 v[154:157], v[70:73], v[162:165], v[154:157]
	v_mfma_f32_16x16x32_bf16 v[134:137], v[58:61], v[186:189], v[134:137]
	v_mfma_f32_16x16x32_bf16 v[130:133], v[70:73], v[186:189], v[130:133]
	v_mfma_f32_16x16x32_bf16 v[110:113], v[58:61], v[194:197], v[110:113]
	v_mfma_f32_16x16x32_bf16 v[106:109], v[70:73], v[194:197], v[106:109]
	s_setprio 0
	s_setprio 1
	v_mfma_f32_16x16x32_bf16 v[166:169], v[74:77], v[142:145], v[170:173]
	v_mfma_f32_16x16x32_bf16 v[114:117], v[94:97], v[142:145], v[114:117]
	v_mfma_f32_16x16x32_bf16 v[170:173], v[82:85], v[146:149], v[166:169]
	v_mfma_f32_16x16x32_bf16 v[166:169], v[102:105], v[146:149], v[114:117]
	v_mfma_f32_16x16x32_bf16 v[114:117], v[74:77], v[150:153], v[126:129]
	v_mfma_f32_16x16x32_bf16 v[146:149], v[82:85], v[162:165], v[114:117]
	v_mfma_f32_16x16x32_bf16 v[114:117], v[94:97], v[150:153], v[138:141]
	v_mfma_f32_16x16x32_bf16 v[142:145], v[102:105], v[162:165], v[114:117]
	v_mfma_f32_16x16x32_bf16 v[114:117], v[74:77], v[174:177], v[122:125]
	v_mfma_f32_16x16x32_bf16 v[122:125], v[82:85], v[186:189], v[114:117]
	v_mfma_f32_16x16x32_bf16 v[114:117], v[94:97], v[174:177], v[118:121]
	v_mfma_f32_16x16x32_bf16 v[98:101], v[74:77], v[190:193], v[98:101]
	v_mfma_f32_16x16x32_bf16 v[90:93], v[94:97], v[190:193], v[90:93]
	s_setprio 2
	s_barrier
; #define PG8_STAGE(bufoff, gbase, voff) do { _Pragma("unroll") for (int _i = 0; _i < 2; ++_i) \
;         __builtin_amdgcn_global_load_lds((const unsigned*)((const char*)(gbase) + (voff)[_i]), (LAS unsigned*)(lds + (bufoff) + ldsw + _i * 8192), 16, 0, 0); } while (0)
; #define PG8_LDA(dst, b, h) do { _Pragma("unroll") for (int m = 0; m < 4; ++m) _Pragma("unroll") for (int k = 0; k < 2; ++k) dst[m][k] = *(const LAS bf16x8*)(lds + PG8_SA(b, h) + aoff + m * 2048 + k * 1024); } while (0)
; #define PG8_MMA(ai, bj, At, Bt) do { __builtin_amdgcn_s_setprio(1); _Pragma("unroll") for (int m = 0; m < 4; ++m) _Pragma("unroll") for (int n = 0; n < 2; ++n) _Pragma("unroll") for (int k = 0; k < 2; ++k) \
;         acc[ai][bj][m][n] = __builtin_amdgcn_mfma_f32_16x16x32_bf16(Bt[n][k], At[m][k], acc[ai][bj][m][n], 0, 0, 0); __builtin_amdgcn_s_setprio(0); } while (0)
; #define PG8_WAIT_V(n) asm volatile("s_waitcnt vmcnt(" #n ")" ::: "memory")
; #define PG8_WAIT_L(n) asm volatile("s_waitcnt lgkmcnt(" #n ")" ::: "memory")
; #define PG8_BAR __builtin_amdgcn_s_barrier()
; #define PG8_SCHED __builtin_amdgcn_sched_barrier(0)
; template <class Epi>
; __device__ __forceinline__ void gemm_phase(LAS unsigned char* lds, const Gemm g, const TileOrder& S, const Epi& E) {
;     ...
;             PG8_WAIT_V(8); PG8_WAIT_L(0); PG8_BAR; PG8_MMA(0, 0, At, B0); PG8_MMA(0, 1, At, B1); PG8_BAR; PG8_SCHED;
;             PG8_LDA(At, 1, 1); PG8_STAGE(PG8_SB(1, 0), b3, voffB); PG8_STAGE(PG8_SB(1, 1), b3 + hstepB, voffB); PG8_STAGE(PG8_SA(1, 0), a3, voffA);
;             PG8_WAIT_V(8); PG8_WAIT_L(0); PG8_BAR; PG8_MMA(1, 0, At, B0); PG8_MMA(1, 1, At, B1); PG8_BAR; PG8_SCHED;
;         }
;         if (wr == 0) PG8_BAR;
	v_mfma_f32_16x16x32_bf16 v[118:121], v[102:105], v[186:189], v[114:117]
	v_mfma_f32_16x16x32_bf16 v[98:101], v[82:85], v[194:197], v[98:101]
	v_mfma_f32_16x16x32_bf16 v[90:93], v[102:105], v[194:197], v[90:93]
	s_setprio 0
	s_add_i32 s6, s6, s25
	v_lshl_add_u64 v[194:195], v[198:199], 0, s[34:35]
	s_mov_b32 m0, s6
	ds_read_b128 v[114:117], v225 offset:49152
	ds_read_b128 v[126:129], v225 offset:50176
	ds_read_b128 v[138:141], v225 offset:51200
	ds_read_b128 v[150:153], v225 offset:52224
	ds_read_b128 v[162:165], v225 offset:53248
	ds_read_b128 v[174:177], v225 offset:54272
	ds_read_b128 v[186:189], v225 offset:55296
	ds_read_b128 v[190:193], v225 offset:56320
	global_load_lds_dwordx4 v[194:195], off
	s_add_i32 m0, s6, 0x2000
	s_add_u32 s14, s30, 0x30080
	v_lshl_add_u64 v[194:195], v[200:201], 0, s[34:35]
	s_addc_u32 s15, s31, 0
	s_add_i32 s6, s12, s25
	global_load_lds_dwordx4 v[194:195], off
	v_lshl_add_u64 v[194:195], s[14:15], 0, v[0:1]
	s_mov_b32 m0, s6
	s_nop 0
	global_load_lds_dwordx4 v[194:195], off
	v_lshl_add_u64 v[194:195], s[14:15], 0, v[208:209]
	s_add_i32 m0, s6, 0x2000
	s_nop 0
	global_load_lds_dwordx4 v[194:195], off
	v_lshl_add_u64 v[194:195], v[202:203], 0, s[34:35]
	s_mov_b32 m0, s51
	s_nop 0
	global_load_lds_dwordx4 v[194:195], off
	v_lshl_add_u64 v[194:195], v[204:205], 0, s[34:35]
	s_mov_b32 m0, s52
	s_nop 0
	global_load_lds_dwordx4 v[194:195], off
	s_waitcnt vmcnt(8)
	s_waitcnt lgkmcnt(0)
	s_barrier
	s_setprio 1
	s_waitcnt lgkmcnt(0)
	v_mfma_f32_16x16x32_bf16 v[86:89], v[50:53], v[114:117], v[86:89]
	v_mfma_f32_16x16x32_bf16 v[78:81], v[66:69], v[114:117], v[78:81]
	v_mfma_f32_16x16x32_bf16 v[62:65], v[50:53], v[138:141], v[62:65]
	v_mfma_f32_16x16x32_bf16 v[54:57], v[66:69], v[138:141], v[54:57]
	v_mfma_f32_16x16x32_bf16 v[30:33], v[50:53], v[162:165], v[30:33]
	v_mfma_f32_16x16x32_bf16 v[26:29], v[66:69], v[162:165], v[26:29]
	v_mfma_f32_16x16x32_bf16 v[14:17], v[50:53], v[186:189], v[14:17]
	v_mfma_f32_16x16x32_bf16 v[10:13], v[66:69], v[186:189], v[10:13]
	v_mfma_f32_16x16x32_bf16 v[86:89], v[58:61], v[126:129], v[86:89]
	v_mfma_f32_16x16x32_bf16 v[78:81], v[70:73], v[126:129], v[78:81]
	v_mfma_f32_16x16x32_bf16 v[62:65], v[58:61], v[150:153], v[62:65]
	v_mfma_f32_16x16x32_bf16 v[54:57], v[70:73], v[150:153], v[54:57]
	v_mfma_f32_16x16x32_bf16 v[30:33], v[58:61], v[174:177], v[30:33]
	v_mfma_f32_16x16x32_bf16 v[26:29], v[70:73], v[174:177], v[26:29]
	v_mfma_f32_16x16x32_bf16 v[14:17], v[58:61], v[190:193], v[14:17]
	v_mfma_f32_16x16x32_bf16 v[10:13], v[70:73], v[190:193], v[10:13]
	s_setprio 0
	s_setprio 1
	v_mfma_f32_16x16x32_bf16 v[42:45], v[74:77], v[114:117], v[42:45]
	v_mfma_f32_16x16x32_bf16 v[70:73], v[82:85], v[126:129], v[42:45]
	v_mfma_f32_16x16x32_bf16 v[42:45], v[94:97], v[114:117], v[46:49]
	v_mfma_f32_16x16x32_bf16 v[38:41], v[74:77], v[138:141], v[38:41]
	v_mfma_f32_16x16x32_bf16 v[34:37], v[94:97], v[138:141], v[34:37]
	v_mfma_f32_16x16x32_bf16 v[22:25], v[74:77], v[162:165], v[22:25]
	v_mfma_f32_16x16x32_bf16 v[18:21], v[94:97], v[162:165], v[18:21]
	v_mfma_f32_16x16x32_bf16 v[6:9], v[74:77], v[186:189], v[6:9]
	v_mfma_f32_16x16x32_bf16 v[2:5], v[94:97], v[186:189], v[2:5]
	v_mfma_f32_16x16x32_bf16 v[66:69], v[102:105], v[126:129], v[42:45]
	v_mfma_f32_16x16x32_bf16 v[38:41], v[82:85], v[150:153], v[38:41]
	v_mfma_f32_16x16x32_bf16 v[34:37], v[102:105], v[150:153], v[34:37]
	v_mfma_f32_16x16x32_bf16 v[22:25], v[82:85], v[174:177], v[22:25]
	s_setprio 2
	s_barrier
	v_mfma_f32_16x16x32_bf16 v[18:21], v[102:105], v[174:177], v[18:21]
	v_mfma_f32_16x16x32_bf16 v[6:9], v[82:85], v[190:193], v[6:9]
	v_mfma_f32_16x16x32_bf16 v[2:5], v[102:105], v[190:193], v[2:5]
	s_setprio 0
	s_add_i32 s62, s62, 2
	s_add_u32 s60, s60, 0x100
	s_addc_u32 s61, s61, 0
	s_cmp_gt_u32 s62, 9
	s_mov_b64 s[28:29], s[2:3]
	s_cbranch_scc0 .LBB0_596
	s_and_b64 vcc, exec, s[42:43]
	s_cbranch_vccz .LBB0_599
	s_barrier

; #define PG8_STAGE(bufoff, gbase, voff) do { _Pragma("unroll") for (int _i = 0; _i < 2; ++_i) \
;         __builtin_amdgcn_global_load_lds((const unsigned*)((const char*)(gbase) + (voff)[_i]), (LAS unsigned*)(lds + (bufoff) + ldsw + _i * 8192), 16, 0, 0); } while (0)
; #define PG8_LDA(dst, b, h) do { _Pragma("unroll") for (int m = 0; m < 4; ++m) _Pragma("unroll") for (int k = 0; k < 2; ++k) dst[m][k] = *(const LAS bf16x8*)(lds + PG8_SA(b, h) + aoff + m * 2048 + k * 1024); } while (0)
; #define PG8_LDB(dst, b, h) do { _Pragma("unroll") for (int n = 0; n < 2; ++n) _Pragma("unroll") for (int k = 0; k < 2; ++k) dst[n][k] = *(const LAS bf16x8*)(lds + PG8_SB(b, h) + boff + n * 2048 + k * 1024); } while (0)
; #define PG8_MMA(ai, bj, At, Bt) do { __builtin_amdgcn_s_setprio(1); _Pragma("unroll") for (int m = 0; m < 4; ++m) _Pragma("unroll") for (int n = 0; n < 2; ++n) _Pragma("unroll") for (int k = 0; k < 2; ++k) \
;         acc[ai][bj][m][n] = __builtin_amdgcn_mfma_f32_16x16x32_bf16(Bt[n][k], At[m][k], acc[ai][bj][m][n], 0, 0, 0); __builtin_amdgcn_s_setprio(0); } while (0)
; #define PG8_WAIT_V(n) asm volatile("s_waitcnt vmcnt(" #n ")" ::: "memory")
; #define PG8_WAIT_L(n) asm volatile("s_waitcnt lgkmcnt(" #n ")" ::: "memory")
; #define PG8_BAR __builtin_amdgcn_s_barrier()
; #define PG8_SCHED __builtin_amdgcn_sched_barrier(0)
; template <class Epi>
; __device__ __forceinline__ void gemm_phase(LAS unsigned char* lds, const Gemm g, const TileOrder& S, const Epi& E) {
;     ...
;             const bool last = (t == nt - 2);
;             const char* a1 = cA + (size_t)(t + 1) * kstepA;
;             const char* a2 = last ? nA : cA + (size_t)(t + 2) * kstepA; const char* b2 = last ? nB : cB + (size_t)(t + 2) * kstep;
;             const char* a3 = a2 + kstepA; const char* b3 = b2 + kstep;
;             PG8_LDB(B0, 0, 0); PG8_LDB(B1, 0, 1); PG8_SCHED; PG8_LDA(At, 0, 0); PG8_STAGE(PG8_SA(1, 1), a1 + hstepA, voffA);
;             PG8_WAIT_V(8); PG8_WAIT_L(0); PG8_BAR; PG8_MMA(0, 0, At, B0); PG8_MMA(0, 1, At, B1); PG8_BAR; PG8_SCHED;
;             PG8_LDA(At, 0, 1); PG8_STAGE(PG8_SB(0, 0), b2, voffB); PG8_STAGE(PG8_SB(0, 1), b2 + hstepB, voffB); PG8_STAGE(PG8_SA(0, 0), a2, voffA);
;             PG8_WAIT_V(8); PG8_WAIT_L(0); PG8_BAR; PG8_MMA(1, 0, At, B0); PG8_MMA(1, 1, At, B1); PG8_BAR; PG8_SCHED;
.LBB0_668:
	s_add_u32 s2, s4, 0xfff80080
	s_addc_u32 s3, s5, -1
	s_add_i32 s6, 0, 0x10000
	s_cmp_eq_u32 s66, 28
	s_cselect_b32 s29, s45, s3
	s_cselect_b32 s28, s62, s2
	s_cselect_b32 s3, s43, s65
	s_cselect_b32 s2, s63, s64
	s_add_i32 s12, 0, 0x14000
	v_add_u32_e32 v142, s6, v184
	v_add_u32_e32 v168, s12, v184
	ds_read_b128 v[130:133], v142
	ds_read_b128 v[134:137], v142 offset:1024
	ds_read_b128 v[138:141], v142 offset:2048
	ds_read_b128 v[142:145], v142 offset:3072
	ds_read_b128 v[146:149], v168
	ds_read_b128 v[150:153], v168 offset:1024
	ds_read_b128 v[164:167], v168 offset:2048
	ds_read_b128 v[168:171], v168 offset:3072
	v_lshl_add_u64 v[180:181], s[4:5], 0, v[160:161]
	s_add_i32 m0, s50, 0xc000
	ds_read_b128 v[172:175], v185
	ds_read_b128 v[176:179], v185 offset:1024
	ds_read_b128 v[186:189], v185 offset:2048
	ds_read_b128 v[190:193], v185 offset:3072
	ds_read_b128 v[194:197], v185 offset:4096
	ds_read_b128 v[198:201], v185 offset:5120
	ds_read_b128 v[202:205], v185 offset:6144
	ds_read_b128 v[206:209], v185 offset:7168
	global_load_lds_dwordx4 v[180:181], off
	v_lshl_add_u64 v[180:181], s[4:5], 0, v[162:163]
	s_add_i32 m0, s50, 0xe000
	s_nop 0
	global_load_lds_dwordx4 v[180:181], off
	s_waitcnt vmcnt(8)
	s_waitcnt lgkmcnt(0)
	s_barrier
	s_setprio 1
	s_waitcnt lgkmcnt(0)
	v_mfma_f32_16x16x32_bf16 v[122:125], v[130:133], v[172:175], v[122:125]
	v_mfma_f32_16x16x32_bf16 v[118:121], v[138:141], v[172:175], v[118:121]
	v_mfma_f32_16x16x32_bf16 v[110:113], v[130:133], v[186:189], v[110:113]
	v_mfma_f32_16x16x32_bf16 v[102:105], v[138:141], v[186:189], v[102:105]
	v_mfma_f32_16x16x32_bf16 v[94:97], v[130:133], v[194:197], v[94:97]
	v_mfma_f32_16x16x32_bf16 v[86:89], v[138:141], v[194:197], v[86:89]
	v_mfma_f32_16x16x32_bf16 v[78:81], v[130:133], v[202:205], v[78:81]
	v_mfma_f32_16x16x32_bf16 v[70:73], v[138:141], v[202:205], v[70:73]
	v_mfma_f32_16x16x32_bf16 v[122:125], v[134:137], v[176:179], v[122:125]
	v_mfma_f32_16x16x32_bf16 v[118:121], v[142:145], v[176:179], v[118:121]
	v_mfma_f32_16x16x32_bf16 v[110:113], v[134:137], v[190:193], v[110:113]
	v_mfma_f32_16x16x32_bf16 v[102:105], v[142:145], v[190:193], v[102:105]
	v_mfma_f32_16x16x32_bf16 v[94:97], v[134:137], v[198:201], v[94:97]
	v_mfma_f32_16x16x32_bf16 v[86:89], v[142:145], v[198:201], v[86:89]
	v_mfma_f32_16x16x32_bf16 v[78:81], v[134:137], v[206:209], v[78:81]
	v_mfma_f32_16x16x32_bf16 v[70:73], v[142:145], v[206:209], v[70:73]
	s_setprio 0
	s_setprio 1
	v_mfma_f32_16x16x32_bf16 v[114:117], v[146:149], v[172:175], v[114:117]
	v_mfma_f32_16x16x32_bf16 v[126:129], v[164:167], v[172:175], v[126:129]
	v_mfma_f32_16x16x32_bf16 v[106:109], v[146:149], v[186:189], v[106:109]
	v_mfma_f32_16x16x32_bf16 v[98:101], v[164:167], v[186:189], v[98:101]
	v_mfma_f32_16x16x32_bf16 v[90:93], v[146:149], v[194:197], v[90:93]
	v_mfma_f32_16x16x32_bf16 v[82:85], v[164:167], v[194:197], v[82:85]
	v_mfma_f32_16x16x32_bf16 v[74:77], v[146:149], v[202:205], v[74:77]
	v_mfma_f32_16x16x32_bf16 v[66:69], v[164:167], v[202:205], v[66:69]
	v_mfma_f32_16x16x32_bf16 v[114:117], v[150:153], v[176:179], v[114:117]
	v_mfma_f32_16x16x32_bf16 v[126:129], v[168:171], v[176:179], v[126:129]
	v_mfma_f32_16x16x32_bf16 v[106:109], v[150:153], v[190:193], v[106:109]
	v_mfma_f32_16x16x32_bf16 v[98:101], v[168:171], v[190:193], v[98:101]
	v_mfma_f32_16x16x32_bf16 v[90:93], v[150:153], v[198:201], v[90:93]
	s_setprio 2
	s_barrier
	v_mfma_f32_16x16x32_bf16 v[82:85], v[168:171], v[198:201], v[82:85]
	v_mfma_f32_16x16x32_bf16 v[74:77], v[150:153], v[206:209], v[74:77]
	v_mfma_f32_16x16x32_bf16 v[66:69], v[168:171], v[206:209], v[66:69]
	s_setprio 0
	s_add_i32 s6, s6, s31
	v_lshl_add_u64 v[180:181], s[2:3], 0, v[0:1]
	s_mov_b32 m0, s6
	ds_read_b128 v[172:175], v185 offset:16384
	ds_read_b128 v[176:179], v185 offset:17408
	ds_read_b128 v[186:189], v185 offset:18432
	ds_read_b128 v[190:193], v185 offset:19456
	ds_read_b128 v[194:197], v185 offset:20480
	ds_read_b128 v[198:201], v185 offset:21504
	ds_read_b128 v[202:205], v185 offset:22528
	ds_read_b128 v[206:209], v185 offset:23552
	global_load_lds_dwordx4 v[180:181], off
	s_add_i32 m0, s6, 0x2000
	s_add_u32 s14, s2, 0x80000
	v_lshl_add_u64 v[210:211], s[2:3], 0, v[154:155]
	s_addc_u32 s15, s3, 0
	s_add_i32 s6, s12, s31
	global_load_lds_dwordx4 v[210:211], off
	v_lshl_add_u64 v[212:213], s[14:15], 0, v[0:1]
	s_mov_b32 m0, s6
	v_lshl_add_u64 v[214:215], s[28:29], 0, v[156:157]
	global_load_lds_dwordx4 v[212:213], off
	v_lshl_add_u64 v[212:213], s[14:15], 0, v[154:155]
	s_add_i32 m0, s6, 0x2000
	s_nop 0
	global_load_lds_dwordx4 v[212:213], off
	v_lshl_add_u64 v[212:213], s[28:29], 0, v[158:159]
	s_mov_b32 m0, s50
	s_nop 0
	global_load_lds_dwordx4 v[212:213], off
	s_mov_b32 m0, s51
	s_nop 0
	global_load_lds_dwordx4 v[214:215], off
	s_waitcnt vmcnt(8)
	s_waitcnt lgkmcnt(0)
	s_barrier
; #define PG8_STAGE(bufoff, gbase, voff) do { _Pragma("unroll") for (int _i = 0; _i < 2; ++_i) \
;         __builtin_amdgcn_global_load_lds((const unsigned*)((const char*)(gbase) + (voff)[_i]), (LAS unsigned*)(lds + (bufoff) + ldsw + _i * 8192), 16, 0, 0); } while (0)
; #define PG8_LDA(dst, b, h) do { _Pragma("unroll") for (int m = 0; m < 4; ++m) _Pragma("unroll") for (int k = 0; k < 2; ++k) dst[m][k] = *(const LAS bf16x8*)(lds + PG8_SA(b, h) + aoff + m * 2048 + k * 1024); } while (0)
; #define PG8_LDB(dst, b, h) do { _Pragma("unroll") for (int n = 0; n < 2; ++n) _Pragma("unroll") for (int k = 0; k < 2; ++k) dst[n][k] = *(const LAS bf16x8*)(lds + PG8_SB(b, h) + boff + n * 2048 + k * 1024); } while (0)
; #define PG8_MMA(ai, bj, At, Bt) do { __builtin_amdgcn_s_setprio(1); _Pragma("unroll") for (int m = 0; m < 4; ++m) _Pragma("unroll") for (int n = 0; n < 2; ++n) _Pragma("unroll") for (int k = 0; k < 2; ++k) \
;         acc[ai][bj][m][n] = __builtin_amdgcn_mfma_f32_16x16x32_bf16(Bt[n][k], At[m][k], acc[ai][bj][m][n], 0, 0, 0); __builtin_amdgcn_s_setprio(0); } while (0)
; #define PG8_WAIT_V(n) asm volatile("s_waitcnt vmcnt(" #n ")" ::: "memory")
; #define PG8_WAIT_L(n) asm volatile("s_waitcnt lgkmcnt(" #n ")" ::: "memory")
; #define PG8_BAR __builtin_amdgcn_s_barrier()
; #define PG8_SCHED __builtin_amdgcn_sched_barrier(0)
; template <class Epi>
; __device__ __forceinline__ void gemm_phase(LAS unsigned char* lds, const Gemm g, const TileOrder& S, const Epi& E) {
;     ...
;             PG8_WAIT_V(8); PG8_WAIT_L(0); PG8_BAR; PG8_MMA(1, 0, At, B0); PG8_MMA(1, 1, At, B1); PG8_BAR; PG8_SCHED;
;             PG8_LDB(B0, 1, 0); PG8_LDB(B1, 1, 1); PG8_SCHED; PG8_LDA(At, 1, 0); PG8_STAGE(PG8_SA(0, 1), a2 + hstepA, voffA);
;             PG8_WAIT_V(8); PG8_WAIT_L(0); PG8_BAR; PG8_MMA(0, 0, At, B0); PG8_MMA(0, 1, At, B1); PG8_BAR; PG8_SCHED;
	s_setprio 1
	s_waitcnt lgkmcnt(0)
	v_mfma_f32_16x16x32_bf16 v[62:65], v[130:133], v[172:175], v[62:65]
	v_mfma_f32_16x16x32_bf16 v[54:57], v[138:141], v[172:175], v[54:57]
	v_mfma_f32_16x16x32_bf16 v[46:49], v[130:133], v[186:189], v[46:49]
	v_mfma_f32_16x16x32_bf16 v[38:41], v[138:141], v[186:189], v[38:41]
	v_mfma_f32_16x16x32_bf16 v[30:33], v[130:133], v[194:197], v[30:33]
	v_mfma_f32_16x16x32_bf16 v[22:25], v[138:141], v[194:197], v[22:25]
	v_mfma_f32_16x16x32_bf16 v[14:17], v[130:133], v[202:205], v[14:17]
	v_mfma_f32_16x16x32_bf16 v[6:9], v[138:141], v[202:205], v[6:9]
	v_mfma_f32_16x16x32_bf16 v[62:65], v[134:137], v[176:179], v[62:65]
	v_mfma_f32_16x16x32_bf16 v[54:57], v[142:145], v[176:179], v[54:57]
	v_mfma_f32_16x16x32_bf16 v[46:49], v[134:137], v[190:193], v[46:49]
	v_mfma_f32_16x16x32_bf16 v[38:41], v[142:145], v[190:193], v[38:41]
	v_mfma_f32_16x16x32_bf16 v[30:33], v[134:137], v[198:201], v[30:33]
	v_mfma_f32_16x16x32_bf16 v[22:25], v[142:145], v[198:201], v[22:25]
	v_mfma_f32_16x16x32_bf16 v[14:17], v[134:137], v[206:209], v[14:17]
	v_mfma_f32_16x16x32_bf16 v[6:9], v[142:145], v[206:209], v[6:9]
	s_setprio 0
	s_setprio 1
	v_mfma_f32_16x16x32_bf16 v[58:61], v[146:149], v[172:175], v[58:61]
	v_mfma_f32_16x16x32_bf16 v[50:53], v[164:167], v[172:175], v[50:53]
	v_mfma_f32_16x16x32_bf16 v[42:45], v[146:149], v[186:189], v[42:45]
	v_mfma_f32_16x16x32_bf16 v[34:37], v[164:167], v[186:189], v[34:37]
	v_mfma_f32_16x16x32_bf16 v[26:29], v[146:149], v[194:197], v[26:29]
	v_mfma_f32_16x16x32_bf16 v[18:21], v[164:167], v[194:197], v[18:21]
	v_mfma_f32_16x16x32_bf16 v[10:13], v[146:149], v[202:205], v[10:13]
	v_mfma_f32_16x16x32_bf16 v[2:5], v[164:167], v[202:205], v[2:5]
	v_mfma_f32_16x16x32_bf16 v[58:61], v[150:153], v[176:179], v[58:61]
	v_mfma_f32_16x16x32_bf16 v[50:53], v[168:171], v[176:179], v[50:53]
	v_mfma_f32_16x16x32_bf16 v[42:45], v[150:153], v[190:193], v[42:45]
	v_mfma_f32_16x16x32_bf16 v[34:37], v[168:171], v[190:193], v[34:37]
	v_mfma_f32_16x16x32_bf16 v[26:29], v[150:153], v[198:201], v[26:29]
	s_setprio 2
	s_barrier
	v_mfma_f32_16x16x32_bf16 v[18:21], v[168:171], v[198:201], v[18:21]
	v_mfma_f32_16x16x32_bf16 v[10:13], v[150:153], v[206:209], v[10:13]
	v_mfma_f32_16x16x32_bf16 v[2:5], v[168:171], v[206:209], v[2:5]
	s_setprio 0
	s_add_i32 s6, 0, 0x18000
	s_add_i32 s12, 0, 0x1c000
	v_add_u32_e32 v142, s6, v184
	v_add_u32_e32 v168, s12, v184
	ds_read_b128 v[130:133], v142
	ds_read_b128 v[134:137], v142 offset:1024
	ds_read_b128 v[138:141], v142 offset:2048
	ds_read_b128 v[142:145], v142 offset:3072
	ds_read_b128 v[146:149], v168
	ds_read_b128 v[150:153], v168 offset:1024
	ds_read_b128 v[164:167], v168 offset:2048
	ds_read_b128 v[168:171], v168 offset:3072
	s_add_u32 s14, s28, 0x80000
	s_addc_u32 s15, s29, 0
	s_mov_b32 m0, s52
	v_lshl_add_u64 v[216:217], s[14:15], 0, v[158:159]
	ds_read_b128 v[172:175], v185 offset:32768
	ds_read_b128 v[176:179], v185 offset:33792
	ds_read_b128 v[186:189], v185 offset:34816
	ds_read_b128 v[190:193], v185 offset:35840
	ds_read_b128 v[194:197], v185 offset:36864
	ds_read_b128 v[198:201], v185 offset:37888
	ds_read_b128 v[202:205], v185 offset:38912
	ds_read_b128 v[206:209], v185 offset:39936
	global_load_lds_dwordx4 v[216:217], off
	v_lshl_add_u64 v[216:217], s[14:15], 0, v[156:157]
	s_mov_b32 m0, s53
	s_nop 0
	global_load_lds_dwordx4 v[216:217], off
	s_waitcnt vmcnt(8)
	s_waitcnt lgkmcnt(0)
	s_barrier
	s_setprio 1
	s_waitcnt lgkmcnt(0)
	v_mfma_f32_16x16x32_bf16 v[122:125], v[130:133], v[172:175], v[122:125]
	v_mfma_f32_16x16x32_bf16 v[118:121], v[138:141], v[172:175], v[118:121]
	v_mfma_f32_16x16x32_bf16 v[110:113], v[130:133], v[186:189], v[110:113]
	v_mfma_f32_16x16x32_bf16 v[102:105], v[138:141], v[186:189], v[102:105]
	v_mfma_f32_16x16x32_bf16 v[94:97], v[130:133], v[194:197], v[94:97]
	v_mfma_f32_16x16x32_bf16 v[86:89], v[138:141], v[194:197], v[86:89]
	v_mfma_f32_16x16x32_bf16 v[78:81], v[130:133], v[202:205], v[78:81]
	v_mfma_f32_16x16x32_bf16 v[70:73], v[138:141], v[202:205], v[70:73]
	v_mfma_f32_16x16x32_bf16 v[122:125], v[134:137], v[176:179], v[122:125]
	v_mfma_f32_16x16x32_bf16 v[118:121], v[142:145], v[176:179], v[118:121]
	v_mfma_f32_16x16x32_bf16 v[110:113], v[134:137], v[190:193], v[110:113]
	v_mfma_f32_16x16x32_bf16 v[102:105], v[142:145], v[190:193], v[102:105]
	v_mfma_f32_16x16x32_bf16 v[94:97], v[134:137], v[198:201], v[94:97]
	v_mfma_f32_16x16x32_bf16 v[86:89], v[142:145], v[198:201], v[86:89]
	v_mfma_f32_16x16x32_bf16 v[78:81], v[134:137], v[206:209], v[78:81]
	v_mfma_f32_16x16x32_bf16 v[70:73], v[142:145], v[206:209], v[70:73]
	s_setprio 0
	s_setprio 1
	v_mfma_f32_16x16x32_bf16 v[114:117], v[146:149], v[172:175], v[114:117]
	v_mfma_f32_16x16x32_bf16 v[126:129], v[164:167], v[172:175], v[126:129]
	v_mfma_f32_16x16x32_bf16 v[106:109], v[146:149], v[186:189], v[106:109]
	v_mfma_f32_16x16x32_bf16 v[98:101], v[164:167], v[186:189], v[98:101]
	v_mfma_f32_16x16x32_bf16 v[90:93], v[146:149], v[194:197], v[90:93]
	v_mfma_f32_16x16x32_bf16 v[82:85], v[164:167], v[194:197], v[82:85]
	v_mfma_f32_16x16x32_bf16 v[74:77], v[146:149], v[202:205], v[74:77]
	v_mfma_f32_16x16x32_bf16 v[66:69], v[164:167], v[202:205], v[66:69]
	v_mfma_f32_16x16x32_bf16 v[114:117], v[150:153], v[176:179], v[114:117]
	v_mfma_f32_16x16x32_bf16 v[126:129], v[168:171], v[176:179], v[126:129]
	v_mfma_f32_16x16x32_bf16 v[106:109], v[150:153], v[190:193], v[106:109]
	v_mfma_f32_16x16x32_bf16 v[98:101], v[168:171], v[190:193], v[98:101]
	v_mfma_f32_16x16x32_bf16 v[90:93], v[150:153], v[198:201], v[90:93]
	s_setprio 2
	s_barrier
; #define PG8_STAGE(bufoff, gbase, voff) do { _Pragma("unroll") for (int _i = 0; _i < 2; ++_i) \
;         __builtin_amdgcn_global_load_lds((const unsigned*)((const char*)(gbase) + (voff)[_i]), (LAS unsigned*)(lds + (bufoff) + ldsw + _i * 8192), 16, 0, 0); } while (0)
; #define PG8_LDA(dst, b, h) do { _Pragma("unroll") for (int m = 0; m < 4; ++m) _Pragma("unroll") for (int k = 0; k < 2; ++k) dst[m][k] = *(const LAS bf16x8*)(lds + PG8_SA(b, h) + aoff + m * 2048 + k * 1024); } while (0)
; #define PG8_MMA(ai, bj, At, Bt) do { __builtin_amdgcn_s_setprio(1); _Pragma("unroll") for (int m = 0; m < 4; ++m) _Pragma("unroll") for (int n = 0; n < 2; ++n) _Pragma("unroll") for (int k = 0; k < 2; ++k) \
;         acc[ai][bj][m][n] = __builtin_amdgcn_mfma_f32_16x16x32_bf16(Bt[n][k], At[m][k], acc[ai][bj][m][n], 0, 0, 0); __builtin_amdgcn_s_setprio(0); } while (0)
; #define PG8_WAIT_V(n) asm volatile("s_waitcnt vmcnt(" #n ")" ::: "memory")
; #define PG8_WAIT_L(n) asm volatile("s_waitcnt lgkmcnt(" #n ")" ::: "memory")
; #define PG8_BAR __builtin_amdgcn_s_barrier()
; #define PG8_SCHED __builtin_amdgcn_sched_barrier(0)
; template <class Epi>
; __device__ __forceinline__ void gemm_phase(LAS unsigned char* lds, const Gemm g, const TileOrder& S, const Epi& E) {
;     ...
;             PG8_WAIT_V(8); PG8_WAIT_L(0); PG8_BAR; PG8_MMA(0, 0, At, B0); PG8_MMA(0, 1, At, B1); PG8_BAR; PG8_SCHED;
;             PG8_LDA(At, 1, 1); PG8_STAGE(PG8_SB(1, 0), b3, voffB); PG8_STAGE(PG8_SB(1, 1), b3 + hstepB, voffB); PG8_STAGE(PG8_SA(1, 0), a3, voffA);
;             PG8_WAIT_V(8); PG8_WAIT_L(0); PG8_BAR; PG8_MMA(1, 0, At, B0); PG8_MMA(1, 1, At, B1); PG8_BAR; PG8_SCHED;
;         }
;         if (wr == 0) PG8_BAR;
	v_mfma_f32_16x16x32_bf16 v[82:85], v[168:171], v[198:201], v[82:85]
	v_mfma_f32_16x16x32_bf16 v[74:77], v[150:153], v[206:209], v[74:77]
	v_mfma_f32_16x16x32_bf16 v[66:69], v[168:171], v[206:209], v[66:69]
	s_setprio 0
	s_add_i32 s6, s6, s31
	v_lshl_add_u64 v[180:181], v[180:181], 0, s[34:35]
	s_mov_b32 m0, s6
	ds_read_b128 v[172:175], v185 offset:49152
	ds_read_b128 v[176:179], v185 offset:50176
	ds_read_b128 v[186:189], v185 offset:51200
	ds_read_b128 v[190:193], v185 offset:52224
	ds_read_b128 v[194:197], v185 offset:53248
	ds_read_b128 v[198:201], v185 offset:54272
	ds_read_b128 v[202:205], v185 offset:55296
	ds_read_b128 v[206:209], v185 offset:56320
	global_load_lds_dwordx4 v[180:181], off
	s_add_i32 m0, s6, 0x2000
	s_add_u32 s2, s2, 0x80080
	v_lshl_add_u64 v[180:181], v[210:211], 0, s[34:35]
	s_addc_u32 s3, s3, 0
	s_add_i32 s6, s12, s31
	global_load_lds_dwordx4 v[180:181], off
	v_lshl_add_u64 v[180:181], s[2:3], 0, v[0:1]
	s_mov_b32 m0, s6
	s_nop 0
	global_load_lds_dwordx4 v[180:181], off
	v_lshl_add_u64 v[180:181], s[2:3], 0, v[154:155]
	s_add_i32 m0, s6, 0x2000
	s_nop 0
	global_load_lds_dwordx4 v[180:181], off
	v_lshl_add_u64 v[180:181], v[212:213], 0, s[34:35]
	s_mov_b32 m0, s58
	s_nop 0
	global_load_lds_dwordx4 v[180:181], off
	v_lshl_add_u64 v[180:181], v[214:215], 0, s[34:35]
	s_mov_b32 m0, s59
	s_nop 0
	global_load_lds_dwordx4 v[180:181], off
	s_waitcnt vmcnt(8)
	s_waitcnt lgkmcnt(0)
	s_barrier
	s_setprio 1
	s_waitcnt lgkmcnt(0)
	v_mfma_f32_16x16x32_bf16 v[62:65], v[130:133], v[172:175], v[62:65]
	v_mfma_f32_16x16x32_bf16 v[54:57], v[138:141], v[172:175], v[54:57]
	v_mfma_f32_16x16x32_bf16 v[46:49], v[130:133], v[186:189], v[46:49]
	v_mfma_f32_16x16x32_bf16 v[38:41], v[138:141], v[186:189], v[38:41]
	v_mfma_f32_16x16x32_bf16 v[30:33], v[130:133], v[194:197], v[30:33]
	v_mfma_f32_16x16x32_bf16 v[22:25], v[138:141], v[194:197], v[22:25]
	v_mfma_f32_16x16x32_bf16 v[14:17], v[130:133], v[202:205], v[14:17]
	v_mfma_f32_16x16x32_bf16 v[6:9], v[138:141], v[202:205], v[6:9]
	v_mfma_f32_16x16x32_bf16 v[62:65], v[134:137], v[176:179], v[62:65]
	v_mfma_f32_16x16x32_bf16 v[54:57], v[142:145], v[176:179], v[54:57]
	v_mfma_f32_16x16x32_bf16 v[46:49], v[134:137], v[190:193], v[46:49]
	v_mfma_f32_16x16x32_bf16 v[38:41], v[142:145], v[190:193], v[38:41]
	v_mfma_f32_16x16x32_bf16 v[30:33], v[134:137], v[198:201], v[30:33]
	v_mfma_f32_16x16x32_bf16 v[22:25], v[142:145], v[198:201], v[22:25]
	v_mfma_f32_16x16x32_bf16 v[14:17], v[134:137], v[206:209], v[14:17]
	v_mfma_f32_16x16x32_bf16 v[6:9], v[142:145], v[206:209], v[6:9]
	s_setprio 0
	s_setprio 1
	v_mfma_f32_16x16x32_bf16 v[58:61], v[146:149], v[172:175], v[58:61]
	v_mfma_f32_16x16x32_bf16 v[50:53], v[164:167], v[172:175], v[50:53]
	v_mfma_f32_16x16x32_bf16 v[42:45], v[146:149], v[186:189], v[42:45]
	v_mfma_f32_16x16x32_bf16 v[34:37], v[164:167], v[186:189], v[34:37]
	v_mfma_f32_16x16x32_bf16 v[26:29], v[146:149], v[194:197], v[26:29]
	v_mfma_f32_16x16x32_bf16 v[18:21], v[164:167], v[194:197], v[18:21]
	v_mfma_f32_16x16x32_bf16 v[10:13], v[146:149], v[202:205], v[10:13]
	v_mfma_f32_16x16x32_bf16 v[2:5], v[164:167], v[202:205], v[2:5]
	v_mfma_f32_16x16x32_bf16 v[58:61], v[150:153], v[176:179], v[58:61]
	v_mfma_f32_16x16x32_bf16 v[50:53], v[168:171], v[176:179], v[50:53]
	v_mfma_f32_16x16x32_bf16 v[42:45], v[150:153], v[190:193], v[42:45]
	v_mfma_f32_16x16x32_bf16 v[34:37], v[168:171], v[190:193], v[34:37]
	v_mfma_f32_16x16x32_bf16 v[26:29], v[150:153], v[198:201], v[26:29]
	s_setprio 2
	s_barrier
	v_mfma_f32_16x16x32_bf16 v[18:21], v[168:171], v[198:201], v[18:21]
	v_mfma_f32_16x16x32_bf16 v[10:13], v[150:153], v[206:209], v[10:13]
	v_mfma_f32_16x16x32_bf16 v[2:5], v[168:171], v[206:209], v[2:5]
	s_setprio 0
	s_add_i32 s66, s66, 2
	s_add_u32 s4, s4, 0x100
	s_addc_u32 s5, s5, 0
	s_add_u32 s64, s64, 0x100
	s_addc_u32 s65, s65, 0
	s_cmp_gt_u32 s66, 29
	s_cbranch_scc0 .LBB0_668
	s_and_b64 vcc, exec, s[38:39]
	s_cbranch_vccz .LBB0_671
	s_barrier

; #define PG8_STAGE(bufoff, gbase, voff) do { _Pragma("unroll") for (int _i = 0; _i < 2; ++_i) \
;         __builtin_amdgcn_global_load_lds((const unsigned*)((const char*)(gbase) + (voff)[_i]), (LAS unsigned*)(lds + (bufoff) + ldsw + _i * 8192), 16, 0, 0); } while (0)
; #define PG8_LDA(dst, b, h) do { _Pragma("unroll") for (int m = 0; m < 4; ++m) _Pragma("unroll") for (int k = 0; k < 2; ++k) dst[m][k] = *(const LAS bf16x8*)(lds + PG8_SA(b, h) + aoff + m * 2048 + k * 1024); } while (0)
; #define PG8_LDB(dst, b, h) do { _Pragma("unroll") for (int n = 0; n < 2; ++n) _Pragma("unroll") for (int k = 0; k < 2; ++k) dst[n][k] = *(const LAS bf16x8*)(lds + PG8_SB(b, h) + boff + n * 2048 + k * 1024); } while (0)
; #define PG8_MMA(ai, bj, At, Bt) do { __builtin_amdgcn_s_setprio(1); _Pragma("unroll") for (int m = 0; m < 4; ++m) _Pragma("unroll") for (int n = 0; n < 2; ++n) _Pragma("unroll") for (int k = 0; k < 2; ++k) \
;         acc[ai][bj][m][n] = __builtin_amdgcn_mfma_f32_16x16x32_bf16(Bt[n][k], At[m][k], acc[ai][bj][m][n], 0, 0, 0); __builtin_amdgcn_s_setprio(0); } while (0)
; #define PG8_WAIT_V(n) asm volatile("s_waitcnt vmcnt(" #n ")" ::: "memory")
; #define PG8_WAIT_L(n) asm volatile("s_waitcnt lgkmcnt(" #n ")" ::: "memory")
; #define PG8_BAR __builtin_amdgcn_s_barrier()
; #define PG8_SCHED __builtin_amdgcn_sched_barrier(0)
; template <class Epi>
; __device__ __forceinline__ void gemm_phase(LAS unsigned char* lds, const Gemm g, const TileOrder& S, const Epi& E) {
;     ...
;             const bool last = (t == nt - 2);
;             const char* a1 = cA + (size_t)(t + 1) * kstepA;
;             const char* a2 = last ? nA : cA + (size_t)(t + 2) * kstepA; const char* b2 = last ? nB : cB + (size_t)(t + 2) * kstep;
;             const char* a3 = a2 + kstepA; const char* b3 = b2 + kstep;
;             PG8_LDB(B0, 0, 0); PG8_LDB(B1, 0, 1); PG8_SCHED; PG8_LDA(At, 0, 0); PG8_STAGE(PG8_SA(1, 1), a1 + hstepA, voffA);
;             PG8_WAIT_V(8); PG8_WAIT_L(0); PG8_BAR; PG8_MMA(0, 0, At, B0); PG8_MMA(0, 1, At, B1); PG8_BAR; PG8_SCHED;
;             PG8_LDA(At, 0, 1); PG8_STAGE(PG8_SB(0, 0), b2, voffB); PG8_STAGE(PG8_SB(0, 1), b2 + hstepB, voffB); PG8_STAGE(PG8_SA(0, 0), a2, voffA);
;             PG8_WAIT_V(8); PG8_WAIT_L(0); PG8_BAR; PG8_MMA(1, 0, At, B0); PG8_MMA(1, 1, At, B1); PG8_BAR; PG8_SCHED;
.LBB0_757:
	s_add_u32 s2, s28, 0xfff80080
	s_addc_u32 s3, s29, -1
	s_add_i32 s6, 0, 0x10000
	s_cmp_eq_u32 s72, 28
	s_cselect_b32 s31, s47, s3
	s_cselect_b32 s30, s51, s2
	v_add_u32_e32 v0, s6, v154
	s_cselect_b32 s3, s49, s71
	s_cselect_b32 s2, s69, s70
	s_add_i32 s14, 0, 0x14000
	ds_read_b128 v[142:145], v0
	ds_read_b128 v[146:149], v0 offset:1024
	ds_read_b128 v[156:159], v0 offset:2048
	ds_read_b128 v[160:163], v0 offset:3072
	v_add_u32_e32 v0, s14, v154
	ds_read_b128 v[164:167], v0
	ds_read_b128 v[168:171], v0 offset:1024
	ds_read_b128 v[172:175], v0 offset:2048
	ds_read_b128 v[176:179], v0 offset:3072
	v_lshl_add_u64 v[150:151], s[28:29], 0, v[138:139]
	s_add_i32 m0, s59, 0xc000
	ds_read_b128 v[180:183], v155
	ds_read_b128 v[184:187], v155 offset:1024
	ds_read_b128 v[188:191], v155 offset:2048
	ds_read_b128 v[192:195], v155 offset:3072
	ds_read_b128 v[196:199], v155 offset:4096
	ds_read_b128 v[200:203], v155 offset:5120
	ds_read_b128 v[204:207], v155 offset:6144
	ds_read_b128 v[208:211], v155 offset:7168
	global_load_lds_dwordx4 v[150:151], off
	v_lshl_add_u64 v[150:151], s[28:29], 0, v[140:141]
	s_add_i32 m0, s59, 0xe000
	s_nop 0
	global_load_lds_dwordx4 v[150:151], off
	s_waitcnt vmcnt(8)
	s_waitcnt lgkmcnt(0)
	s_barrier
	s_setprio 1
	s_waitcnt lgkmcnt(0)
	v_mfma_f32_16x16x32_bf16 v[126:129], v[142:145], v[180:183], v[126:129]
	v_mfma_f32_16x16x32_bf16 v[122:125], v[156:159], v[180:183], v[122:125]
	v_mfma_f32_16x16x32_bf16 v[110:113], v[142:145], v[188:191], v[110:113]
	v_mfma_f32_16x16x32_bf16 v[106:109], v[156:159], v[188:191], v[106:109]
	v_mfma_f32_16x16x32_bf16 v[94:97], v[142:145], v[196:199], v[94:97]
	v_mfma_f32_16x16x32_bf16 v[90:93], v[156:159], v[196:199], v[90:93]
	v_mfma_f32_16x16x32_bf16 v[78:81], v[142:145], v[204:207], v[78:81]
	v_mfma_f32_16x16x32_bf16 v[74:77], v[156:159], v[204:207], v[74:77]
	v_mfma_f32_16x16x32_bf16 v[126:129], v[146:149], v[184:187], v[126:129]
	v_mfma_f32_16x16x32_bf16 v[122:125], v[160:163], v[184:187], v[122:125]
	v_mfma_f32_16x16x32_bf16 v[110:113], v[146:149], v[192:195], v[110:113]
	v_mfma_f32_16x16x32_bf16 v[106:109], v[160:163], v[192:195], v[106:109]
	v_mfma_f32_16x16x32_bf16 v[94:97], v[146:149], v[200:203], v[94:97]
	v_mfma_f32_16x16x32_bf16 v[90:93], v[160:163], v[200:203], v[90:93]
	v_mfma_f32_16x16x32_bf16 v[78:81], v[146:149], v[208:211], v[78:81]
	v_mfma_f32_16x16x32_bf16 v[74:77], v[160:163], v[208:211], v[74:77]
	s_setprio 0
	s_setprio 1
	v_mfma_f32_16x16x32_bf16 v[118:121], v[164:167], v[180:183], v[118:121]
	v_mfma_f32_16x16x32_bf16 v[114:117], v[172:175], v[180:183], v[114:117]
	v_mfma_f32_16x16x32_bf16 v[102:105], v[164:167], v[188:191], v[102:105]
	v_mfma_f32_16x16x32_bf16 v[98:101], v[172:175], v[188:191], v[98:101]
	v_mfma_f32_16x16x32_bf16 v[86:89], v[164:167], v[196:199], v[86:89]
	v_mfma_f32_16x16x32_bf16 v[82:85], v[172:175], v[196:199], v[82:85]
	v_mfma_f32_16x16x32_bf16 v[70:73], v[164:167], v[204:207], v[70:73]
	v_mfma_f32_16x16x32_bf16 v[66:69], v[172:175], v[204:207], v[66:69]
	v_mfma_f32_16x16x32_bf16 v[118:121], v[168:171], v[184:187], v[118:121]
	v_mfma_f32_16x16x32_bf16 v[114:117], v[176:179], v[184:187], v[114:117]
	v_mfma_f32_16x16x32_bf16 v[102:105], v[168:171], v[192:195], v[102:105]
	v_mfma_f32_16x16x32_bf16 v[98:101], v[176:179], v[192:195], v[98:101]
	v_mfma_f32_16x16x32_bf16 v[86:89], v[168:171], v[200:203], v[86:89]
	s_setprio 2
	s_barrier
	v_mfma_f32_16x16x32_bf16 v[82:85], v[176:179], v[200:203], v[82:85]
	v_mfma_f32_16x16x32_bf16 v[70:73], v[168:171], v[208:211], v[70:73]
	v_mfma_f32_16x16x32_bf16 v[66:69], v[176:179], v[208:211], v[66:69]
	s_setprio 0
	s_add_i32 s6, s6, s58
	v_lshl_add_u64 v[150:151], s[2:3], 0, v[134:135]
	s_mov_b32 m0, s6
	ds_read_b128 v[180:183], v155 offset:16384
	ds_read_b128 v[184:187], v155 offset:17408
	ds_read_b128 v[188:191], v155 offset:18432
	ds_read_b128 v[192:195], v155 offset:19456
	ds_read_b128 v[196:199], v155 offset:20480
	ds_read_b128 v[200:203], v155 offset:21504
	ds_read_b128 v[204:207], v155 offset:22528
	ds_read_b128 v[208:211], v155 offset:23552
	global_load_lds_dwordx4 v[150:151], off
	s_add_i32 m0, s6, 0x2000
	s_add_u32 s12, s2, 0x80000
	v_lshl_add_u64 v[212:213], s[2:3], 0, v[130:131]
	s_addc_u32 s13, s3, 0
	s_add_i32 s6, s14, s58
	global_load_lds_dwordx4 v[212:213], off
	v_lshl_add_u64 v[214:215], s[12:13], 0, v[134:135]
	s_mov_b32 m0, s6
	v_lshl_add_u64 v[216:217], s[30:31], 0, v[132:133]
	global_load_lds_dwordx4 v[214:215], off
	v_lshl_add_u64 v[214:215], s[12:13], 0, v[130:131]
	s_add_i32 m0, s6, 0x2000
	s_nop 0
	global_load_lds_dwordx4 v[214:215], off
	v_lshl_add_u64 v[214:215], s[30:31], 0, v[136:137]
	s_mov_b32 m0, s59
	s_nop 0
	global_load_lds_dwordx4 v[214:215], off
	s_mov_b32 m0, s60
	s_nop 0
	global_load_lds_dwordx4 v[216:217], off
	s_waitcnt vmcnt(8)
	s_waitcnt lgkmcnt(0)
	s_barrier
; #define PG8_STAGE(bufoff, gbase, voff) do { _Pragma("unroll") for (int _i = 0; _i < 2; ++_i) \
;         __builtin_amdgcn_global_load_lds((const unsigned*)((const char*)(gbase) + (voff)[_i]), (LAS unsigned*)(lds + (bufoff) + ldsw + _i * 8192), 16, 0, 0); } while (0)
; #define PG8_LDA(dst, b, h) do { _Pragma("unroll") for (int m = 0; m < 4; ++m) _Pragma("unroll") for (int k = 0; k < 2; ++k) dst[m][k] = *(const LAS bf16x8*)(lds + PG8_SA(b, h) + aoff + m * 2048 + k * 1024); } while (0)
; #define PG8_LDB(dst, b, h) do { _Pragma("unroll") for (int n = 0; n < 2; ++n) _Pragma("unroll") for (int k = 0; k < 2; ++k) dst[n][k] = *(const LAS bf16x8*)(lds + PG8_SB(b, h) + boff + n * 2048 + k * 1024); } while (0)
; #define PG8_MMA(ai, bj, At, Bt) do { __builtin_amdgcn_s_setprio(1); _Pragma("unroll") for (int m = 0; m < 4; ++m) _Pragma("unroll") for (int n = 0; n < 2; ++n) _Pragma("unroll") for (int k = 0; k < 2; ++k) \
;         acc[ai][bj][m][n] = __builtin_amdgcn_mfma_f32_16x16x32_bf16(Bt[n][k], At[m][k], acc[ai][bj][m][n], 0, 0, 0); __builtin_amdgcn_s_setprio(0); } while (0)
; #define PG8_WAIT_V(n) asm volatile("s_waitcnt vmcnt(" #n ")" ::: "memory")
; #define PG8_WAIT_L(n) asm volatile("s_waitcnt lgkmcnt(" #n ")" ::: "memory")
; #define PG8_BAR __builtin_amdgcn_s_barrier()
; #define PG8_SCHED __builtin_amdgcn_sched_barrier(0)
; template <class Epi>
; __device__ __forceinline__ void gemm_phase(LAS unsigned char* lds, const Gemm g, const TileOrder& S, const Epi& E) {
;     ...
;             PG8_WAIT_V(8); PG8_WAIT_L(0); PG8_BAR; PG8_MMA(1, 0, At, B0); PG8_MMA(1, 1, At, B1); PG8_BAR; PG8_SCHED;
;             PG8_LDB(B0, 1, 0); PG8_LDB(B1, 1, 1); PG8_SCHED; PG8_LDA(At, 1, 0); PG8_STAGE(PG8_SA(0, 1), a2 + hstepA, voffA);
;             PG8_WAIT_V(8); PG8_WAIT_L(0); PG8_BAR; PG8_MMA(0, 0, At, B0); PG8_MMA(0, 1, At, B1); PG8_BAR; PG8_SCHED;
	s_setprio 1
	s_waitcnt lgkmcnt(0)
	v_mfma_f32_16x16x32_bf16 v[62:65], v[142:145], v[180:183], v[62:65]
	v_mfma_f32_16x16x32_bf16 v[58:61], v[156:159], v[180:183], v[58:61]
	v_mfma_f32_16x16x32_bf16 v[46:49], v[142:145], v[188:191], v[46:49]
	v_mfma_f32_16x16x32_bf16 v[42:45], v[156:159], v[188:191], v[42:45]
	v_mfma_f32_16x16x32_bf16 v[30:33], v[142:145], v[196:199], v[30:33]
	v_mfma_f32_16x16x32_bf16 v[26:29], v[156:159], v[196:199], v[26:29]
	v_mfma_f32_16x16x32_bf16 v[14:17], v[142:145], v[204:207], v[14:17]
	v_mfma_f32_16x16x32_bf16 v[10:13], v[156:159], v[204:207], v[10:13]
	v_mfma_f32_16x16x32_bf16 v[62:65], v[146:149], v[184:187], v[62:65]
	v_mfma_f32_16x16x32_bf16 v[58:61], v[160:163], v[184:187], v[58:61]
	v_mfma_f32_16x16x32_bf16 v[46:49], v[146:149], v[192:195], v[46:49]
	v_mfma_f32_16x16x32_bf16 v[42:45], v[160:163], v[192:195], v[42:45]
	v_mfma_f32_16x16x32_bf16 v[30:33], v[146:149], v[200:203], v[30:33]
	v_mfma_f32_16x16x32_bf16 v[26:29], v[160:163], v[200:203], v[26:29]
	v_mfma_f32_16x16x32_bf16 v[14:17], v[146:149], v[208:211], v[14:17]
	v_mfma_f32_16x16x32_bf16 v[10:13], v[160:163], v[208:211], v[10:13]
	s_setprio 0
	s_setprio 1
	v_mfma_f32_16x16x32_bf16 v[54:57], v[164:167], v[180:183], v[54:57]
	v_mfma_f32_16x16x32_bf16 v[50:53], v[172:175], v[180:183], v[50:53]
	v_mfma_f32_16x16x32_bf16 v[38:41], v[164:167], v[188:191], v[38:41]
	v_mfma_f32_16x16x32_bf16 v[34:37], v[172:175], v[188:191], v[34:37]
	v_mfma_f32_16x16x32_bf16 v[22:25], v[164:167], v[196:199], v[22:25]
	v_mfma_f32_16x16x32_bf16 v[18:21], v[172:175], v[196:199], v[18:21]
	v_mfma_f32_16x16x32_bf16 v[6:9], v[164:167], v[204:207], v[6:9]
	v_mfma_f32_16x16x32_bf16 v[2:5], v[172:175], v[204:207], v[2:5]
	v_mfma_f32_16x16x32_bf16 v[54:57], v[168:171], v[184:187], v[54:57]
	v_mfma_f32_16x16x32_bf16 v[50:53], v[176:179], v[184:187], v[50:53]
	v_mfma_f32_16x16x32_bf16 v[38:41], v[168:171], v[192:195], v[38:41]
	v_mfma_f32_16x16x32_bf16 v[34:37], v[176:179], v[192:195], v[34:37]
	v_mfma_f32_16x16x32_bf16 v[22:25], v[168:171], v[200:203], v[22:25]
	s_setprio 2
	s_barrier
	v_mfma_f32_16x16x32_bf16 v[18:21], v[176:179], v[200:203], v[18:21]
	v_mfma_f32_16x16x32_bf16 v[6:9], v[168:171], v[208:211], v[6:9]
	v_mfma_f32_16x16x32_bf16 v[2:5], v[176:179], v[208:211], v[2:5]
	s_setprio 0
	s_add_i32 s6, 0, 0x18000
	v_add_u32_e32 v0, s6, v154
	s_add_i32 s14, 0, 0x1c000
	ds_read_b128 v[142:145], v0
	ds_read_b128 v[146:149], v0 offset:1024
	ds_read_b128 v[156:159], v0 offset:2048
	ds_read_b128 v[160:163], v0 offset:3072
	v_add_u32_e32 v0, s14, v154
	ds_read_b128 v[164:167], v0
	ds_read_b128 v[168:171], v0 offset:1024
	ds_read_b128 v[172:175], v0 offset:2048
	ds_read_b128 v[176:179], v0 offset:3072
	s_add_u32 s12, s30, 0x80000
	s_addc_u32 s13, s31, 0
	s_mov_b32 m0, s61
	v_lshl_add_u64 v[218:219], s[12:13], 0, v[136:137]
	ds_read_b128 v[180:183], v155 offset:32768
	ds_read_b128 v[184:187], v155 offset:33792
	ds_read_b128 v[188:191], v155 offset:34816
	ds_read_b128 v[192:195], v155 offset:35840
	ds_read_b128 v[196:199], v155 offset:36864
	ds_read_b128 v[200:203], v155 offset:37888
	ds_read_b128 v[204:207], v155 offset:38912
	ds_read_b128 v[208:211], v155 offset:39936
	global_load_lds_dwordx4 v[218:219], off
	v_lshl_add_u64 v[218:219], s[12:13], 0, v[132:133]
	s_mov_b32 m0, s62
	s_nop 0
	global_load_lds_dwordx4 v[218:219], off
	s_waitcnt vmcnt(8)
	s_waitcnt lgkmcnt(0)
	s_barrier
	s_setprio 1
	s_waitcnt lgkmcnt(0)
	v_mfma_f32_16x16x32_bf16 v[126:129], v[142:145], v[180:183], v[126:129]
	v_mfma_f32_16x16x32_bf16 v[122:125], v[156:159], v[180:183], v[122:125]
	v_mfma_f32_16x16x32_bf16 v[110:113], v[142:145], v[188:191], v[110:113]
	v_mfma_f32_16x16x32_bf16 v[106:109], v[156:159], v[188:191], v[106:109]
	v_mfma_f32_16x16x32_bf16 v[94:97], v[142:145], v[196:199], v[94:97]
	v_mfma_f32_16x16x32_bf16 v[90:93], v[156:159], v[196:199], v[90:93]
	v_mfma_f32_16x16x32_bf16 v[78:81], v[142:145], v[204:207], v[78:81]
	v_mfma_f32_16x16x32_bf16 v[74:77], v[156:159], v[204:207], v[74:77]
	v_mfma_f32_16x16x32_bf16 v[126:129], v[146:149], v[184:187], v[126:129]
	v_mfma_f32_16x16x32_bf16 v[122:125], v[160:163], v[184:187], v[122:125]
	v_mfma_f32_16x16x32_bf16 v[110:113], v[146:149], v[192:195], v[110:113]
	v_mfma_f32_16x16x32_bf16 v[106:109], v[160:163], v[192:195], v[106:109]
	v_mfma_f32_16x16x32_bf16 v[94:97], v[146:149], v[200:203], v[94:97]
	v_mfma_f32_16x16x32_bf16 v[90:93], v[160:163], v[200:203], v[90:93]
	v_mfma_f32_16x16x32_bf16 v[78:81], v[146:149], v[208:211], v[78:81]
	v_mfma_f32_16x16x32_bf16 v[74:77], v[160:163], v[208:211], v[74:77]
	s_setprio 0
	s_setprio 1
	v_mfma_f32_16x16x32_bf16 v[118:121], v[164:167], v[180:183], v[118:121]
	v_mfma_f32_16x16x32_bf16 v[114:117], v[172:175], v[180:183], v[114:117]
	v_mfma_f32_16x16x32_bf16 v[102:105], v[164:167], v[188:191], v[102:105]
	v_mfma_f32_16x16x32_bf16 v[98:101], v[172:175], v[188:191], v[98:101]
	v_mfma_f32_16x16x32_bf16 v[86:89], v[164:167], v[196:199], v[86:89]
	v_mfma_f32_16x16x32_bf16 v[82:85], v[172:175], v[196:199], v[82:85]
	v_mfma_f32_16x16x32_bf16 v[70:73], v[164:167], v[204:207], v[70:73]
	v_mfma_f32_16x16x32_bf16 v[66:69], v[172:175], v[204:207], v[66:69]
	v_mfma_f32_16x16x32_bf16 v[118:121], v[168:171], v[184:187], v[118:121]
	v_mfma_f32_16x16x32_bf16 v[114:117], v[176:179], v[184:187], v[114:117]
	v_mfma_f32_16x16x32_bf16 v[102:105], v[168:171], v[192:195], v[102:105]
	v_mfma_f32_16x16x32_bf16 v[98:101], v[176:179], v[192:195], v[98:101]
	v_mfma_f32_16x16x32_bf16 v[86:89], v[168:171], v[200:203], v[86:89]
	s_setprio 2
	s_barrier
; #define PG8_STAGE(bufoff, gbase, voff) do { _Pragma("unroll") for (int _i = 0; _i < 2; ++_i) \
;         __builtin_amdgcn_global_load_lds((const unsigned*)((const char*)(gbase) + (voff)[_i]), (LAS unsigned*)(lds + (bufoff) + ldsw + _i * 8192), 16, 0, 0); } while (0)
; #define PG8_LDA(dst, b, h) do { _Pragma("unroll") for (int m = 0; m < 4; ++m) _Pragma("unroll") for (int k = 0; k < 2; ++k) dst[m][k] = *(const LAS bf16x8*)(lds + PG8_SA(b, h) + aoff + m * 2048 + k * 1024); } while (0)
; #define PG8_MMA(ai, bj, At, Bt) do { __builtin_amdgcn_s_setprio(1); _Pragma("unroll") for (int m = 0; m < 4; ++m) _Pragma("unroll") for (int n = 0; n < 2; ++n) _Pragma("unroll") for (int k = 0; k < 2; ++k) \
;         acc[ai][bj][m][n] = __builtin_amdgcn_mfma_f32_16x16x32_bf16(Bt[n][k], At[m][k], acc[ai][bj][m][n], 0, 0, 0); __builtin_amdgcn_s_setprio(0); } while (0)
; #define PG8_WAIT_V(n) asm volatile("s_waitcnt vmcnt(" #n ")" ::: "memory")
; #define PG8_WAIT_L(n) asm volatile("s_waitcnt lgkmcnt(" #n ")" ::: "memory")
; #define PG8_BAR __builtin_amdgcn_s_barrier()
; #define PG8_SCHED __builtin_amdgcn_sched_barrier(0)
; template <class Epi>
; __device__ __forceinline__ void gemm_phase(LAS unsigned char* lds, const Gemm g, const TileOrder& S, const Epi& E) {
;     ...
;             PG8_WAIT_V(8); PG8_WAIT_L(0); PG8_BAR; PG8_MMA(0, 0, At, B0); PG8_MMA(0, 1, At, B1); PG8_BAR; PG8_SCHED;
;             PG8_LDA(At, 1, 1); PG8_STAGE(PG8_SB(1, 0), b3, voffB); PG8_STAGE(PG8_SB(1, 1), b3 + hstepB, voffB); PG8_STAGE(PG8_SA(1, 0), a3, voffA);
;             PG8_WAIT_V(8); PG8_WAIT_L(0); PG8_BAR; PG8_MMA(1, 0, At, B0); PG8_MMA(1, 1, At, B1); PG8_BAR; PG8_SCHED;
;         }
;         if (wr == 0) PG8_BAR;
	v_mfma_f32_16x16x32_bf16 v[82:85], v[176:179], v[200:203], v[82:85]
	v_mfma_f32_16x16x32_bf16 v[70:73], v[168:171], v[208:211], v[70:73]
	v_mfma_f32_16x16x32_bf16 v[66:69], v[176:179], v[208:211], v[66:69]
	s_setprio 0
	s_add_i32 s6, s6, s58
	v_lshl_add_u64 v[150:151], v[150:151], 0, s[34:35]
	s_mov_b32 m0, s6
	ds_read_b128 v[180:183], v155 offset:49152
	ds_read_b128 v[184:187], v155 offset:50176
	ds_read_b128 v[188:191], v155 offset:51200
	ds_read_b128 v[192:195], v155 offset:52224
	ds_read_b128 v[196:199], v155 offset:53248
	ds_read_b128 v[200:203], v155 offset:54272
	ds_read_b128 v[204:207], v155 offset:55296
	ds_read_b128 v[208:211], v155 offset:56320
	global_load_lds_dwordx4 v[150:151], off
	s_add_i32 m0, s6, 0x2000
	s_add_u32 s2, s2, 0x80080
	v_lshl_add_u64 v[150:151], v[212:213], 0, s[34:35]
	s_addc_u32 s3, s3, 0
	s_add_i32 s6, s14, s58
	global_load_lds_dwordx4 v[150:151], off
	v_lshl_add_u64 v[150:151], s[2:3], 0, v[134:135]
	s_mov_b32 m0, s6
	s_nop 0
	global_load_lds_dwordx4 v[150:151], off
	v_lshl_add_u64 v[150:151], s[2:3], 0, v[130:131]
	s_add_i32 m0, s6, 0x2000
	s_nop 0
	global_load_lds_dwordx4 v[150:151], off
	v_lshl_add_u64 v[150:151], v[214:215], 0, s[34:35]
	s_mov_b32 m0, s63
	s_nop 0
	global_load_lds_dwordx4 v[150:151], off
	v_lshl_add_u64 v[150:151], v[216:217], 0, s[34:35]
	s_mov_b32 m0, s64
	s_nop 0
	global_load_lds_dwordx4 v[150:151], off
	s_waitcnt vmcnt(8)
	s_waitcnt lgkmcnt(0)
	s_barrier
	s_setprio 1
	s_waitcnt lgkmcnt(0)
	v_mfma_f32_16x16x32_bf16 v[62:65], v[142:145], v[180:183], v[62:65]
	v_mfma_f32_16x16x32_bf16 v[58:61], v[156:159], v[180:183], v[58:61]
	v_mfma_f32_16x16x32_bf16 v[46:49], v[142:145], v[188:191], v[46:49]
	v_mfma_f32_16x16x32_bf16 v[42:45], v[156:159], v[188:191], v[42:45]
	v_mfma_f32_16x16x32_bf16 v[30:33], v[142:145], v[196:199], v[30:33]
	v_mfma_f32_16x16x32_bf16 v[26:29], v[156:159], v[196:199], v[26:29]
	v_mfma_f32_16x16x32_bf16 v[14:17], v[142:145], v[204:207], v[14:17]
	v_mfma_f32_16x16x32_bf16 v[10:13], v[156:159], v[204:207], v[10:13]
	v_mfma_f32_16x16x32_bf16 v[62:65], v[146:149], v[184:187], v[62:65]
	v_mfma_f32_16x16x32_bf16 v[58:61], v[160:163], v[184:187], v[58:61]
	v_mfma_f32_16x16x32_bf16 v[46:49], v[146:149], v[192:195], v[46:49]
	v_mfma_f32_16x16x32_bf16 v[42:45], v[160:163], v[192:195], v[42:45]
	v_mfma_f32_16x16x32_bf16 v[30:33], v[146:149], v[200:203], v[30:33]
	v_mfma_f32_16x16x32_bf16 v[26:29], v[160:163], v[200:203], v[26:29]
	v_mfma_f32_16x16x32_bf16 v[14:17], v[146:149], v[208:211], v[14:17]
	v_mfma_f32_16x16x32_bf16 v[10:13], v[160:163], v[208:211], v[10:13]
	s_setprio 0
	s_setprio 1
	v_mfma_f32_16x16x32_bf16 v[54:57], v[164:167], v[180:183], v[54:57]
	v_mfma_f32_16x16x32_bf16 v[50:53], v[172:175], v[180:183], v[50:53]
	v_mfma_f32_16x16x32_bf16 v[38:41], v[164:167], v[188:191], v[38:41]
	v_mfma_f32_16x16x32_bf16 v[34:37], v[172:175], v[188:191], v[34:37]
	v_mfma_f32_16x16x32_bf16 v[22:25], v[164:167], v[196:199], v[22:25]
	v_mfma_f32_16x16x32_bf16 v[18:21], v[172:175], v[196:199], v[18:21]
	v_mfma_f32_16x16x32_bf16 v[6:9], v[164:167], v[204:207], v[6:9]
	v_mfma_f32_16x16x32_bf16 v[2:5], v[172:175], v[204:207], v[2:5]
	v_mfma_f32_16x16x32_bf16 v[54:57], v[168:171], v[184:187], v[54:57]
	v_mfma_f32_16x16x32_bf16 v[50:53], v[176:179], v[184:187], v[50:53]
	v_mfma_f32_16x16x32_bf16 v[38:41], v[168:171], v[192:195], v[38:41]
	v_mfma_f32_16x16x32_bf16 v[34:37], v[176:179], v[192:195], v[34:37]
	v_mfma_f32_16x16x32_bf16 v[22:25], v[168:171], v[200:203], v[22:25]
	s_setprio 2
	s_barrier
	v_mfma_f32_16x16x32_bf16 v[18:21], v[176:179], v[200:203], v[18:21]
	v_mfma_f32_16x16x32_bf16 v[6:9], v[168:171], v[208:211], v[6:9]
	v_mfma_f32_16x16x32_bf16 v[2:5], v[176:179], v[208:211], v[2:5]
	s_setprio 0
	s_add_i32 s72, s72, 2
	s_add_u32 s28, s28, 0x100
	s_addc_u32 s29, s29, 0
	s_add_u32 s70, s70, 0x100
	s_addc_u32 s71, s71, 0
	s_cmp_gt_u32 s72, 29
	s_cbranch_scc0 .LBB0_757
	s_and_b64 vcc, exec, s[42:43]
	s_cbranch_vccz .LBB0_760
	s_barrier

; #define PG8_STAGE(bufoff, gbase, voff) do { _Pragma("unroll") for (int _i = 0; _i < 2; ++_i) \
;         __builtin_amdgcn_global_load_lds((const unsigned*)((const char*)(gbase) + (voff)[_i]), (LAS unsigned*)(lds + (bufoff) + ldsw + _i * 8192), 16, 0, 0); } while (0)
; #define PG8_LDA(dst, b, h) do { _Pragma("unroll") for (int m = 0; m < 4; ++m) _Pragma("unroll") for (int k = 0; k < 2; ++k) dst[m][k] = *(const LAS bf16x8*)(lds + PG8_SA(b, h) + aoff + m * 2048 + k * 1024); } while (0)
; #define PG8_LDB(dst, b, h) do { _Pragma("unroll") for (int n = 0; n < 2; ++n) _Pragma("unroll") for (int k = 0; k < 2; ++k) dst[n][k] = *(const LAS bf16x8*)(lds + PG8_SB(b, h) + boff + n * 2048 + k * 1024); } while (0)
; #define PG8_MMA(ai, bj, At, Bt) do { __builtin_amdgcn_s_setprio(1); _Pragma("unroll") for (int m = 0; m < 4; ++m) _Pragma("unroll") for (int n = 0; n < 2; ++n) _Pragma("unroll") for (int k = 0; k < 2; ++k) \
;         acc[ai][bj][m][n] = __builtin_amdgcn_mfma_f32_16x16x32_bf16(Bt[n][k], At[m][k], acc[ai][bj][m][n], 0, 0, 0); __builtin_amdgcn_s_setprio(0); } while (0)
; #define PG8_WAIT_V(n) asm volatile("s_waitcnt vmcnt(" #n ")" ::: "memory")
; #define PG8_WAIT_L(n) asm volatile("s_waitcnt lgkmcnt(" #n ")" ::: "memory")
; #define PG8_BAR __builtin_amdgcn_s_barrier()
; #define PG8_SCHED __builtin_amdgcn_sched_barrier(0)
; template <class Epi>
; __device__ __forceinline__ void gemm_phase(LAS unsigned char* lds, const Gemm g, const TileOrder& S, const Epi& E) {
;     ...
;             const bool last = (t == nt - 2);
;             const char* a1 = cA + (size_t)(t + 1) * kstepA;
;             const char* a2 = last ? nA : cA + (size_t)(t + 2) * kstepA; const char* b2 = last ? nB : cB + (size_t)(t + 2) * kstep;
;             const char* a3 = a2 + kstepA; const char* b3 = b2 + kstep;
;             PG8_LDB(B0, 0, 0); PG8_LDB(B1, 0, 1); PG8_SCHED; PG8_LDA(At, 0, 0); PG8_STAGE(PG8_SA(1, 1), a1 + hstepA, voffA);
;             PG8_WAIT_V(8); PG8_WAIT_L(0); PG8_BAR; PG8_MMA(0, 0, At, B0); PG8_MMA(0, 1, At, B1); PG8_BAR; PG8_SCHED;
;             PG8_LDA(At, 0, 1); PG8_STAGE(PG8_SB(0, 0), b2, voffB); PG8_STAGE(PG8_SB(0, 1), b2 + hstepB, voffB); PG8_STAGE(PG8_SA(0, 0), a2, voffA);
;             PG8_WAIT_V(8); PG8_WAIT_L(0); PG8_BAR; PG8_MMA(1, 0, At, B0); PG8_MMA(1, 1, At, B1); PG8_BAR; PG8_SCHED;
.LBB0_835:
	s_add_u32 s2, s28, 0x4000
	s_addc_u32 s3, s29, 0
	s_cmpk_eq_i32 s72, 0x7c
	s_cselect_b32 s38, s43, s2
	s_cselect_b32 s39, s42, s3
	s_cselect_b32 s30, s51, s53
	s_cselect_b32 s31, s45, s71
	s_add_u32 s2, s38, 0x8000
	s_addc_u32 s3, s39, 0
	s_add_i32 s6, 0, 0x10000
	s_add_i32 s14, 0, 0x14000
	v_add_u32_e32 v106, s6, v240
	v_add_u32_e32 v150, s14, v240
	ds_read_b128 v[74:77], v106
	ds_read_b128 v[86:89], v106 offset:1024
	ds_read_b128 v[98:101], v106 offset:2048
	ds_read_b128 v[106:109], v106 offset:3072
	ds_read_b128 v[122:125], v150
	ds_read_b128 v[126:129], v150 offset:1024
	ds_read_b128 v[142:145], v150 offset:2048
	ds_read_b128 v[150:153], v150 offset:3072
	v_lshl_add_u64 v[204:205], s[28:29], 0, v[196:197]
	s_add_i32 m0, s60, 0xc000
	ds_read_b128 v[154:157], v241
	ds_read_b128 v[166:169], v241 offset:1024
	ds_read_b128 v[170:173], v241 offset:2048
	ds_read_b128 v[174:177], v241 offset:3072
	ds_read_b128 v[178:181], v241 offset:4096
	ds_read_b128 v[182:185], v241 offset:5120
	ds_read_b128 v[186:189], v241 offset:6144
	ds_read_b128 v[200:203], v241 offset:7168
	global_load_lds_dwordx4 v[204:205], off
	v_lshl_add_u64 v[204:205], s[28:29], 0, v[198:199]
	s_add_i32 m0, s60, 0xe000
	s_nop 0
	global_load_lds_dwordx4 v[204:205], off
	s_waitcnt vmcnt(8)
	s_waitcnt lgkmcnt(0)
	s_barrier
	s_setprio 1
	s_waitcnt lgkmcnt(0)
	v_mfma_f32_16x16x32_bf16 v[162:165], v[74:77], v[154:157], v[162:165]
	v_mfma_f32_16x16x32_bf16 v[158:161], v[98:101], v[154:157], v[158:161]
	v_mfma_f32_16x16x32_bf16 v[134:137], v[74:77], v[170:173], v[134:137]
	v_mfma_f32_16x16x32_bf16 v[130:133], v[98:101], v[170:173], v[130:133]
	v_mfma_f32_16x16x32_bf16 v[110:113], v[74:77], v[178:181], v[110:113]
	v_mfma_f32_16x16x32_bf16 v[102:105], v[98:101], v[178:181], v[102:105]
	v_mfma_f32_16x16x32_bf16 v[82:85], v[74:77], v[186:189], v[82:85]
	v_mfma_f32_16x16x32_bf16 v[78:81], v[98:101], v[186:189], v[78:81]
	v_mfma_f32_16x16x32_bf16 v[162:165], v[86:89], v[166:169], v[162:165]
	v_mfma_f32_16x16x32_bf16 v[158:161], v[106:109], v[166:169], v[158:161]
	v_mfma_f32_16x16x32_bf16 v[134:137], v[86:89], v[174:177], v[134:137]
	v_mfma_f32_16x16x32_bf16 v[130:133], v[106:109], v[174:177], v[130:133]
	v_mfma_f32_16x16x32_bf16 v[110:113], v[86:89], v[182:185], v[110:113]
	v_mfma_f32_16x16x32_bf16 v[102:105], v[106:109], v[182:185], v[102:105]
	v_mfma_f32_16x16x32_bf16 v[82:85], v[86:89], v[200:203], v[82:85]
	v_mfma_f32_16x16x32_bf16 v[78:81], v[106:109], v[200:203], v[78:81]
	s_setprio 0
	s_setprio 1
	v_mfma_f32_16x16x32_bf16 v[146:149], v[122:125], v[154:157], v[146:149]
	v_mfma_f32_16x16x32_bf16 v[138:141], v[142:145], v[154:157], v[138:141]
	v_mfma_f32_16x16x32_bf16 v[118:121], v[122:125], v[170:173], v[118:121]
	v_mfma_f32_16x16x32_bf16 v[114:117], v[142:145], v[170:173], v[114:117]
	v_mfma_f32_16x16x32_bf16 v[94:97], v[122:125], v[178:181], v[94:97]
	v_mfma_f32_16x16x32_bf16 v[90:93], v[142:145], v[178:181], v[90:93]
	v_mfma_f32_16x16x32_bf16 v[70:73], v[122:125], v[186:189], v[70:73]
	v_mfma_f32_16x16x32_bf16 v[66:69], v[142:145], v[186:189], v[66:69]
	v_mfma_f32_16x16x32_bf16 v[146:149], v[126:129], v[166:169], v[146:149]
	v_mfma_f32_16x16x32_bf16 v[138:141], v[150:153], v[166:169], v[138:141]
	v_mfma_f32_16x16x32_bf16 v[118:121], v[126:129], v[174:177], v[118:121]
	v_mfma_f32_16x16x32_bf16 v[114:117], v[150:153], v[174:177], v[114:117]
	v_mfma_f32_16x16x32_bf16 v[94:97], v[126:129], v[182:185], v[94:97]
	s_setprio 2
	s_barrier
	v_mfma_f32_16x16x32_bf16 v[90:93], v[150:153], v[182:185], v[90:93]
	v_mfma_f32_16x16x32_bf16 v[70:73], v[126:129], v[200:203], v[70:73]
	v_mfma_f32_16x16x32_bf16 v[66:69], v[150:153], v[200:203], v[66:69]
	s_setprio 0
	s_add_i32 s6, s6, s59
	v_lshl_add_u64 v[204:205], s[30:31], 0, v[0:1]
	s_mov_b32 m0, s6
	ds_read_b128 v[154:157], v241 offset:16384
	ds_read_b128 v[166:169], v241 offset:17408
	ds_read_b128 v[170:173], v241 offset:18432
	ds_read_b128 v[174:177], v241 offset:19456
	ds_read_b128 v[178:181], v241 offset:20480
	ds_read_b128 v[182:185], v241 offset:21504
	ds_read_b128 v[186:189], v241 offset:22528
	ds_read_b128 v[200:203], v241 offset:23552
	global_load_lds_dwordx4 v[204:205], off
	s_add_i32 m0, s6, 0x2000
	s_add_u32 s12, s30, 0x200000
	v_lshl_add_u64 v[206:207], s[30:31], 0, v[190:191]
	s_addc_u32 s13, s31, 0
	s_add_i32 s6, s14, s59
	global_load_lds_dwordx4 v[206:207], off
	v_lshl_add_u64 v[208:209], s[12:13], 0, v[0:1]
	s_mov_b32 m0, s6
	s_nop 0
	global_load_lds_dwordx4 v[208:209], off
	v_lshl_add_u64 v[208:209], s[12:13], 0, v[190:191]
	s_add_i32 m0, s6, 0x2000
	s_nop 0
	global_load_lds_dwordx4 v[208:209], off
	v_lshl_add_u64 v[208:209], s[38:39], 0, v[194:195]
	s_mov_b32 m0, s60
	s_nop 0
	global_load_lds_dwordx4 v[208:209], off
	v_lshl_add_u64 v[208:209], s[38:39], 0, v[192:193]
	s_mov_b32 m0, s61
	s_nop 0
	global_load_lds_dwordx4 v[208:209], off
	s_waitcnt vmcnt(8)
	s_waitcnt lgkmcnt(0)
	s_barrier
; #define PG8_STAGE(bufoff, gbase, voff) do { _Pragma("unroll") for (int _i = 0; _i < 2; ++_i) \
;         __builtin_amdgcn_global_load_lds((const unsigned*)((const char*)(gbase) + (voff)[_i]), (LAS unsigned*)(lds + (bufoff) + ldsw + _i * 8192), 16, 0, 0); } while (0)
; #define PG8_LDA(dst, b, h) do { _Pragma("unroll") for (int m = 0; m < 4; ++m) _Pragma("unroll") for (int k = 0; k < 2; ++k) dst[m][k] = *(const LAS bf16x8*)(lds + PG8_SA(b, h) + aoff + m * 2048 + k * 1024); } while (0)
; #define PG8_LDB(dst, b, h) do { _Pragma("unroll") for (int n = 0; n < 2; ++n) _Pragma("unroll") for (int k = 0; k < 2; ++k) dst[n][k] = *(const LAS bf16x8*)(lds + PG8_SB(b, h) + boff + n * 2048 + k * 1024); } while (0)
; #define PG8_MMA(ai, bj, At, Bt) do { __builtin_amdgcn_s_setprio(1); _Pragma("unroll") for (int m = 0; m < 4; ++m) _Pragma("unroll") for (int n = 0; n < 2; ++n) _Pragma("unroll") for (int k = 0; k < 2; ++k) \
;         acc[ai][bj][m][n] = __builtin_amdgcn_mfma_f32_16x16x32_bf16(Bt[n][k], At[m][k], acc[ai][bj][m][n], 0, 0, 0); __builtin_amdgcn_s_setprio(0); } while (0)
; #define PG8_WAIT_V(n) asm volatile("s_waitcnt vmcnt(" #n ")" ::: "memory")
; #define PG8_WAIT_L(n) asm volatile("s_waitcnt lgkmcnt(" #n ")" ::: "memory")
; #define PG8_BAR __builtin_amdgcn_s_barrier()
; #define PG8_SCHED __builtin_amdgcn_sched_barrier(0)
; template <class Epi>
; __device__ __forceinline__ void gemm_phase(LAS unsigned char* lds, const Gemm g, const TileOrder& S, const Epi& E) {
;     ...
;             PG8_WAIT_V(8); PG8_WAIT_L(0); PG8_BAR; PG8_MMA(1, 0, At, B0); PG8_MMA(1, 1, At, B1); PG8_BAR; PG8_SCHED;
;             PG8_LDB(B0, 1, 0); PG8_LDB(B1, 1, 1); PG8_SCHED; PG8_LDA(At, 1, 0); PG8_STAGE(PG8_SA(0, 1), a2 + hstepA, voffA);
;             PG8_WAIT_V(8); PG8_WAIT_L(0); PG8_BAR; PG8_MMA(0, 0, At, B0); PG8_MMA(0, 1, At, B1); PG8_BAR; PG8_SCHED;
	s_setprio 1
	s_waitcnt lgkmcnt(0)
	v_mfma_f32_16x16x32_bf16 v[62:65], v[74:77], v[154:157], v[62:65]
	v_mfma_f32_16x16x32_bf16 v[58:61], v[98:101], v[154:157], v[58:61]
	v_mfma_f32_16x16x32_bf16 v[46:49], v[74:77], v[170:173], v[46:49]
	v_mfma_f32_16x16x32_bf16 v[42:45], v[98:101], v[170:173], v[42:45]
	v_mfma_f32_16x16x32_bf16 v[30:33], v[74:77], v[178:181], v[30:33]
	v_mfma_f32_16x16x32_bf16 v[26:29], v[98:101], v[178:181], v[26:29]
	v_mfma_f32_16x16x32_bf16 v[14:17], v[74:77], v[186:189], v[14:17]
	v_mfma_f32_16x16x32_bf16 v[10:13], v[98:101], v[186:189], v[10:13]
	v_mfma_f32_16x16x32_bf16 v[62:65], v[86:89], v[166:169], v[62:65]
	v_mfma_f32_16x16x32_bf16 v[58:61], v[106:109], v[166:169], v[58:61]
	v_mfma_f32_16x16x32_bf16 v[46:49], v[86:89], v[174:177], v[46:49]
	v_mfma_f32_16x16x32_bf16 v[42:45], v[106:109], v[174:177], v[42:45]
	v_mfma_f32_16x16x32_bf16 v[30:33], v[86:89], v[182:185], v[30:33]
	v_mfma_f32_16x16x32_bf16 v[26:29], v[106:109], v[182:185], v[26:29]
	v_mfma_f32_16x16x32_bf16 v[14:17], v[86:89], v[200:203], v[14:17]
	v_mfma_f32_16x16x32_bf16 v[10:13], v[106:109], v[200:203], v[10:13]
	s_setprio 0
	s_setprio 1
	v_mfma_f32_16x16x32_bf16 v[54:57], v[122:125], v[154:157], v[54:57]
	v_mfma_f32_16x16x32_bf16 v[50:53], v[142:145], v[154:157], v[50:53]
	v_mfma_f32_16x16x32_bf16 v[38:41], v[122:125], v[170:173], v[38:41]
	v_mfma_f32_16x16x32_bf16 v[34:37], v[142:145], v[170:173], v[34:37]
	v_mfma_f32_16x16x32_bf16 v[22:25], v[122:125], v[178:181], v[22:25]
	v_mfma_f32_16x16x32_bf16 v[18:21], v[142:145], v[178:181], v[18:21]
	v_mfma_f32_16x16x32_bf16 v[6:9], v[122:125], v[186:189], v[6:9]
	v_mfma_f32_16x16x32_bf16 v[2:5], v[142:145], v[186:189], v[2:5]
	v_mfma_f32_16x16x32_bf16 v[54:57], v[126:129], v[166:169], v[54:57]
	v_mfma_f32_16x16x32_bf16 v[50:53], v[150:153], v[166:169], v[50:53]
	v_mfma_f32_16x16x32_bf16 v[38:41], v[126:129], v[174:177], v[38:41]
	v_mfma_f32_16x16x32_bf16 v[34:37], v[150:153], v[174:177], v[34:37]
	v_mfma_f32_16x16x32_bf16 v[22:25], v[126:129], v[182:185], v[22:25]
	s_setprio 2
	s_barrier
	v_mfma_f32_16x16x32_bf16 v[18:21], v[150:153], v[182:185], v[18:21]
	v_mfma_f32_16x16x32_bf16 v[6:9], v[126:129], v[200:203], v[6:9]
	v_mfma_f32_16x16x32_bf16 v[2:5], v[150:153], v[200:203], v[2:5]
	s_setprio 0
	s_add_i32 s6, 0, 0x18000
	s_add_i32 s14, 0, 0x1c000
	v_add_u32_e32 v106, s6, v240
	v_add_u32_e32 v150, s14, v240
	ds_read_b128 v[74:77], v106
	ds_read_b128 v[86:89], v106 offset:1024
	ds_read_b128 v[98:101], v106 offset:2048
	ds_read_b128 v[106:109], v106 offset:3072
	ds_read_b128 v[122:125], v150
	ds_read_b128 v[126:129], v150 offset:1024
	ds_read_b128 v[142:145], v150 offset:2048
	ds_read_b128 v[150:153], v150 offset:3072
	s_add_u32 s12, s38, 0x4000
	s_addc_u32 s13, s39, 0
	s_mov_b32 m0, s62
	v_lshl_add_u64 v[208:209], s[12:13], 0, v[194:195]
	ds_read_b128 v[154:157], v241 offset:32768
	ds_read_b128 v[166:169], v241 offset:33792
	ds_read_b128 v[170:173], v241 offset:34816
	ds_read_b128 v[174:177], v241 offset:35840
	ds_read_b128 v[178:181], v241 offset:36864
	ds_read_b128 v[182:185], v241 offset:37888
	ds_read_b128 v[186:189], v241 offset:38912
	ds_read_b128 v[200:203], v241 offset:39936
	global_load_lds_dwordx4 v[208:209], off
	v_lshl_add_u64 v[208:209], s[12:13], 0, v[192:193]
	s_mov_b32 m0, s63
	s_nop 0
	global_load_lds_dwordx4 v[208:209], off
	s_waitcnt vmcnt(8)
	s_waitcnt lgkmcnt(0)
	s_barrier
	s_setprio 1
	s_waitcnt lgkmcnt(0)
	v_mfma_f32_16x16x32_bf16 v[162:165], v[74:77], v[154:157], v[162:165]
	v_mfma_f32_16x16x32_bf16 v[158:161], v[98:101], v[154:157], v[158:161]
	v_mfma_f32_16x16x32_bf16 v[134:137], v[74:77], v[170:173], v[134:137]
	v_mfma_f32_16x16x32_bf16 v[130:133], v[98:101], v[170:173], v[130:133]
	v_mfma_f32_16x16x32_bf16 v[110:113], v[74:77], v[178:181], v[110:113]
	v_mfma_f32_16x16x32_bf16 v[102:105], v[98:101], v[178:181], v[102:105]
	v_mfma_f32_16x16x32_bf16 v[82:85], v[74:77], v[186:189], v[82:85]
	v_mfma_f32_16x16x32_bf16 v[78:81], v[98:101], v[186:189], v[78:81]
	v_mfma_f32_16x16x32_bf16 v[162:165], v[86:89], v[166:169], v[162:165]
	v_mfma_f32_16x16x32_bf16 v[158:161], v[106:109], v[166:169], v[158:161]
	v_mfma_f32_16x16x32_bf16 v[134:137], v[86:89], v[174:177], v[134:137]
	v_mfma_f32_16x16x32_bf16 v[130:133], v[106:109], v[174:177], v[130:133]
	v_mfma_f32_16x16x32_bf16 v[110:113], v[86:89], v[182:185], v[110:113]
	v_mfma_f32_16x16x32_bf16 v[102:105], v[106:109], v[182:185], v[102:105]
	v_mfma_f32_16x16x32_bf16 v[82:85], v[86:89], v[200:203], v[82:85]
	v_mfma_f32_16x16x32_bf16 v[78:81], v[106:109], v[200:203], v[78:81]
	s_setprio 0
	s_setprio 1
	v_mfma_f32_16x16x32_bf16 v[146:149], v[122:125], v[154:157], v[146:149]
	v_mfma_f32_16x16x32_bf16 v[138:141], v[142:145], v[154:157], v[138:141]
	v_mfma_f32_16x16x32_bf16 v[118:121], v[122:125], v[170:173], v[118:121]
	v_mfma_f32_16x16x32_bf16 v[114:117], v[142:145], v[170:173], v[114:117]
	v_mfma_f32_16x16x32_bf16 v[94:97], v[122:125], v[178:181], v[94:97]
	v_mfma_f32_16x16x32_bf16 v[90:93], v[142:145], v[178:181], v[90:93]
	v_mfma_f32_16x16x32_bf16 v[70:73], v[122:125], v[186:189], v[70:73]
	v_mfma_f32_16x16x32_bf16 v[66:69], v[142:145], v[186:189], v[66:69]
	v_mfma_f32_16x16x32_bf16 v[146:149], v[126:129], v[166:169], v[146:149]
	v_mfma_f32_16x16x32_bf16 v[138:141], v[150:153], v[166:169], v[138:141]
	v_mfma_f32_16x16x32_bf16 v[118:121], v[126:129], v[174:177], v[118:121]
	v_mfma_f32_16x16x32_bf16 v[114:117], v[150:153], v[174:177], v[114:117]
	v_mfma_f32_16x16x32_bf16 v[94:97], v[126:129], v[182:185], v[94:97]
	s_setprio 2
	s_barrier
; #define PG8_STAGE(bufoff, gbase, voff) do { _Pragma("unroll") for (int _i = 0; _i < 2; ++_i) \
;         __builtin_amdgcn_global_load_lds((const unsigned*)((const char*)(gbase) + (voff)[_i]), (LAS unsigned*)(lds + (bufoff) + ldsw + _i * 8192), 16, 0, 0); } while (0)
; #define PG8_LDA(dst, b, h) do { _Pragma("unroll") for (int m = 0; m < 4; ++m) _Pragma("unroll") for (int k = 0; k < 2; ++k) dst[m][k] = *(const LAS bf16x8*)(lds + PG8_SA(b, h) + aoff + m * 2048 + k * 1024); } while (0)
; #define PG8_MMA(ai, bj, At, Bt) do { __builtin_amdgcn_s_setprio(1); _Pragma("unroll") for (int m = 0; m < 4; ++m) _Pragma("unroll") for (int n = 0; n < 2; ++n) _Pragma("unroll") for (int k = 0; k < 2; ++k) \
;         acc[ai][bj][m][n] = __builtin_amdgcn_mfma_f32_16x16x32_bf16(Bt[n][k], At[m][k], acc[ai][bj][m][n], 0, 0, 0); __builtin_amdgcn_s_setprio(0); } while (0)
; #define PG8_WAIT_V(n) asm volatile("s_waitcnt vmcnt(" #n ")" ::: "memory")
; #define PG8_WAIT_L(n) asm volatile("s_waitcnt lgkmcnt(" #n ")" ::: "memory")
; #define PG8_BAR __builtin_amdgcn_s_barrier()
; #define PG8_SCHED __builtin_amdgcn_sched_barrier(0)
; template <class Epi>
; __device__ __forceinline__ void gemm_phase(LAS unsigned char* lds, const Gemm g, const TileOrder& S, const Epi& E) {
;     ...
;             PG8_WAIT_V(8); PG8_WAIT_L(0); PG8_BAR; PG8_MMA(0, 0, At, B0); PG8_MMA(0, 1, At, B1); PG8_BAR; PG8_SCHED;
;             PG8_LDA(At, 1, 1); PG8_STAGE(PG8_SB(1, 0), b3, voffB); PG8_STAGE(PG8_SB(1, 1), b3 + hstepB, voffB); PG8_STAGE(PG8_SA(1, 0), a3, voffA);
;             PG8_WAIT_V(8); PG8_WAIT_L(0); PG8_BAR; PG8_MMA(1, 0, At, B0); PG8_MMA(1, 1, At, B1); PG8_BAR; PG8_SCHED;
;         }
;         if (wr == 0) PG8_BAR;
	v_mfma_f32_16x16x32_bf16 v[90:93], v[150:153], v[182:185], v[90:93]
	v_mfma_f32_16x16x32_bf16 v[70:73], v[126:129], v[200:203], v[70:73]
	v_mfma_f32_16x16x32_bf16 v[66:69], v[150:153], v[200:203], v[66:69]
	s_setprio 0
	s_add_i32 s6, s6, s59
	v_lshl_add_u64 v[204:205], v[204:205], 0, s[34:35]
	s_mov_b32 m0, s6
	ds_read_b128 v[154:157], v241 offset:49152
	ds_read_b128 v[166:169], v241 offset:50176
	ds_read_b128 v[170:173], v241 offset:51200
	ds_read_b128 v[174:177], v241 offset:52224
	ds_read_b128 v[178:181], v241 offset:53248
	ds_read_b128 v[182:185], v241 offset:54272
	ds_read_b128 v[186:189], v241 offset:55296
	ds_read_b128 v[200:203], v241 offset:56320
	global_load_lds_dwordx4 v[204:205], off
	s_add_i32 m0, s6, 0x2000
	s_add_u32 s12, s30, 0x200080
	v_lshl_add_u64 v[204:205], v[206:207], 0, s[34:35]
	s_addc_u32 s13, s31, 0
	s_add_i32 s6, s14, s59
	global_load_lds_dwordx4 v[204:205], off
	v_lshl_add_u64 v[204:205], s[12:13], 0, v[0:1]
	s_mov_b32 m0, s6
	s_nop 0
	global_load_lds_dwordx4 v[204:205], off
	v_lshl_add_u64 v[204:205], s[12:13], 0, v[190:191]
	s_add_i32 m0, s6, 0x2000
	s_nop 0
	global_load_lds_dwordx4 v[204:205], off
	v_lshl_add_u64 v[204:205], s[2:3], 0, v[194:195]
	s_mov_b32 m0, s69
	s_nop 0
	global_load_lds_dwordx4 v[204:205], off
	v_lshl_add_u64 v[204:205], s[2:3], 0, v[192:193]
	s_mov_b32 m0, s70
	s_nop 0
	global_load_lds_dwordx4 v[204:205], off
	s_waitcnt vmcnt(8)
	s_waitcnt lgkmcnt(0)
	s_barrier
	s_setprio 1
	s_waitcnt lgkmcnt(0)
	v_mfma_f32_16x16x32_bf16 v[62:65], v[74:77], v[154:157], v[62:65]
	v_mfma_f32_16x16x32_bf16 v[58:61], v[98:101], v[154:157], v[58:61]
	v_mfma_f32_16x16x32_bf16 v[46:49], v[74:77], v[170:173], v[46:49]
	v_mfma_f32_16x16x32_bf16 v[42:45], v[98:101], v[170:173], v[42:45]
	v_mfma_f32_16x16x32_bf16 v[30:33], v[74:77], v[178:181], v[30:33]
	v_mfma_f32_16x16x32_bf16 v[26:29], v[98:101], v[178:181], v[26:29]
	v_mfma_f32_16x16x32_bf16 v[14:17], v[74:77], v[186:189], v[14:17]
	v_mfma_f32_16x16x32_bf16 v[10:13], v[98:101], v[186:189], v[10:13]
	v_mfma_f32_16x16x32_bf16 v[62:65], v[86:89], v[166:169], v[62:65]
	v_mfma_f32_16x16x32_bf16 v[58:61], v[106:109], v[166:169], v[58:61]
	v_mfma_f32_16x16x32_bf16 v[46:49], v[86:89], v[174:177], v[46:49]
	v_mfma_f32_16x16x32_bf16 v[42:45], v[106:109], v[174:177], v[42:45]
	v_mfma_f32_16x16x32_bf16 v[30:33], v[86:89], v[182:185], v[30:33]
	v_mfma_f32_16x16x32_bf16 v[26:29], v[106:109], v[182:185], v[26:29]
	v_mfma_f32_16x16x32_bf16 v[14:17], v[86:89], v[200:203], v[14:17]
	v_mfma_f32_16x16x32_bf16 v[10:13], v[106:109], v[200:203], v[10:13]
	s_setprio 0
	s_setprio 1
	v_mfma_f32_16x16x32_bf16 v[54:57], v[122:125], v[154:157], v[54:57]
	v_mfma_f32_16x16x32_bf16 v[50:53], v[142:145], v[154:157], v[50:53]
	v_mfma_f32_16x16x32_bf16 v[38:41], v[122:125], v[170:173], v[38:41]
	v_mfma_f32_16x16x32_bf16 v[34:37], v[142:145], v[170:173], v[34:37]
	v_mfma_f32_16x16x32_bf16 v[22:25], v[122:125], v[178:181], v[22:25]
	v_mfma_f32_16x16x32_bf16 v[18:21], v[142:145], v[178:181], v[18:21]
	v_mfma_f32_16x16x32_bf16 v[6:9], v[122:125], v[186:189], v[6:9]
	v_mfma_f32_16x16x32_bf16 v[2:5], v[142:145], v[186:189], v[2:5]
	v_mfma_f32_16x16x32_bf16 v[54:57], v[126:129], v[166:169], v[54:57]
	v_mfma_f32_16x16x32_bf16 v[50:53], v[150:153], v[166:169], v[50:53]
	v_mfma_f32_16x16x32_bf16 v[38:41], v[126:129], v[174:177], v[38:41]
	v_mfma_f32_16x16x32_bf16 v[34:37], v[150:153], v[174:177], v[34:37]
	v_mfma_f32_16x16x32_bf16 v[22:25], v[126:129], v[182:185], v[22:25]
	s_setprio 2
	s_barrier
	v_mfma_f32_16x16x32_bf16 v[18:21], v[150:153], v[182:185], v[18:21]
	v_mfma_f32_16x16x32_bf16 v[6:9], v[126:129], v[200:203], v[6:9]
	v_mfma_f32_16x16x32_bf16 v[2:5], v[150:153], v[200:203], v[2:5]
	s_setprio 0
	s_add_i32 s72, s72, 2
	s_add_u32 s53, s53, 0x100
	s_addc_u32 s71, s71, 0
	s_add_u32 s28, s28, 0x10000
	s_addc_u32 s29, s29, 0
	s_cmpk_gt_u32 s72, 0x7d
	s_cbranch_scc0 .LBB0_835
	s_and_b64 vcc, exec, s[46:47]
	s_cbranch_vccz .LBB0_838
	s_barrier
